# K-loop compute segments: the two k-half MFMAs of each accumulator issued back to back (same-accumulator pairs, SrcC forwarding) instead of 8 apart; bit-identical results
# speedup vs baseline: 1.0047x; 1.0047x over previous
; #define STAGE_A(P, br, kt) do { const char* _g = (const char*)(A + (long)(br) * lda + (long)(kt) * BK); \
;     __builtin_amdgcn_global_load_lds((const unsigned*)(_g + (size_t)offA0), (unsigned*)((char*)(P) + sb0), 16, 0, 0); \
;     __builtin_amdgcn_global_load_lds((const unsigned*)(_g + (size_t)lda * 128 + (size_t)offA0), (unsigned*)((char*)(P) + sb1), 16, 0, 0); } while (0)
; #define STAGE_B(P, br, kt) do { const char* _g = (const char*)(B + (long)(br) * ldb + (long)(kt) * BK); \
;     __builtin_amdgcn_global_load_lds((const unsigned*)(_g + (size_t)offB0), (unsigned*)((char*)(P) + sb0), 16, 0, 0); \
;     __builtin_amdgcn_global_load_lds((const unsigned*)(_g + (size_t)ldb * 128 + (size_t)offB0), (unsigned*)((char*)(P) + sb1), 16, 0, 0); } while (0)
; #define LDA(dst, b, h) for (int m = 0; m < 4; ++m) for (int k = 0; k < 2; ++k) \
;     dst[m][k] = *reinterpret_cast<const bf16x8*>((char*)SA(b, h) + lds_byte(wr * 64 + m * 16 + fr, k * 32 + fq * 8))
; #define LDB(dst, b, h) for (int n = 0; n < 2; ++n) for (int k = 0; k < 2; ++k) \
;     dst[n][k] = *reinterpret_cast<const bf16x8*>((char*)SB(b, h) + lds_byte(wc * 32 + n * 16 + fr, k * 32 + fq * 8))
; #define MMA(ai, bj, At_, Bt_) do { __builtin_amdgcn_s_setprio(1); \
;     for (int m = 0; m < 4; ++m) for (int n = 0; n < 2; ++n) for (int k = 0; k < 2; ++k) \
;       acc[ai][bj][m][n] = MFMA16(At_[m][k], Bt_[n][k], acc[ai][bj][m][n]); \
;     __builtin_amdgcn_s_setprio(0); } while (0)
; #define WAIT_V(n) asm volatile("s_waitcnt vmcnt(" #n ")" ::: "memory")
; #define WAIT_L(n) asm volatile("s_waitcnt lgkmcnt(" #n ")" ::: "memory")
; #define BAR __builtin_amdgcn_s_barrier()
; #define SCHED __builtin_amdgcn_sched_barrier(0)
; DI void gemm_core(WVP char* smem, const u16* __restrict__ A, int lda, int ar0, int ar1,
;                   const u16* __restrict__ B, int ldb, int bc0, int K, AccT& acc) {
;     ...
;     LDB(B0, 0, 0); SCHED; LDA(At, 0, 0); STAGE_A(SA(1, 1), ac1, t + 1);
;     WAIT_L(8); BAR; WAIT_L(0); MMA(0, 0, At, B0); BAR; SCHED;
;     LDB(B1, 0, 1); STAGE_B(SB(0, 0), bb0, t + 2);
;     BAR; WAIT_L(0); MMA(0, 1, At, B1); BAR;
;     LDA(At, 0, 1); STAGE_A(SA(0, 0), ac0, t + 2);
;     BAR; WAIT_L(0); MMA(1, 0, At, B0); BAR; SCHED;
;     STAGE_B(SB(0, 1), bb1, t + 2);
;     WAIT_V(6); BAR; MMA(1, 1, At, B1); BAR;
.LBB0_94:
	v_add_u32_e32 v150, s0, v148
	v_add_u32_e32 v151, s1, v148
	v_add_u32_e32 v152, s19, v148
	ds_read_b128 v[156:159], v149
	ds_read_b128 v[160:163], v149 offset:1024
	ds_read_b128 v[164:167], v149 offset:2048
	ds_read_b128 v[168:171], v149 offset:3072
	ds_read_b128 v[172:175], v132
	ds_read_b128 v[176:179], v132 offset:1024
	ds_read_b128 v[180:183], v150
	ds_read_b128 v[184:187], v150 offset:1024
	ds_read_b128 v[188:191], v151
	ds_read_b128 v[192:195], v151 offset:1024
	ds_read_b128 v[196:199], v152
	ds_read_b128 v[200:203], v152 offset:1024
	ds_read_b128 v[206:209], v146
	ds_read_b128 v[210:213], v146 offset:1024
	ds_read_b128 v[214:217], v146 offset:2048
	ds_read_b128 v[218:221], v146 offset:3072
	v_add_u32_e32 v153, 0xc000, v135
	v_lshl_add_u64 v[224:225], s[16:17], 0, v[0:1]
	s_mov_b64 s[22:23], 0x1f430080
	v_lshl_add_u64 v[222:223], v[224:225], 0, s[22:23]
	v_readfirstlane_b32 s21, v153
	s_mov_b32 m0, s21
	s_nop 0
	global_load_lds_dwordx4 v[222:223], off
	v_add_u32_e32 v154, 0xe000, v135
	v_lshl_add_u64 v[224:225], s[16:17], 0, v[0:1]
	s_mov_b64 s[22:23], 0x1f488080
	v_lshl_add_u64 v[222:223], v[224:225], 0, s[22:23]
	v_readfirstlane_b32 s21, v154
	s_mov_b32 m0, s21
	s_nop 0
	global_load_lds_dwordx4 v[222:223], off
	s_waitcnt vmcnt(8)
	s_waitcnt lgkmcnt(0)
	s_barrier
	v_mfma_f32_16x16x32_bf16 v[126:129], v[172:175], v[156:159], v[126:129]
	v_mfma_f32_16x16x32_bf16 v[126:129], v[176:179], v[160:163], v[126:129]
	v_mfma_f32_16x16x32_bf16 v[122:125], v[172:175], v[164:167], v[122:125]
	v_mfma_f32_16x16x32_bf16 v[122:125], v[176:179], v[168:171], v[122:125]
	v_mfma_f32_16x16x32_bf16 v[118:121], v[180:183], v[156:159], v[118:121]
	v_mfma_f32_16x16x32_bf16 v[118:121], v[184:187], v[160:163], v[118:121]
	v_mfma_f32_16x16x32_bf16 v[114:117], v[180:183], v[164:167], v[114:117]
	v_mfma_f32_16x16x32_bf16 v[114:117], v[184:187], v[168:171], v[114:117]
	v_mfma_f32_16x16x32_bf16 v[110:113], v[188:191], v[156:159], v[110:113]
	v_mfma_f32_16x16x32_bf16 v[110:113], v[192:195], v[160:163], v[110:113]
	v_mfma_f32_16x16x32_bf16 v[106:109], v[188:191], v[164:167], v[106:109]
	v_mfma_f32_16x16x32_bf16 v[106:109], v[192:195], v[168:171], v[106:109]
	v_mfma_f32_16x16x32_bf16 v[102:105], v[196:199], v[156:159], v[102:105]
	v_mfma_f32_16x16x32_bf16 v[102:105], v[200:203], v[160:163], v[102:105]
	v_mfma_f32_16x16x32_bf16 v[98:101], v[196:199], v[164:167], v[98:101]
	v_mfma_f32_16x16x32_bf16 v[98:101], v[200:203], v[168:171], v[98:101]
	v_mfma_f32_16x16x32_bf16 v[94:97], v[172:175], v[206:209], v[94:97]
	v_mfma_f32_16x16x32_bf16 v[94:97], v[176:179], v[210:213], v[94:97]
	v_mfma_f32_16x16x32_bf16 v[90:93], v[172:175], v[214:217], v[90:93]
	v_mfma_f32_16x16x32_bf16 v[90:93], v[176:179], v[218:221], v[90:93]
	v_mfma_f32_16x16x32_bf16 v[86:89], v[180:183], v[206:209], v[86:89]
	v_mfma_f32_16x16x32_bf16 v[86:89], v[184:187], v[210:213], v[86:89]
	v_mfma_f32_16x16x32_bf16 v[82:85], v[180:183], v[214:217], v[82:85]
	v_mfma_f32_16x16x32_bf16 v[82:85], v[184:187], v[218:221], v[82:85]
	v_mfma_f32_16x16x32_bf16 v[78:81], v[188:191], v[206:209], v[78:81]
	v_mfma_f32_16x16x32_bf16 v[78:81], v[192:195], v[210:213], v[78:81]
	v_mfma_f32_16x16x32_bf16 v[74:77], v[188:191], v[214:217], v[74:77]
	v_mfma_f32_16x16x32_bf16 v[74:77], v[192:195], v[218:221], v[74:77]
	v_mfma_f32_16x16x32_bf16 v[70:73], v[196:199], v[206:209], v[70:73]
	v_mfma_f32_16x16x32_bf16 v[70:73], v[200:203], v[210:213], v[70:73]
	v_mfma_f32_16x16x32_bf16 v[66:69], v[196:199], v[214:217], v[66:69]
	v_mfma_f32_16x16x32_bf16 v[66:69], v[200:203], v[218:221], v[66:69]
	s_barrier
	ds_read_b128 v[172:175], v132 offset:16384
	ds_read_b128 v[176:179], v132 offset:17408
	ds_read_b128 v[180:183], v150 offset:16384
	ds_read_b128 v[184:187], v150 offset:17408
	ds_read_b128 v[188:191], v151 offset:16384
	ds_read_b128 v[192:195], v151 offset:17408
	ds_read_b128 v[196:199], v152 offset:16384
	ds_read_b128 v[200:203], v152 offset:17408
	v_lshl_add_u64 v[224:225], s[8:9], 0, v[0:1]
	v_lshl_add_u64 v[222:223], v[224:225], 0, s[68:69]
	v_readfirstlane_b32 s21, v134
	s_mov_b32 m0, s21
	s_nop 0
	global_load_lds_dwordx4 v[222:223], off
	v_add_u32_e32 v155, 0x2000, v134
	v_lshl_add_u64 v[224:225], s[8:9], 0, v[0:1]
	s_mov_b64 s[22:23], 0x58100
	v_lshl_add_u64 v[222:223], v[224:225], 0, s[22:23]
	v_readfirstlane_b32 s21, v155
	s_mov_b32 m0, s21
	s_nop 0
	global_load_lds_dwordx4 v[222:223], off
	v_lshl_add_u64 v[224:225], s[16:17], 0, v[0:1]
	s_mov_b64 s[22:23], 0x1f380100
	v_lshl_add_u64 v[222:223], v[224:225], 0, s[22:23]
	v_readfirstlane_b32 s21, v135
	s_mov_b32 m0, s21
	s_nop 0
	global_load_lds_dwordx4 v[222:223], off
	v_lshl_add_u64 v[224:225], s[16:17], 0, v[0:1]
	s_mov_b64 s[22:23], 0x1f3d8100
	v_lshl_add_u64 v[222:223], v[224:225], 0, s[22:23]
	v_readfirstlane_b32 s21, v136
	s_mov_b32 m0, s21
	s_nop 0
	global_load_lds_dwordx4 v[222:223], off
	v_lshl_add_u64 v[224:225], s[8:9], 0, v[0:1]
	s_mov_b64 s[22:23], 0xb0100
	v_lshl_add_u64 v[222:223], v[224:225], 0, s[22:23]
	v_readfirstlane_b32 s21, v138
	s_mov_b32 m0, s21
	s_nop 0
	global_load_lds_dwordx4 v[222:223], off
	v_add_u32_e32 v155, 0x2000, v138
	v_lshl_add_u64 v[224:225], s[8:9], 0, v[0:1]
	s_mov_b64 s[22:23], 0x108100
	v_lshl_add_u64 v[222:223], v[224:225], 0, s[22:23]
	v_readfirstlane_b32 s21, v155
	s_mov_b32 m0, s21
	s_nop 0
	global_load_lds_dwordx4 v[222:223], off
	s_waitcnt vmcnt(8)
	s_waitcnt lgkmcnt(0)
	s_barrier
; #define STAGE_A(P, br, kt) do { const char* _g = (const char*)(A + (long)(br) * lda + (long)(kt) * BK); \
;     __builtin_amdgcn_global_load_lds((const unsigned*)(_g + (size_t)offA0), (unsigned*)((char*)(P) + sb0), 16, 0, 0); \
;     __builtin_amdgcn_global_load_lds((const unsigned*)(_g + (size_t)lda * 128 + (size_t)offA0), (unsigned*)((char*)(P) + sb1), 16, 0, 0); } while (0)
; #define STAGE_B(P, br, kt) do { const char* _g = (const char*)(B + (long)(br) * ldb + (long)(kt) * BK); \
;     __builtin_amdgcn_global_load_lds((const unsigned*)(_g + (size_t)offB0), (unsigned*)((char*)(P) + sb0), 16, 0, 0); \
;     __builtin_amdgcn_global_load_lds((const unsigned*)(_g + (size_t)ldb * 128 + (size_t)offB0), (unsigned*)((char*)(P) + sb1), 16, 0, 0); } while (0)
; #define LDA(dst, b, h) for (int m = 0; m < 4; ++m) for (int k = 0; k < 2; ++k) \
;     dst[m][k] = *reinterpret_cast<const bf16x8*>((char*)SA(b, h) + lds_byte(wr * 64 + m * 16 + fr, k * 32 + fq * 8))
; #define LDB(dst, b, h) for (int n = 0; n < 2; ++n) for (int k = 0; k < 2; ++k) \
;     dst[n][k] = *reinterpret_cast<const bf16x8*>((char*)SB(b, h) + lds_byte(wc * 32 + n * 16 + fr, k * 32 + fq * 8))
; #define MMA(ai, bj, At_, Bt_) do { __builtin_amdgcn_s_setprio(1); \
;     for (int m = 0; m < 4; ++m) for (int n = 0; n < 2; ++n) for (int k = 0; k < 2; ++k) \
;       acc[ai][bj][m][n] = MFMA16(At_[m][k], Bt_[n][k], acc[ai][bj][m][n]); \
;     __builtin_amdgcn_s_setprio(0); } while (0)
; #define WAIT_V(n) asm volatile("s_waitcnt vmcnt(" #n ")" ::: "memory")
; #define WAIT_L(n) asm volatile("s_waitcnt lgkmcnt(" #n ")" ::: "memory")
; #define BAR __builtin_amdgcn_s_barrier()
; #define SCHED __builtin_amdgcn_sched_barrier(0)
; DI void gemm_core(WVP char* smem, const u16* __restrict__ A, int lda, int ar0, int ar1,
;                   const u16* __restrict__ B, int ldb, int bc0, int K, AccT& acc) {
;     ...
;     WAIT_V(6); BAR; MMA(1, 1, At, B1); BAR;
;     LDB(B0, 1, 0); SCHED; LDA(At, 1, 0); STAGE_A(SA(0, 1), ac1, t + 2);
;     WAIT_L(8); BAR; WAIT_L(0); MMA(0, 0, At, B0); BAR; SCHED;
;     LDB(B1, 1, 1); STAGE_B(SB(1, 0), bb0, t + 3);
;     BAR; WAIT_L(0); MMA(0, 1, At, B1); BAR;
	v_mfma_f32_16x16x32_bf16 v[62:65], v[172:175], v[156:159], v[62:65]
	v_mfma_f32_16x16x32_bf16 v[62:65], v[176:179], v[160:163], v[62:65]
	v_mfma_f32_16x16x32_bf16 v[58:61], v[172:175], v[164:167], v[58:61]
	v_mfma_f32_16x16x32_bf16 v[58:61], v[176:179], v[168:171], v[58:61]
	v_mfma_f32_16x16x32_bf16 v[54:57], v[180:183], v[156:159], v[54:57]
	v_mfma_f32_16x16x32_bf16 v[54:57], v[184:187], v[160:163], v[54:57]
	v_mfma_f32_16x16x32_bf16 v[50:53], v[180:183], v[164:167], v[50:53]
	v_mfma_f32_16x16x32_bf16 v[50:53], v[184:187], v[168:171], v[50:53]
	v_mfma_f32_16x16x32_bf16 v[46:49], v[188:191], v[156:159], v[46:49]
	v_mfma_f32_16x16x32_bf16 v[46:49], v[192:195], v[160:163], v[46:49]
	v_mfma_f32_16x16x32_bf16 v[42:45], v[188:191], v[164:167], v[42:45]
	v_mfma_f32_16x16x32_bf16 v[42:45], v[192:195], v[168:171], v[42:45]
	v_mfma_f32_16x16x32_bf16 v[38:41], v[196:199], v[156:159], v[38:41]
	v_mfma_f32_16x16x32_bf16 v[38:41], v[200:203], v[160:163], v[38:41]
	v_mfma_f32_16x16x32_bf16 v[34:37], v[196:199], v[164:167], v[34:37]
	v_mfma_f32_16x16x32_bf16 v[34:37], v[200:203], v[168:171], v[34:37]
	v_mfma_f32_16x16x32_bf16 v[30:33], v[172:175], v[206:209], v[30:33]
	v_mfma_f32_16x16x32_bf16 v[30:33], v[176:179], v[210:213], v[30:33]
	v_mfma_f32_16x16x32_bf16 v[26:29], v[172:175], v[214:217], v[26:29]
	v_mfma_f32_16x16x32_bf16 v[26:29], v[176:179], v[218:221], v[26:29]
	v_mfma_f32_16x16x32_bf16 v[22:25], v[180:183], v[206:209], v[22:25]
	v_mfma_f32_16x16x32_bf16 v[22:25], v[184:187], v[210:213], v[22:25]
	v_mfma_f32_16x16x32_bf16 v[18:21], v[180:183], v[214:217], v[18:21]
	v_mfma_f32_16x16x32_bf16 v[18:21], v[184:187], v[218:221], v[18:21]
	v_mfma_f32_16x16x32_bf16 v[14:17], v[188:191], v[206:209], v[14:17]
	v_mfma_f32_16x16x32_bf16 v[14:17], v[192:195], v[210:213], v[14:17]
	v_mfma_f32_16x16x32_bf16 v[10:13], v[188:191], v[214:217], v[10:13]
	v_mfma_f32_16x16x32_bf16 v[10:13], v[192:195], v[218:221], v[10:13]
	v_mfma_f32_16x16x32_bf16 v[6:9], v[196:199], v[206:209], v[6:9]
	v_mfma_f32_16x16x32_bf16 v[6:9], v[200:203], v[210:213], v[6:9]
	v_mfma_f32_16x16x32_bf16 v[2:5], v[196:199], v[214:217], v[2:5]
	v_mfma_f32_16x16x32_bf16 v[2:5], v[200:203], v[218:221], v[2:5]
	s_barrier
	ds_read_b128 v[156:159], v137
	ds_read_b128 v[160:163], v137 offset:1024
	ds_read_b128 v[164:167], v137 offset:2048
	ds_read_b128 v[168:171], v137 offset:3072
	ds_read_b128 v[172:175], v132 offset:32768
	ds_read_b128 v[176:179], v132 offset:33792
	ds_read_b128 v[180:183], v150 offset:32768
	ds_read_b128 v[184:187], v150 offset:33792
	ds_read_b128 v[188:191], v151 offset:32768
	ds_read_b128 v[192:195], v151 offset:33792
	ds_read_b128 v[196:199], v152 offset:32768
	ds_read_b128 v[200:203], v152 offset:33792
	ds_read_b128 v[206:209], v133
	ds_read_b128 v[210:213], v133 offset:1024
	ds_read_b128 v[214:217], v133 offset:2048
	ds_read_b128 v[218:221], v133 offset:3072
	v_lshl_add_u64 v[224:225], s[16:17], 0, v[0:1]
	s_mov_b64 s[22:23], 0x1f430100
	v_lshl_add_u64 v[222:223], v[224:225], 0, s[22:23]
	v_readfirstlane_b32 s21, v139
	s_mov_b32 m0, s21
	s_nop 0
	global_load_lds_dwordx4 v[222:223], off
	v_lshl_add_u64 v[224:225], s[16:17], 0, v[0:1]
	s_mov_b64 s[22:23], 0x1f488100
	v_lshl_add_u64 v[222:223], v[224:225], 0, s[22:23]
	v_readfirstlane_b32 s21, v140
	s_mov_b32 m0, s21
	s_nop 0
	global_load_lds_dwordx4 v[222:223], off
	s_waitcnt vmcnt(8)
	s_waitcnt lgkmcnt(0)
	s_barrier
	v_mfma_f32_16x16x32_bf16 v[126:129], v[172:175], v[156:159], v[126:129]
	v_mfma_f32_16x16x32_bf16 v[126:129], v[176:179], v[160:163], v[126:129]
	v_mfma_f32_16x16x32_bf16 v[122:125], v[172:175], v[164:167], v[122:125]
	v_mfma_f32_16x16x32_bf16 v[122:125], v[176:179], v[168:171], v[122:125]
	v_mfma_f32_16x16x32_bf16 v[118:121], v[180:183], v[156:159], v[118:121]
	v_mfma_f32_16x16x32_bf16 v[118:121], v[184:187], v[160:163], v[118:121]
	v_mfma_f32_16x16x32_bf16 v[114:117], v[180:183], v[164:167], v[114:117]
	v_mfma_f32_16x16x32_bf16 v[114:117], v[184:187], v[168:171], v[114:117]
	v_mfma_f32_16x16x32_bf16 v[110:113], v[188:191], v[156:159], v[110:113]
	v_mfma_f32_16x16x32_bf16 v[110:113], v[192:195], v[160:163], v[110:113]
	v_mfma_f32_16x16x32_bf16 v[106:109], v[188:191], v[164:167], v[106:109]
	v_mfma_f32_16x16x32_bf16 v[106:109], v[192:195], v[168:171], v[106:109]
	v_mfma_f32_16x16x32_bf16 v[102:105], v[196:199], v[156:159], v[102:105]
	v_mfma_f32_16x16x32_bf16 v[102:105], v[200:203], v[160:163], v[102:105]
	v_mfma_f32_16x16x32_bf16 v[98:101], v[196:199], v[164:167], v[98:101]
	v_mfma_f32_16x16x32_bf16 v[98:101], v[200:203], v[168:171], v[98:101]
	v_mfma_f32_16x16x32_bf16 v[94:97], v[172:175], v[206:209], v[94:97]
	v_mfma_f32_16x16x32_bf16 v[94:97], v[176:179], v[210:213], v[94:97]
	v_mfma_f32_16x16x32_bf16 v[90:93], v[172:175], v[214:217], v[90:93]
	v_mfma_f32_16x16x32_bf16 v[90:93], v[176:179], v[218:221], v[90:93]
	v_mfma_f32_16x16x32_bf16 v[86:89], v[180:183], v[206:209], v[86:89]
	v_mfma_f32_16x16x32_bf16 v[86:89], v[184:187], v[210:213], v[86:89]
	v_mfma_f32_16x16x32_bf16 v[82:85], v[180:183], v[214:217], v[82:85]
	v_mfma_f32_16x16x32_bf16 v[82:85], v[184:187], v[218:221], v[82:85]
	v_mfma_f32_16x16x32_bf16 v[78:81], v[188:191], v[206:209], v[78:81]
	v_mfma_f32_16x16x32_bf16 v[78:81], v[192:195], v[210:213], v[78:81]
	v_mfma_f32_16x16x32_bf16 v[74:77], v[188:191], v[214:217], v[74:77]
	v_mfma_f32_16x16x32_bf16 v[74:77], v[192:195], v[218:221], v[74:77]
	v_mfma_f32_16x16x32_bf16 v[70:73], v[196:199], v[206:209], v[70:73]
	v_mfma_f32_16x16x32_bf16 v[70:73], v[200:203], v[210:213], v[70:73]
	v_mfma_f32_16x16x32_bf16 v[66:69], v[196:199], v[214:217], v[66:69]
	v_mfma_f32_16x16x32_bf16 v[66:69], v[200:203], v[218:221], v[66:69]
	s_barrier
; #define STAGE_A(P, br, kt) do { const char* _g = (const char*)(A + (long)(br) * lda + (long)(kt) * BK); \
;     __builtin_amdgcn_global_load_lds((const unsigned*)(_g + (size_t)offA0), (unsigned*)((char*)(P) + sb0), 16, 0, 0); \
;     __builtin_amdgcn_global_load_lds((const unsigned*)(_g + (size_t)lda * 128 + (size_t)offA0), (unsigned*)((char*)(P) + sb1), 16, 0, 0); } while (0)
; #define STAGE_B(P, br, kt) do { const char* _g = (const char*)(B + (long)(br) * ldb + (long)(kt) * BK); \
;     __builtin_amdgcn_global_load_lds((const unsigned*)(_g + (size_t)offB0), (unsigned*)((char*)(P) + sb0), 16, 0, 0); \
;     __builtin_amdgcn_global_load_lds((const unsigned*)(_g + (size_t)ldb * 128 + (size_t)offB0), (unsigned*)((char*)(P) + sb1), 16, 0, 0); } while (0)
; #define LDA(dst, b, h) for (int m = 0; m < 4; ++m) for (int k = 0; k < 2; ++k) \
;     dst[m][k] = *reinterpret_cast<const bf16x8*>((char*)SA(b, h) + lds_byte(wr * 64 + m * 16 + fr, k * 32 + fq * 8))
; #define LDB(dst, b, h) for (int n = 0; n < 2; ++n) for (int k = 0; k < 2; ++k) \
;     dst[n][k] = *reinterpret_cast<const bf16x8*>((char*)SB(b, h) + lds_byte(wc * 32 + n * 16 + fr, k * 32 + fq * 8))
; #define MMA(ai, bj, At_, Bt_) do { __builtin_amdgcn_s_setprio(1); \
;     for (int m = 0; m < 4; ++m) for (int n = 0; n < 2; ++n) for (int k = 0; k < 2; ++k) \
;       acc[ai][bj][m][n] = MFMA16(At_[m][k], Bt_[n][k], acc[ai][bj][m][n]); \
;     __builtin_amdgcn_s_setprio(0); } while (0)
; #define WAIT_V(n) asm volatile("s_waitcnt vmcnt(" #n ")" ::: "memory")
; #define WAIT_L(n) asm volatile("s_waitcnt lgkmcnt(" #n ")" ::: "memory")
; #define BAR __builtin_amdgcn_s_barrier()
; #define SCHED __builtin_amdgcn_sched_barrier(0)
; DI void gemm_core(WVP char* smem, const u16* __restrict__ A, int lda, int ar0, int ar1,
;                   const u16* __restrict__ B, int ldb, int bc0, int K, AccT& acc) {
;     ...
;     LDA(At, 1, 1); STAGE_A(SA(1, 0), ac0, t + 3);
;     BAR; WAIT_L(0); MMA(1, 0, At, B0); BAR; SCHED;
;     STAGE_B(SB(1, 1), bb1, t + 3);
;     WAIT_V(6); BAR; MMA(1, 1, At, B1); BAR;
;   }
;   { LDB(B0, 0, 0); LDA(At, 0, 0); STAGE_A(SA(1, 1), ac1, nt - 1);
;     BAR; WAIT_L(0); MMA(0, 0, At, B0); BAR;
	ds_read_b128 v[172:175], v132 offset:49152
	ds_read_b128 v[176:179], v132 offset:50176
	ds_read_b128 v[180:183], v150 offset:49152
	ds_read_b128 v[184:187], v150 offset:50176
	ds_read_b128 v[188:191], v151 offset:49152
	ds_read_b128 v[192:195], v151 offset:50176
	ds_read_b128 v[196:199], v152 offset:49152
	ds_read_b128 v[200:203], v152 offset:50176
	v_lshl_add_u64 v[224:225], s[8:9], 0, v[0:1]
	v_lshl_add_u64 v[222:223], v[224:225], 0, s[70:71]
	v_readfirstlane_b32 s21, v141
	s_mov_b32 m0, s21
	s_nop 0
	global_load_lds_dwordx4 v[222:223], off
	v_lshl_add_u64 v[224:225], s[8:9], 0, v[0:1]
	s_mov_b64 s[22:23], 0x58180
	v_lshl_add_u64 v[222:223], v[224:225], 0, s[22:23]
	v_readfirstlane_b32 s21, v142
	s_mov_b32 m0, s21
	s_nop 0
	global_load_lds_dwordx4 v[222:223], off
	v_lshl_add_u64 v[224:225], s[16:17], 0, v[0:1]
	s_mov_b64 s[22:23], 0x1f380180
	v_lshl_add_u64 v[222:223], v[224:225], 0, s[22:23]
	v_readfirstlane_b32 s21, v143
	s_mov_b32 m0, s21
	s_nop 0
	global_load_lds_dwordx4 v[222:223], off
	v_lshl_add_u64 v[224:225], s[16:17], 0, v[0:1]
	s_mov_b64 s[22:23], 0x1f3d8180
	v_lshl_add_u64 v[222:223], v[224:225], 0, s[22:23]
	v_readfirstlane_b32 s21, v144
	s_mov_b32 m0, s21
	s_nop 0
	global_load_lds_dwordx4 v[222:223], off
	v_lshl_add_u64 v[224:225], s[8:9], 0, v[0:1]
	s_mov_b64 s[22:23], 0xb0180
	v_lshl_add_u64 v[222:223], v[224:225], 0, s[22:23]
	v_readfirstlane_b32 s21, v145
	s_mov_b32 m0, s21
	s_nop 0
	global_load_lds_dwordx4 v[222:223], off
	v_lshl_add_u64 v[224:225], s[8:9], 0, v[0:1]
	s_mov_b64 s[22:23], 0x108180
	v_lshl_add_u64 v[222:223], v[224:225], 0, s[22:23]
	v_readfirstlane_b32 s21, v147
	s_mov_b32 m0, s21
	s_nop 0
	global_load_lds_dwordx4 v[222:223], off
	s_waitcnt vmcnt(8)
	s_waitcnt lgkmcnt(0)
	s_barrier
	v_mfma_f32_16x16x32_bf16 v[62:65], v[172:175], v[156:159], v[62:65]
	v_mfma_f32_16x16x32_bf16 v[62:65], v[176:179], v[160:163], v[62:65]
	v_mfma_f32_16x16x32_bf16 v[58:61], v[172:175], v[164:167], v[58:61]
	v_mfma_f32_16x16x32_bf16 v[58:61], v[176:179], v[168:171], v[58:61]
	v_mfma_f32_16x16x32_bf16 v[54:57], v[180:183], v[156:159], v[54:57]
	v_mfma_f32_16x16x32_bf16 v[54:57], v[184:187], v[160:163], v[54:57]
	v_mfma_f32_16x16x32_bf16 v[50:53], v[180:183], v[164:167], v[50:53]
	v_mfma_f32_16x16x32_bf16 v[50:53], v[184:187], v[168:171], v[50:53]
	v_mfma_f32_16x16x32_bf16 v[46:49], v[188:191], v[156:159], v[46:49]
	v_mfma_f32_16x16x32_bf16 v[46:49], v[192:195], v[160:163], v[46:49]
	v_mfma_f32_16x16x32_bf16 v[42:45], v[188:191], v[164:167], v[42:45]
	v_mfma_f32_16x16x32_bf16 v[42:45], v[192:195], v[168:171], v[42:45]
	v_mfma_f32_16x16x32_bf16 v[38:41], v[196:199], v[156:159], v[38:41]
	v_mfma_f32_16x16x32_bf16 v[38:41], v[200:203], v[160:163], v[38:41]
	v_mfma_f32_16x16x32_bf16 v[34:37], v[196:199], v[164:167], v[34:37]
	v_mfma_f32_16x16x32_bf16 v[34:37], v[200:203], v[168:171], v[34:37]
	v_mfma_f32_16x16x32_bf16 v[30:33], v[172:175], v[206:209], v[30:33]
	v_mfma_f32_16x16x32_bf16 v[30:33], v[176:179], v[210:213], v[30:33]
	v_mfma_f32_16x16x32_bf16 v[26:29], v[172:175], v[214:217], v[26:29]
	v_mfma_f32_16x16x32_bf16 v[26:29], v[176:179], v[218:221], v[26:29]
	v_mfma_f32_16x16x32_bf16 v[22:25], v[180:183], v[206:209], v[22:25]
	v_mfma_f32_16x16x32_bf16 v[22:25], v[184:187], v[210:213], v[22:25]
	v_mfma_f32_16x16x32_bf16 v[18:21], v[180:183], v[214:217], v[18:21]
	v_mfma_f32_16x16x32_bf16 v[18:21], v[184:187], v[218:221], v[18:21]
	v_mfma_f32_16x16x32_bf16 v[14:17], v[188:191], v[206:209], v[14:17]
	v_mfma_f32_16x16x32_bf16 v[14:17], v[192:195], v[210:213], v[14:17]
	v_mfma_f32_16x16x32_bf16 v[10:13], v[188:191], v[214:217], v[10:13]
	v_mfma_f32_16x16x32_bf16 v[10:13], v[192:195], v[218:221], v[10:13]
	v_mfma_f32_16x16x32_bf16 v[6:9], v[196:199], v[206:209], v[6:9]
	v_mfma_f32_16x16x32_bf16 v[6:9], v[200:203], v[210:213], v[6:9]
	v_mfma_f32_16x16x32_bf16 v[2:5], v[196:199], v[214:217], v[2:5]
	v_mfma_f32_16x16x32_bf16 v[2:5], v[200:203], v[218:221], v[2:5]
	s_add_i32 s20, s20, 2
	s_add_u32 s8, s8, 0x100
	s_addc_u32 s9, s9, 0
	s_add_u32 s16, s16, 0x100
	s_addc_u32 s17, s17, 0
	s_cmp_lt_u32 s20, 40
	s_barrier
	s_cbranch_scc1 .LBB0_94
	s_mov_b64 s[0:1], 0x1580
	v_lshl_add_u64 v[134:135], v[130:131], 0, s[0:1]
	v_readfirstlane_b32 s0, v153
	s_mov_b32 m0, s0
	s_mov_b64 s[0:1], 0x59580
	v_lshl_add_u64 v[130:131], v[130:131], 0, s[0:1]
	v_readfirstlane_b32 s0, v154
	ds_read_b128 v[138:141], v149
	ds_read_b128 v[142:145], v149 offset:1024
	ds_read_b128 v[156:159], v149 offset:2048
	ds_read_b128 v[160:163], v149 offset:3072
	ds_read_b128 v[164:167], v132
	ds_read_b128 v[168:171], v132 offset:1024
	ds_read_b128 v[172:175], v150
	ds_read_b128 v[176:179], v150 offset:1024
	ds_read_b128 v[180:183], v151
	ds_read_b128 v[184:187], v151 offset:1024
	ds_read_b128 v[188:191], v152
	ds_read_b128 v[192:195], v152 offset:1024
	global_load_lds_dwordx4 v[134:135], off
	s_mov_b32 m0, s0
	s_nop 0
	global_load_lds_dwordx4 v[130:131], off
	s_waitcnt vmcnt(8)
	s_barrier
	s_waitcnt lgkmcnt(0)
	s_setprio 1
	s_waitcnt lgkmcnt(0)
	v_mfma_f32_16x16x32_bf16 v[126:129], v[164:167], v[138:141], v[126:129]
	v_mfma_f32_16x16x32_bf16 v[118:121], v[172:175], v[138:141], v[118:121]
	v_mfma_f32_16x16x32_bf16 v[110:113], v[180:183], v[138:141], v[110:113]
	v_mfma_f32_16x16x32_bf16 v[102:105], v[188:191], v[138:141], v[102:105]
	v_mfma_f32_16x16x32_bf16 v[126:129], v[168:171], v[142:145], v[126:129]
	v_mfma_f32_16x16x32_bf16 v[122:125], v[164:167], v[156:159], v[122:125]
	v_mfma_f32_16x16x32_bf16 v[118:121], v[176:179], v[142:145], v[118:121]
	v_mfma_f32_16x16x32_bf16 v[114:117], v[172:175], v[156:159], v[114:117]
	v_mfma_f32_16x16x32_bf16 v[110:113], v[184:187], v[142:145], v[110:113]
	v_mfma_f32_16x16x32_bf16 v[106:109], v[180:183], v[156:159], v[106:109]
	v_mfma_f32_16x16x32_bf16 v[102:105], v[192:195], v[142:145], v[102:105]
	v_mfma_f32_16x16x32_bf16 v[98:101], v[188:191], v[156:159], v[98:101]
	v_mfma_f32_16x16x32_bf16 v[122:125], v[168:171], v[160:163], v[122:125]
	v_mfma_f32_16x16x32_bf16 v[196:199], v[176:179], v[160:163], v[114:117]
	v_mfma_f32_16x16x32_bf16 v[200:203], v[184:187], v[160:163], v[106:109]
	v_mfma_f32_16x16x32_bf16 v[206:209], v[192:195], v[160:163], v[98:101]
	s_setprio 0
	s_barrier
; #define LDA(dst, b, h) for (int m = 0; m < 4; ++m) for (int k = 0; k < 2; ++k) \
;     dst[m][k] = *reinterpret_cast<const bf16x8*>((char*)SA(b, h) + lds_byte(wr * 64 + m * 16 + fr, k * 32 + fq * 8))
; #define LDB(dst, b, h) for (int n = 0; n < 2; ++n) for (int k = 0; k < 2; ++k) \
;     dst[n][k] = *reinterpret_cast<const bf16x8*>((char*)SB(b, h) + lds_byte(wc * 32 + n * 16 + fr, k * 32 + fq * 8))
; #define MMA(ai, bj, At_, Bt_) do { __builtin_amdgcn_s_setprio(1); \
;     for (int m = 0; m < 4; ++m) for (int n = 0; n < 2; ++n) for (int k = 0; k < 2; ++k) \
;       acc[ai][bj][m][n] = MFMA16(At_[m][k], Bt_[n][k], acc[ai][bj][m][n]); \
;     __builtin_amdgcn_s_setprio(0); } while (0)
; #define WAIT_V(n) asm volatile("s_waitcnt vmcnt(" #n ")" ::: "memory")
; #define WAIT_L(n) asm volatile("s_waitcnt lgkmcnt(" #n ")" ::: "memory")
; #define BAR __builtin_amdgcn_s_barrier()
; DI void gemm_core(WVP char* smem, const u16* __restrict__ A, int lda, int ar0, int ar1,
;                   const u16* __restrict__ B, int ldb, int bc0, int K, AccT& acc) {
;     ...
;     LDB(B1, 0, 1); BAR; WAIT_L(0); MMA(0, 1, At, B1); BAR;
;     LDA(At, 0, 1); WAIT_V(4); BAR; WAIT_L(0); MMA(1, 0, At, B0); MMA(1, 1, At, B1); BAR; }
;   { LDB(B0, 1, 0); LDA(At, 1, 0); WAIT_V(2); BAR; WAIT_L(0); MMA(0, 0, At, B0); BAR;
	s_nop 1
	ds_read_b128 v[98:101], v146
	ds_read_b128 v[106:109], v146 offset:1024
	ds_read_b128 v[114:117], v146 offset:2048
	ds_read_b128 v[146:149], v146 offset:3072
	s_barrier
	s_waitcnt lgkmcnt(0)
	s_setprio 1
	s_waitcnt lgkmcnt(0)
	v_mfma_f32_16x16x32_bf16 v[94:97], v[164:167], v[98:101], v[94:97]
	v_mfma_f32_16x16x32_bf16 v[86:89], v[172:175], v[98:101], v[86:89]
	v_mfma_f32_16x16x32_bf16 v[78:81], v[180:183], v[98:101], v[78:81]
	v_mfma_f32_16x16x32_bf16 v[70:73], v[188:191], v[98:101], v[70:73]
	v_mfma_f32_16x16x32_bf16 v[94:97], v[168:171], v[106:109], v[94:97]
	v_mfma_f32_16x16x32_bf16 v[90:93], v[164:167], v[114:117], v[90:93]
	v_mfma_f32_16x16x32_bf16 v[86:89], v[176:179], v[106:109], v[86:89]
	v_mfma_f32_16x16x32_bf16 v[82:85], v[172:175], v[114:117], v[82:85]
	v_mfma_f32_16x16x32_bf16 v[78:81], v[184:187], v[106:109], v[78:81]
	v_mfma_f32_16x16x32_bf16 v[74:77], v[180:183], v[114:117], v[74:77]
	v_mfma_f32_16x16x32_bf16 v[70:73], v[192:195], v[106:109], v[70:73]
	v_mfma_f32_16x16x32_bf16 v[66:69], v[188:191], v[114:117], v[66:69]
	v_mfma_f32_16x16x32_bf16 v[164:167], v[168:171], v[146:149], v[90:93]
	v_mfma_f32_16x16x32_bf16 v[168:171], v[176:179], v[146:149], v[82:85]
	v_mfma_f32_16x16x32_bf16 v[172:175], v[184:187], v[146:149], v[74:77]
	v_mfma_f32_16x16x32_bf16 v[176:179], v[192:195], v[146:149], v[66:69]
	s_setprio 0
	s_barrier
	s_nop 1
	ds_read_b128 v[66:69], v132 offset:16384
	ds_read_b128 v[74:77], v132 offset:17408
	ds_read_b128 v[82:85], v150 offset:16384
	ds_read_b128 v[90:93], v150 offset:17408
	ds_read_b128 v[180:183], v151 offset:16384
	ds_read_b128 v[184:187], v151 offset:17408
	ds_read_b128 v[188:191], v152 offset:16384
	ds_read_b128 v[192:195], v152 offset:17408
	s_waitcnt vmcnt(4)
	s_barrier
	s_waitcnt lgkmcnt(0)
	s_setprio 1
	s_waitcnt lgkmcnt(0)
	v_mfma_f32_16x16x32_bf16 v[62:65], v[66:69], v[138:141], v[62:65]
	v_mfma_f32_16x16x32_bf16 v[54:57], v[82:85], v[138:141], v[54:57]
	v_mfma_f32_16x16x32_bf16 v[42:45], v[180:183], v[156:159], v[42:45]
	v_mfma_f32_16x16x32_bf16 v[38:41], v[188:191], v[138:141], v[38:41]
	v_mfma_f32_16x16x32_bf16 v[62:65], v[74:77], v[142:145], v[62:65]
	v_mfma_f32_16x16x32_bf16 v[58:61], v[66:69], v[156:159], v[58:61]
	v_mfma_f32_16x16x32_bf16 v[54:57], v[90:93], v[142:145], v[54:57]
	v_mfma_f32_16x16x32_bf16 v[50:53], v[82:85], v[156:159], v[50:53]
	v_mfma_f32_16x16x32_bf16 v[46:49], v[180:183], v[138:141], v[46:49]
	v_mfma_f32_16x16x32_bf16 v[42:45], v[184:187], v[160:163], v[42:45]
	v_mfma_f32_16x16x32_bf16 v[38:41], v[192:195], v[142:145], v[38:41]
	v_mfma_f32_16x16x32_bf16 v[34:37], v[188:191], v[156:159], v[34:37]
	v_mfma_f32_16x16x32_bf16 v[210:213], v[74:77], v[160:163], v[58:61]
	v_mfma_f32_16x16x32_bf16 v[214:217], v[90:93], v[160:163], v[50:53]
	v_mfma_f32_16x16x32_bf16 v[218:221], v[184:187], v[142:145], v[46:49]
	v_mfma_f32_16x16x32_bf16 v[138:141], v[192:195], v[160:163], v[34:37]
	s_setprio 0
	s_setprio 1
	v_mfma_f32_16x16x32_bf16 v[30:33], v[66:69], v[98:101], v[30:33]
	v_mfma_f32_16x16x32_bf16 v[22:25], v[82:85], v[98:101], v[22:25]
	v_mfma_f32_16x16x32_bf16 v[10:13], v[180:183], v[114:117], v[10:13]
	v_mfma_f32_16x16x32_bf16 v[30:33], v[74:77], v[106:109], v[30:33]
	v_mfma_f32_16x16x32_bf16 v[26:29], v[66:69], v[114:117], v[26:29]
	v_mfma_f32_16x16x32_bf16 v[22:25], v[90:93], v[106:109], v[22:25]
	v_mfma_f32_16x16x32_bf16 v[18:21], v[82:85], v[114:117], v[18:21]
	v_mfma_f32_16x16x32_bf16 v[14:17], v[180:183], v[98:101], v[14:17]
	v_mfma_f32_16x16x32_bf16 v[10:13], v[184:187], v[146:149], v[10:13]
	v_mfma_f32_16x16x32_bf16 v[6:9], v[188:191], v[98:101], v[6:9]
	v_mfma_f32_16x16x32_bf16 v[2:5], v[188:191], v[114:117], v[2:5]
	v_mfma_f32_16x16x32_bf16 v[142:145], v[74:77], v[146:149], v[26:29]
	v_mfma_f32_16x16x32_bf16 v[154:157], v[90:93], v[146:149], v[18:21]
	v_mfma_f32_16x16x32_bf16 v[158:161], v[184:187], v[106:109], v[14:17]
	v_mfma_f32_16x16x32_bf16 v[180:183], v[192:195], v[106:109], v[6:9]
	v_mfma_f32_16x16x32_bf16 v[146:149], v[192:195], v[146:149], v[2:5]
	s_setprio 0
	s_barrier
	ds_read_b128 v[184:187], v137
	ds_read_b128 v[188:191], v137 offset:1024
	ds_read_b128 v[192:195], v137 offset:2048
	ds_read_b128 v[134:137], v137 offset:3072
	ds_read_b128 v[2:5], v132 offset:32768
	ds_read_b128 v[6:9], v132 offset:33792
	ds_read_b128 v[14:17], v150 offset:32768
	ds_read_b128 v[18:21], v150 offset:33792
	ds_read_b128 v[222:225], v151 offset:32768
	ds_read_b128 v[226:229], v151 offset:33792
	ds_read_b128 v[230:233], v152 offset:32768
	ds_read_b128 v[234:237], v152 offset:33792
	s_waitcnt vmcnt(2)
	s_barrier
; #define LDA(dst, b, h) for (int m = 0; m < 4; ++m) for (int k = 0; k < 2; ++k) \
;     dst[m][k] = *reinterpret_cast<const bf16x8*>((char*)SA(b, h) + lds_byte(wr * 64 + m * 16 + fr, k * 32 + fq * 8))
; #define LDB(dst, b, h) for (int n = 0; n < 2; ++n) for (int k = 0; k < 2; ++k) \
;     dst[n][k] = *reinterpret_cast<const bf16x8*>((char*)SB(b, h) + lds_byte(wc * 32 + n * 16 + fr, k * 32 + fq * 8))
; #define MMA(ai, bj, At_, Bt_) do { __builtin_amdgcn_s_setprio(1); \
;     for (int m = 0; m < 4; ++m) for (int n = 0; n < 2; ++n) for (int k = 0; k < 2; ++k) \
;       acc[ai][bj][m][n] = MFMA16(At_[m][k], Bt_[n][k], acc[ai][bj][m][n]); \
;     __builtin_amdgcn_s_setprio(0); } while (0)
; #define WAIT_V(n) asm volatile("s_waitcnt vmcnt(" #n ")" ::: "memory")
; #define WAIT_L(n) asm volatile("s_waitcnt lgkmcnt(" #n ")" ::: "memory")
; #define BAR __builtin_amdgcn_s_barrier()
; DI void gemm_core(WVP char* smem, const u16* __restrict__ A, int lda, int ar0, int ar1,
;                   const u16* __restrict__ B, int ldb, int bc0, int K, AccT& acc) {
;     ...
;   { LDB(B0, 1, 0); LDA(At, 1, 0); WAIT_V(2); BAR; WAIT_L(0); MMA(0, 0, At, B0); BAR;
;     LDB(B1, 1, 1); WAIT_V(0); BAR; WAIT_L(0); MMA(0, 1, At, B1); BAR;
;     LDA(At, 1, 1); BAR; WAIT_L(0); MMA(1, 0, At, B0); MMA(1, 1, At, B1); BAR; }
;   if (wr == 0) BAR;
	s_waitcnt lgkmcnt(0)
	s_setprio 1
	s_waitcnt lgkmcnt(0)
	v_mfma_f32_16x16x32_bf16 v[26:29], v[2:5], v[184:187], v[126:129]
	v_mfma_f32_16x16x32_bf16 v[114:117], v[6:9], v[188:191], v[26:29]
	v_mfma_f32_16x16x32_bf16 v[26:29], v[2:5], v[192:195], v[122:125]
	v_mfma_f32_16x16x32_bf16 v[106:109], v[6:9], v[134:137], v[26:29]
	v_mfma_f32_16x16x32_bf16 v[26:29], v[14:17], v[184:187], v[118:121]
	v_mfma_f32_16x16x32_bf16 v[98:101], v[18:21], v[188:191], v[26:29]
	v_mfma_f32_16x16x32_bf16 v[26:29], v[14:17], v[192:195], v[196:199]
	v_mfma_f32_16x16x32_bf16 v[90:93], v[18:21], v[134:137], v[26:29]
	v_mfma_f32_16x16x32_bf16 v[26:29], v[222:225], v[184:187], v[110:113]
	v_mfma_f32_16x16x32_bf16 v[82:85], v[226:229], v[188:191], v[26:29]
	v_mfma_f32_16x16x32_bf16 v[26:29], v[222:225], v[192:195], v[200:203]
	v_mfma_f32_16x16x32_bf16 v[74:77], v[226:229], v[134:137], v[26:29]
	v_mfma_f32_16x16x32_bf16 v[26:29], v[230:233], v[184:187], v[102:105]
	v_mfma_f32_16x16x32_bf16 v[66:69], v[234:237], v[188:191], v[26:29]
	v_mfma_f32_16x16x32_bf16 v[26:29], v[230:233], v[192:195], v[206:209]
	v_mfma_f32_16x16x32_bf16 v[58:61], v[234:237], v[134:137], v[26:29]
	s_setprio 0
	s_barrier
	ds_read_b128 v[122:125], v133
	ds_read_b128 v[196:199], v133 offset:1024
	ds_read_b128 v[200:203], v133 offset:2048
	ds_read_b128 v[206:209], v133 offset:3072
	s_waitcnt vmcnt(0)
	s_barrier
	s_waitcnt lgkmcnt(0)
	s_setprio 1
	s_waitcnt lgkmcnt(0)
	v_mfma_f32_16x16x32_bf16 v[26:29], v[2:5], v[122:125], v[94:97]
	v_mfma_f32_16x16x32_bf16 v[2:5], v[2:5], v[200:203], v[164:167]
	v_mfma_f32_16x16x32_bf16 v[46:49], v[6:9], v[206:209], v[2:5]
	v_mfma_f32_16x16x32_bf16 v[2:5], v[14:17], v[122:125], v[86:89]
	v_mfma_f32_16x16x32_bf16 v[34:37], v[18:21], v[196:199], v[2:5]
	v_mfma_f32_16x16x32_bf16 v[2:5], v[14:17], v[200:203], v[168:171]
	v_mfma_f32_16x16x32_bf16 v[50:53], v[6:9], v[196:199], v[26:29]
	v_mfma_f32_16x16x32_bf16 v[26:29], v[18:21], v[206:209], v[2:5]
	v_mfma_f32_16x16x32_bf16 v[2:5], v[222:225], v[122:125], v[78:81]
	v_mfma_f32_16x16x32_bf16 v[18:21], v[226:229], v[196:199], v[2:5]
	v_mfma_f32_16x16x32_bf16 v[2:5], v[222:225], v[200:203], v[172:175]
	v_mfma_f32_16x16x32_bf16 v[14:17], v[226:229], v[206:209], v[2:5]
	v_mfma_f32_16x16x32_bf16 v[2:5], v[230:233], v[122:125], v[70:73]
	v_mfma_f32_16x16x32_bf16 v[6:9], v[234:237], v[196:199], v[2:5]
	v_mfma_f32_16x16x32_bf16 v[2:5], v[230:233], v[200:203], v[176:179]
	v_mfma_f32_16x16x32_bf16 v[2:5], v[234:237], v[206:209], v[2:5]
	s_setprio 0
	s_barrier
	ds_read_b128 v[162:165], v132 offset:49152
	ds_read_b128 v[130:133], v132 offset:50176
	ds_read_b128 v[166:169], v150 offset:49152
	ds_read_b128 v[170:173], v150 offset:50176
	ds_read_b128 v[174:177], v151 offset:49152
	ds_read_b128 v[222:225], v151 offset:50176
	ds_read_b128 v[226:229], v152 offset:49152
	ds_read_b128 v[150:153], v152 offset:50176
	s_barrier
	s_waitcnt lgkmcnt(0)
	s_setprio 1
	s_waitcnt lgkmcnt(0)
	v_mfma_f32_16x16x32_bf16 v[54:57], v[166:169], v[184:187], v[54:57]
	v_mfma_f32_16x16x32_bf16 v[62:65], v[162:165], v[184:187], v[62:65]
	v_mfma_f32_16x16x32_bf16 v[110:113], v[170:173], v[188:191], v[54:57]
	v_mfma_f32_16x16x32_bf16 v[54:57], v[166:169], v[192:195], v[214:217]
	v_mfma_f32_16x16x32_bf16 v[38:41], v[226:229], v[184:187], v[38:41]
	v_mfma_f32_16x16x32_bf16 v[118:121], v[130:133], v[188:191], v[62:65]
	v_mfma_f32_16x16x32_bf16 v[62:65], v[162:165], v[192:195], v[210:213]
	v_mfma_f32_16x16x32_bf16 v[102:105], v[170:173], v[134:137], v[54:57]
	v_mfma_f32_16x16x32_bf16 v[54:57], v[174:177], v[184:187], v[218:221]
	v_mfma_f32_16x16x32_bf16 v[42:45], v[174:177], v[192:195], v[42:45]
	v_mfma_f32_16x16x32_bf16 v[78:81], v[150:153], v[188:191], v[38:41]
	v_mfma_f32_16x16x32_bf16 v[38:41], v[226:229], v[192:195], v[138:141]
	v_mfma_f32_16x16x32_bf16 v[126:129], v[130:133], v[134:137], v[62:65]
	v_mfma_f32_16x16x32_bf16 v[86:89], v[222:225], v[188:191], v[54:57]
	v_mfma_f32_16x16x32_bf16 v[94:97], v[222:225], v[134:137], v[42:45]
	v_mfma_f32_16x16x32_bf16 v[70:73], v[150:153], v[134:137], v[38:41]
	s_setprio 0
	s_setprio 1
	v_mfma_f32_16x16x32_bf16 v[30:33], v[162:165], v[122:125], v[30:33]
	v_mfma_f32_16x16x32_bf16 v[22:25], v[166:169], v[122:125], v[22:25]
	v_mfma_f32_16x16x32_bf16 v[54:57], v[130:133], v[196:199], v[30:33]
	v_mfma_f32_16x16x32_bf16 v[30:33], v[162:165], v[200:203], v[142:145]
	v_mfma_f32_16x16x32_bf16 v[42:45], v[170:173], v[196:199], v[22:25]
	v_mfma_f32_16x16x32_bf16 v[22:25], v[166:169], v[200:203], v[154:157]
	v_mfma_f32_16x16x32_bf16 v[10:13], v[174:177], v[200:203], v[10:13]
	v_mfma_f32_16x16x32_bf16 v[62:65], v[130:133], v[206:209], v[30:33]
	v_mfma_f32_16x16x32_bf16 v[38:41], v[170:173], v[206:209], v[22:25]
	v_mfma_f32_16x16x32_bf16 v[22:25], v[174:177], v[122:125], v[158:161]
	v_mfma_f32_16x16x32_bf16 v[30:33], v[222:225], v[206:209], v[10:13]
	v_mfma_f32_16x16x32_bf16 v[10:13], v[226:229], v[122:125], v[180:183]
	v_mfma_f32_16x16x32_bf16 v[122:125], v[226:229], v[200:203], v[146:149]
	v_mfma_f32_16x16x32_bf16 v[22:25], v[222:225], v[196:199], v[22:25]
	v_mfma_f32_16x16x32_bf16 v[10:13], v[150:153], v[196:199], v[10:13]
	v_mfma_f32_16x16x32_bf16 v[130:133], v[150:153], v[206:209], v[122:125]
	s_setprio 0
	s_cmp_gt_u32 s18, 3
	s_barrier
	s_cbranch_scc0 .LBB0_144
	s_mov_b64 s[8:9], -1
	s_and_b64 vcc, exec, s[12:13]
	s_cbranch_vccnz .LBB0_145

; #define STAGE_A(P, br, kt) do { const char* _g = (const char*)(A + (long)(br) * lda + (long)(kt) * BK); \
;     __builtin_amdgcn_global_load_lds((const unsigned*)(_g + (size_t)offA0), (unsigned*)((char*)(P) + sb0), 16, 0, 0); \
;     __builtin_amdgcn_global_load_lds((const unsigned*)(_g + (size_t)lda * 128 + (size_t)offA0), (unsigned*)((char*)(P) + sb1), 16, 0, 0); } while (0)
; #define STAGE_B(P, br, kt) do { const char* _g = (const char*)(B + (long)(br) * ldb + (long)(kt) * BK); \
;     __builtin_amdgcn_global_load_lds((const unsigned*)(_g + (size_t)offB0), (unsigned*)((char*)(P) + sb0), 16, 0, 0); \
;     __builtin_amdgcn_global_load_lds((const unsigned*)(_g + (size_t)ldb * 128 + (size_t)offB0), (unsigned*)((char*)(P) + sb1), 16, 0, 0); } while (0)
; #define LDA(dst, b, h) for (int m = 0; m < 4; ++m) for (int k = 0; k < 2; ++k) \
;     dst[m][k] = *reinterpret_cast<const bf16x8*>((char*)SA(b, h) + lds_byte(wr * 64 + m * 16 + fr, k * 32 + fq * 8))
; #define LDB(dst, b, h) for (int n = 0; n < 2; ++n) for (int k = 0; k < 2; ++k) \
;     dst[n][k] = *reinterpret_cast<const bf16x8*>((char*)SB(b, h) + lds_byte(wc * 32 + n * 16 + fr, k * 32 + fq * 8))
; #define MMA(ai, bj, At_, Bt_) do { __builtin_amdgcn_s_setprio(1); \
;     for (int m = 0; m < 4; ++m) for (int n = 0; n < 2; ++n) for (int k = 0; k < 2; ++k) \
;       acc[ai][bj][m][n] = MFMA16(At_[m][k], Bt_[n][k], acc[ai][bj][m][n]); \
;     __builtin_amdgcn_s_setprio(0); } while (0)
; #define WAIT_V(n) asm volatile("s_waitcnt vmcnt(" #n ")" ::: "memory")
; #define WAIT_L(n) asm volatile("s_waitcnt lgkmcnt(" #n ")" ::: "memory")
; #define BAR __builtin_amdgcn_s_barrier()
; #define SCHED __builtin_amdgcn_sched_barrier(0)
; DI void gemm_core(WVP char* smem, const u16* __restrict__ A, int lda, int ar0, int ar1,
;                   const u16* __restrict__ B, int ldb, int bc0, int K, AccT& acc) {
;     ...
;     LDB(B0, 0, 0); SCHED; LDA(At, 0, 0); STAGE_A(SA(1, 1), ac1, t + 1);
;     WAIT_L(8); BAR; WAIT_L(0); MMA(0, 0, At, B0); BAR; SCHED;
;     LDB(B1, 0, 1); STAGE_B(SB(0, 0), bb0, t + 2);
;     BAR; WAIT_L(0); MMA(0, 1, At, B1); BAR;
;     LDA(At, 0, 1); STAGE_A(SA(0, 0), ac0, t + 2);
;     BAR; WAIT_L(0); MMA(1, 0, At, B0); BAR; SCHED;
;     STAGE_B(SB(0, 1), bb1, t + 2);
;     WAIT_V(6); BAR; MMA(1, 1, At, B1); BAR;
.LBB0_169:
	v_add_u32_e32 v150, s0, v148
	v_add_u32_e32 v151, s1, v148
	v_add_u32_e32 v152, s9, v148
	ds_read_b128 v[156:159], v149
	ds_read_b128 v[160:163], v149 offset:1024
	ds_read_b128 v[164:167], v149 offset:2048
	ds_read_b128 v[168:171], v149 offset:3072
	ds_read_b128 v[172:175], v132
	ds_read_b128 v[176:179], v132 offset:1024
	ds_read_b128 v[180:183], v150
	ds_read_b128 v[184:187], v150 offset:1024
	ds_read_b128 v[188:191], v151
	ds_read_b128 v[192:195], v151 offset:1024
	ds_read_b128 v[196:199], v152
	ds_read_b128 v[200:203], v152 offset:1024
	ds_read_b128 v[206:209], v147
	ds_read_b128 v[210:213], v147 offset:1024
	ds_read_b128 v[214:217], v147 offset:2048
	ds_read_b128 v[218:221], v147 offset:3072
	v_add_u32_e32 v153, 0xc000, v135
	v_lshl_add_u64 v[224:225], s[16:17], 0, v[0:1]
	s_mov_b64 s[20:21], 0x1e880080
	v_lshl_add_u64 v[222:223], v[224:225], 0, s[20:21]
	v_readfirstlane_b32 s19, v153
	s_mov_b32 m0, s19
	s_nop 0
	global_load_lds_dwordx4 v[222:223], off
	v_add_u32_e32 v154, 0xe000, v135
	v_lshl_add_u64 v[224:225], s[16:17], 0, v[0:1]
	s_mov_b64 s[20:21], 0x1e8a0080
	v_lshl_add_u64 v[222:223], v[224:225], 0, s[20:21]
	v_readfirstlane_b32 s19, v154
	s_mov_b32 m0, s19
	s_nop 0
	global_load_lds_dwordx4 v[222:223], off
	s_waitcnt vmcnt(8)
	s_waitcnt lgkmcnt(0)
	s_barrier
	v_mfma_f32_16x16x32_bf16 v[126:129], v[172:175], v[156:159], v[126:129]
	v_mfma_f32_16x16x32_bf16 v[126:129], v[176:179], v[160:163], v[126:129]
	v_mfma_f32_16x16x32_bf16 v[122:125], v[172:175], v[164:167], v[122:125]
	v_mfma_f32_16x16x32_bf16 v[122:125], v[176:179], v[168:171], v[122:125]
	v_mfma_f32_16x16x32_bf16 v[118:121], v[180:183], v[156:159], v[118:121]
	v_mfma_f32_16x16x32_bf16 v[118:121], v[184:187], v[160:163], v[118:121]
	v_mfma_f32_16x16x32_bf16 v[114:117], v[180:183], v[164:167], v[114:117]
	v_mfma_f32_16x16x32_bf16 v[114:117], v[184:187], v[168:171], v[114:117]
	v_mfma_f32_16x16x32_bf16 v[110:113], v[188:191], v[156:159], v[110:113]
	v_mfma_f32_16x16x32_bf16 v[110:113], v[192:195], v[160:163], v[110:113]
	v_mfma_f32_16x16x32_bf16 v[106:109], v[188:191], v[164:167], v[106:109]
	v_mfma_f32_16x16x32_bf16 v[106:109], v[192:195], v[168:171], v[106:109]
	v_mfma_f32_16x16x32_bf16 v[102:105], v[196:199], v[156:159], v[102:105]
	v_mfma_f32_16x16x32_bf16 v[102:105], v[200:203], v[160:163], v[102:105]
	v_mfma_f32_16x16x32_bf16 v[98:101], v[196:199], v[164:167], v[98:101]
	v_mfma_f32_16x16x32_bf16 v[98:101], v[200:203], v[168:171], v[98:101]
	v_mfma_f32_16x16x32_bf16 v[94:97], v[172:175], v[206:209], v[94:97]
	v_mfma_f32_16x16x32_bf16 v[94:97], v[176:179], v[210:213], v[94:97]
	v_mfma_f32_16x16x32_bf16 v[90:93], v[172:175], v[214:217], v[90:93]
	v_mfma_f32_16x16x32_bf16 v[90:93], v[176:179], v[218:221], v[90:93]
	v_mfma_f32_16x16x32_bf16 v[86:89], v[180:183], v[206:209], v[86:89]
	v_mfma_f32_16x16x32_bf16 v[86:89], v[184:187], v[210:213], v[86:89]
	v_mfma_f32_16x16x32_bf16 v[82:85], v[180:183], v[214:217], v[82:85]
	v_mfma_f32_16x16x32_bf16 v[82:85], v[184:187], v[218:221], v[82:85]
	v_mfma_f32_16x16x32_bf16 v[78:81], v[188:191], v[206:209], v[78:81]
	v_mfma_f32_16x16x32_bf16 v[78:81], v[192:195], v[210:213], v[78:81]
	v_mfma_f32_16x16x32_bf16 v[74:77], v[188:191], v[214:217], v[74:77]
	v_mfma_f32_16x16x32_bf16 v[74:77], v[192:195], v[218:221], v[74:77]
	v_mfma_f32_16x16x32_bf16 v[70:73], v[196:199], v[206:209], v[70:73]
	v_mfma_f32_16x16x32_bf16 v[70:73], v[200:203], v[210:213], v[70:73]
	v_mfma_f32_16x16x32_bf16 v[66:69], v[196:199], v[214:217], v[66:69]
	v_mfma_f32_16x16x32_bf16 v[66:69], v[200:203], v[218:221], v[66:69]
	s_barrier
	ds_read_b128 v[172:175], v132 offset:16384
	ds_read_b128 v[176:179], v132 offset:17408
	ds_read_b128 v[180:183], v150 offset:16384
	ds_read_b128 v[184:187], v150 offset:17408
	ds_read_b128 v[188:191], v151 offset:16384
	ds_read_b128 v[192:195], v151 offset:17408
	ds_read_b128 v[196:199], v152 offset:16384
	ds_read_b128 v[200:203], v152 offset:17408
	v_lshl_add_u64 v[224:225], s[12:13], 0, v[0:1]
	v_lshl_add_u64 v[222:223], v[224:225], 0, s[80:81]
	v_readfirstlane_b32 s19, v133
	s_mov_b32 m0, s19
	s_nop 0
	global_load_lds_dwordx4 v[222:223], off
	v_add_u32_e32 v155, 0x2000, v133
	v_lshl_add_u64 v[224:225], s[12:13], 0, v[0:1]
	v_lshl_add_u64 v[222:223], v[224:225], 0, s[82:83]
	v_readfirstlane_b32 s19, v155
	s_mov_b32 m0, s19
	s_nop 0
	global_load_lds_dwordx4 v[222:223], off
	v_lshl_add_u64 v[224:225], s[14:15], 0, v[0:1]
	v_lshl_add_u64 v[222:223], v[224:225], 0, s[22:23]
	v_readfirstlane_b32 s19, v135
	s_mov_b32 m0, s19
	s_nop 0
	global_load_lds_dwordx4 v[222:223], off
	v_lshl_add_u64 v[224:225], s[14:15], 0, v[0:1]
	v_lshl_add_u64 v[222:223], v[224:225], 0, s[24:25]
	v_readfirstlane_b32 s19, v136
	s_mov_b32 m0, s19
	s_nop 0
	global_load_lds_dwordx4 v[222:223], off
	v_lshl_add_u64 v[224:225], s[12:13], 0, v[0:1]
	v_lshl_add_u64 v[222:223], v[224:225], 0, s[88:89]
	v_readfirstlane_b32 s19, v138
	s_mov_b32 m0, s19
	s_nop 0
	global_load_lds_dwordx4 v[222:223], off
	v_add_u32_e32 v155, 0x2000, v138
	v_lshl_add_u64 v[224:225], s[12:13], 0, v[0:1]
	v_lshl_add_u64 v[222:223], v[224:225], 0, s[90:91]
	v_readfirstlane_b32 s19, v155
	s_mov_b32 m0, s19
	s_nop 0
	global_load_lds_dwordx4 v[222:223], off
	s_waitcnt vmcnt(8)
	s_waitcnt lgkmcnt(0)
	s_barrier
; #define STAGE_A(P, br, kt) do { const char* _g = (const char*)(A + (long)(br) * lda + (long)(kt) * BK); \
;     __builtin_amdgcn_global_load_lds((const unsigned*)(_g + (size_t)offA0), (unsigned*)((char*)(P) + sb0), 16, 0, 0); \
;     __builtin_amdgcn_global_load_lds((const unsigned*)(_g + (size_t)lda * 128 + (size_t)offA0), (unsigned*)((char*)(P) + sb1), 16, 0, 0); } while (0)
; #define STAGE_B(P, br, kt) do { const char* _g = (const char*)(B + (long)(br) * ldb + (long)(kt) * BK); \
;     __builtin_amdgcn_global_load_lds((const unsigned*)(_g + (size_t)offB0), (unsigned*)((char*)(P) + sb0), 16, 0, 0); \
;     __builtin_amdgcn_global_load_lds((const unsigned*)(_g + (size_t)ldb * 128 + (size_t)offB0), (unsigned*)((char*)(P) + sb1), 16, 0, 0); } while (0)
; #define LDA(dst, b, h) for (int m = 0; m < 4; ++m) for (int k = 0; k < 2; ++k) \
;     dst[m][k] = *reinterpret_cast<const bf16x8*>((char*)SA(b, h) + lds_byte(wr * 64 + m * 16 + fr, k * 32 + fq * 8))
; #define LDB(dst, b, h) for (int n = 0; n < 2; ++n) for (int k = 0; k < 2; ++k) \
;     dst[n][k] = *reinterpret_cast<const bf16x8*>((char*)SB(b, h) + lds_byte(wc * 32 + n * 16 + fr, k * 32 + fq * 8))
; #define MMA(ai, bj, At_, Bt_) do { __builtin_amdgcn_s_setprio(1); \
;     for (int m = 0; m < 4; ++m) for (int n = 0; n < 2; ++n) for (int k = 0; k < 2; ++k) \
;       acc[ai][bj][m][n] = MFMA16(At_[m][k], Bt_[n][k], acc[ai][bj][m][n]); \
;     __builtin_amdgcn_s_setprio(0); } while (0)
; #define WAIT_V(n) asm volatile("s_waitcnt vmcnt(" #n ")" ::: "memory")
; #define WAIT_L(n) asm volatile("s_waitcnt lgkmcnt(" #n ")" ::: "memory")
; #define BAR __builtin_amdgcn_s_barrier()
; #define SCHED __builtin_amdgcn_sched_barrier(0)
; DI void gemm_core(WVP char* smem, const u16* __restrict__ A, int lda, int ar0, int ar1,
;                   const u16* __restrict__ B, int ldb, int bc0, int K, AccT& acc) {
;     ...
;     WAIT_V(6); BAR; MMA(1, 1, At, B1); BAR;
;     LDB(B0, 1, 0); SCHED; LDA(At, 1, 0); STAGE_A(SA(0, 1), ac1, t + 2);
;     WAIT_L(8); BAR; WAIT_L(0); MMA(0, 0, At, B0); BAR; SCHED;
;     LDB(B1, 1, 1); STAGE_B(SB(1, 0), bb0, t + 3);
;     BAR; WAIT_L(0); MMA(0, 1, At, B1); BAR;
	v_mfma_f32_16x16x32_bf16 v[62:65], v[172:175], v[156:159], v[62:65]
	v_mfma_f32_16x16x32_bf16 v[62:65], v[176:179], v[160:163], v[62:65]
	v_mfma_f32_16x16x32_bf16 v[58:61], v[172:175], v[164:167], v[58:61]
	v_mfma_f32_16x16x32_bf16 v[58:61], v[176:179], v[168:171], v[58:61]
	v_mfma_f32_16x16x32_bf16 v[54:57], v[180:183], v[156:159], v[54:57]
	v_mfma_f32_16x16x32_bf16 v[54:57], v[184:187], v[160:163], v[54:57]
	v_mfma_f32_16x16x32_bf16 v[50:53], v[180:183], v[164:167], v[50:53]
	v_mfma_f32_16x16x32_bf16 v[50:53], v[184:187], v[168:171], v[50:53]
	v_mfma_f32_16x16x32_bf16 v[46:49], v[188:191], v[156:159], v[46:49]
	v_mfma_f32_16x16x32_bf16 v[46:49], v[192:195], v[160:163], v[46:49]
	v_mfma_f32_16x16x32_bf16 v[42:45], v[188:191], v[164:167], v[42:45]
	v_mfma_f32_16x16x32_bf16 v[42:45], v[192:195], v[168:171], v[42:45]
	v_mfma_f32_16x16x32_bf16 v[38:41], v[196:199], v[156:159], v[38:41]
	v_mfma_f32_16x16x32_bf16 v[38:41], v[200:203], v[160:163], v[38:41]
	v_mfma_f32_16x16x32_bf16 v[34:37], v[196:199], v[164:167], v[34:37]
	v_mfma_f32_16x16x32_bf16 v[34:37], v[200:203], v[168:171], v[34:37]
	v_mfma_f32_16x16x32_bf16 v[30:33], v[172:175], v[206:209], v[30:33]
	v_mfma_f32_16x16x32_bf16 v[30:33], v[176:179], v[210:213], v[30:33]
	v_mfma_f32_16x16x32_bf16 v[26:29], v[172:175], v[214:217], v[26:29]
	v_mfma_f32_16x16x32_bf16 v[26:29], v[176:179], v[218:221], v[26:29]
	v_mfma_f32_16x16x32_bf16 v[22:25], v[180:183], v[206:209], v[22:25]
	v_mfma_f32_16x16x32_bf16 v[22:25], v[184:187], v[210:213], v[22:25]
	v_mfma_f32_16x16x32_bf16 v[18:21], v[180:183], v[214:217], v[18:21]
	v_mfma_f32_16x16x32_bf16 v[18:21], v[184:187], v[218:221], v[18:21]
	v_mfma_f32_16x16x32_bf16 v[14:17], v[188:191], v[206:209], v[14:17]
	v_mfma_f32_16x16x32_bf16 v[14:17], v[192:195], v[210:213], v[14:17]
	v_mfma_f32_16x16x32_bf16 v[10:13], v[188:191], v[214:217], v[10:13]
	v_mfma_f32_16x16x32_bf16 v[10:13], v[192:195], v[218:221], v[10:13]
	v_mfma_f32_16x16x32_bf16 v[6:9], v[196:199], v[206:209], v[6:9]
	v_mfma_f32_16x16x32_bf16 v[6:9], v[200:203], v[210:213], v[6:9]
	v_mfma_f32_16x16x32_bf16 v[2:5], v[196:199], v[214:217], v[2:5]
	v_mfma_f32_16x16x32_bf16 v[2:5], v[200:203], v[218:221], v[2:5]
	s_barrier
	ds_read_b128 v[156:159], v137
	ds_read_b128 v[160:163], v137 offset:1024
	ds_read_b128 v[164:167], v137 offset:2048
	ds_read_b128 v[168:171], v137 offset:3072
	ds_read_b128 v[172:175], v132 offset:32768
	ds_read_b128 v[176:179], v132 offset:33792
	ds_read_b128 v[180:183], v150 offset:32768
	ds_read_b128 v[184:187], v150 offset:33792
	ds_read_b128 v[188:191], v151 offset:32768
	ds_read_b128 v[192:195], v151 offset:33792
	ds_read_b128 v[196:199], v152 offset:32768
	ds_read_b128 v[200:203], v152 offset:33792
	ds_read_b128 v[206:209], v134
	ds_read_b128 v[210:213], v134 offset:1024
	ds_read_b128 v[214:217], v134 offset:2048
	ds_read_b128 v[218:221], v134 offset:3072
	v_lshl_add_u64 v[224:225], s[16:17], 0, v[0:1]
	v_lshl_add_u64 v[222:223], v[224:225], 0, s[22:23]
	v_readfirstlane_b32 s19, v139
	s_mov_b32 m0, s19
	s_nop 0
	global_load_lds_dwordx4 v[222:223], off
	v_lshl_add_u64 v[224:225], s[16:17], 0, v[0:1]
	v_lshl_add_u64 v[222:223], v[224:225], 0, s[24:25]
	v_readfirstlane_b32 s19, v140
	s_mov_b32 m0, s19
	s_nop 0
	global_load_lds_dwordx4 v[222:223], off
	s_waitcnt vmcnt(8)
	s_waitcnt lgkmcnt(0)
	s_barrier
	v_mfma_f32_16x16x32_bf16 v[126:129], v[172:175], v[156:159], v[126:129]
	v_mfma_f32_16x16x32_bf16 v[126:129], v[176:179], v[160:163], v[126:129]
	v_mfma_f32_16x16x32_bf16 v[122:125], v[172:175], v[164:167], v[122:125]
	v_mfma_f32_16x16x32_bf16 v[122:125], v[176:179], v[168:171], v[122:125]
	v_mfma_f32_16x16x32_bf16 v[118:121], v[180:183], v[156:159], v[118:121]
	v_mfma_f32_16x16x32_bf16 v[118:121], v[184:187], v[160:163], v[118:121]
	v_mfma_f32_16x16x32_bf16 v[114:117], v[180:183], v[164:167], v[114:117]
	v_mfma_f32_16x16x32_bf16 v[114:117], v[184:187], v[168:171], v[114:117]
	v_mfma_f32_16x16x32_bf16 v[110:113], v[188:191], v[156:159], v[110:113]
	v_mfma_f32_16x16x32_bf16 v[110:113], v[192:195], v[160:163], v[110:113]
	v_mfma_f32_16x16x32_bf16 v[106:109], v[188:191], v[164:167], v[106:109]
	v_mfma_f32_16x16x32_bf16 v[106:109], v[192:195], v[168:171], v[106:109]
	v_mfma_f32_16x16x32_bf16 v[102:105], v[196:199], v[156:159], v[102:105]
	v_mfma_f32_16x16x32_bf16 v[102:105], v[200:203], v[160:163], v[102:105]
	v_mfma_f32_16x16x32_bf16 v[98:101], v[196:199], v[164:167], v[98:101]
	v_mfma_f32_16x16x32_bf16 v[98:101], v[200:203], v[168:171], v[98:101]
	v_mfma_f32_16x16x32_bf16 v[94:97], v[172:175], v[206:209], v[94:97]
	v_mfma_f32_16x16x32_bf16 v[94:97], v[176:179], v[210:213], v[94:97]
	v_mfma_f32_16x16x32_bf16 v[90:93], v[172:175], v[214:217], v[90:93]
	v_mfma_f32_16x16x32_bf16 v[90:93], v[176:179], v[218:221], v[90:93]
	v_mfma_f32_16x16x32_bf16 v[86:89], v[180:183], v[206:209], v[86:89]
	v_mfma_f32_16x16x32_bf16 v[86:89], v[184:187], v[210:213], v[86:89]
	v_mfma_f32_16x16x32_bf16 v[82:85], v[180:183], v[214:217], v[82:85]
	v_mfma_f32_16x16x32_bf16 v[82:85], v[184:187], v[218:221], v[82:85]
	v_mfma_f32_16x16x32_bf16 v[78:81], v[188:191], v[206:209], v[78:81]
	v_mfma_f32_16x16x32_bf16 v[78:81], v[192:195], v[210:213], v[78:81]
	v_mfma_f32_16x16x32_bf16 v[74:77], v[188:191], v[214:217], v[74:77]
	v_mfma_f32_16x16x32_bf16 v[74:77], v[192:195], v[218:221], v[74:77]
	v_mfma_f32_16x16x32_bf16 v[70:73], v[196:199], v[206:209], v[70:73]
	v_mfma_f32_16x16x32_bf16 v[70:73], v[200:203], v[210:213], v[70:73]
	v_mfma_f32_16x16x32_bf16 v[66:69], v[196:199], v[214:217], v[66:69]
	v_mfma_f32_16x16x32_bf16 v[66:69], v[200:203], v[218:221], v[66:69]
	s_barrier
; #define STAGE_A(P, br, kt) do { const char* _g = (const char*)(A + (long)(br) * lda + (long)(kt) * BK); \
;     __builtin_amdgcn_global_load_lds((const unsigned*)(_g + (size_t)offA0), (unsigned*)((char*)(P) + sb0), 16, 0, 0); \
;     __builtin_amdgcn_global_load_lds((const unsigned*)(_g + (size_t)lda * 128 + (size_t)offA0), (unsigned*)((char*)(P) + sb1), 16, 0, 0); } while (0)
; #define STAGE_B(P, br, kt) do { const char* _g = (const char*)(B + (long)(br) * ldb + (long)(kt) * BK); \
;     __builtin_amdgcn_global_load_lds((const unsigned*)(_g + (size_t)offB0), (unsigned*)((char*)(P) + sb0), 16, 0, 0); \
;     __builtin_amdgcn_global_load_lds((const unsigned*)(_g + (size_t)ldb * 128 + (size_t)offB0), (unsigned*)((char*)(P) + sb1), 16, 0, 0); } while (0)
; #define LDA(dst, b, h) for (int m = 0; m < 4; ++m) for (int k = 0; k < 2; ++k) \
;     dst[m][k] = *reinterpret_cast<const bf16x8*>((char*)SA(b, h) + lds_byte(wr * 64 + m * 16 + fr, k * 32 + fq * 8))
; #define LDB(dst, b, h) for (int n = 0; n < 2; ++n) for (int k = 0; k < 2; ++k) \
;     dst[n][k] = *reinterpret_cast<const bf16x8*>((char*)SB(b, h) + lds_byte(wc * 32 + n * 16 + fr, k * 32 + fq * 8))
; #define MMA(ai, bj, At_, Bt_) do { __builtin_amdgcn_s_setprio(1); \
;     for (int m = 0; m < 4; ++m) for (int n = 0; n < 2; ++n) for (int k = 0; k < 2; ++k) \
;       acc[ai][bj][m][n] = MFMA16(At_[m][k], Bt_[n][k], acc[ai][bj][m][n]); \
;     __builtin_amdgcn_s_setprio(0); } while (0)
; #define WAIT_V(n) asm volatile("s_waitcnt vmcnt(" #n ")" ::: "memory")
; #define WAIT_L(n) asm volatile("s_waitcnt lgkmcnt(" #n ")" ::: "memory")
; #define BAR __builtin_amdgcn_s_barrier()
; #define SCHED __builtin_amdgcn_sched_barrier(0)
; DI void gemm_core(WVP char* smem, const u16* __restrict__ A, int lda, int ar0, int ar1,
;                   const u16* __restrict__ B, int ldb, int bc0, int K, AccT& acc) {
;     ...
;     LDA(At, 1, 1); STAGE_A(SA(1, 0), ac0, t + 3);
;     BAR; WAIT_L(0); MMA(1, 0, At, B0); BAR; SCHED;
;     STAGE_B(SB(1, 1), bb1, t + 3);
;     WAIT_V(6); BAR; MMA(1, 1, At, B1); BAR;
;   }
;   { LDB(B0, 0, 0); LDA(At, 0, 0); STAGE_A(SA(1, 1), ac1, nt - 1);
;     BAR; WAIT_L(0); MMA(0, 0, At, B0); BAR;
	ds_read_b128 v[172:175], v132 offset:49152
	ds_read_b128 v[176:179], v132 offset:50176
	ds_read_b128 v[180:183], v150 offset:49152
	ds_read_b128 v[184:187], v150 offset:50176
	ds_read_b128 v[188:191], v151 offset:49152
	ds_read_b128 v[192:195], v151 offset:50176
	ds_read_b128 v[196:199], v152 offset:49152
	ds_read_b128 v[200:203], v152 offset:50176
	v_lshl_add_u64 v[224:225], s[12:13], 0, v[0:1]
	v_lshl_add_u64 v[222:223], v[224:225], 0, s[92:93]
	v_readfirstlane_b32 s19, v141
	s_mov_b32 m0, s19
	s_nop 0
	global_load_lds_dwordx4 v[222:223], off
	v_lshl_add_u64 v[224:225], s[12:13], 0, v[0:1]
	v_lshl_add_u64 v[222:223], v[224:225], 0, s[94:95]
	v_readfirstlane_b32 s19, v142
	s_mov_b32 m0, s19
	s_nop 0
	global_load_lds_dwordx4 v[222:223], off
	v_lshl_add_u64 v[224:225], s[14:15], 0, v[0:1]
	s_mov_b64 s[20:21], 0x1e880180
	v_lshl_add_u64 v[222:223], v[224:225], 0, s[20:21]
	v_readfirstlane_b32 s19, v143
	s_mov_b32 m0, s19
	s_nop 0
	global_load_lds_dwordx4 v[222:223], off
	v_lshl_add_u64 v[224:225], s[14:15], 0, v[0:1]
	s_mov_b64 s[20:21], 0x1e8a0180
	v_lshl_add_u64 v[222:223], v[224:225], 0, s[20:21]
	v_readfirstlane_b32 s19, v144
	s_mov_b32 m0, s19
	s_nop 0
	global_load_lds_dwordx4 v[222:223], off
	v_lshl_add_u64 v[224:225], s[12:13], 0, v[0:1]
	v_lshl_add_u64 v[222:223], v[224:225], 0, s[96:97]
	v_readfirstlane_b32 s19, v145
	s_mov_b32 m0, s19
	s_nop 0
	global_load_lds_dwordx4 v[222:223], off
	v_lshl_add_u64 v[224:225], s[12:13], 0, v[0:1]
	v_lshl_add_u64 v[222:223], v[224:225], 0, s[72:73]
	v_readfirstlane_b32 s19, v146
	s_mov_b32 m0, s19
	s_nop 0
	global_load_lds_dwordx4 v[222:223], off
	s_waitcnt vmcnt(8)
	s_waitcnt lgkmcnt(0)
	s_barrier
	v_mfma_f32_16x16x32_bf16 v[62:65], v[172:175], v[156:159], v[62:65]
	v_mfma_f32_16x16x32_bf16 v[62:65], v[176:179], v[160:163], v[62:65]
	v_mfma_f32_16x16x32_bf16 v[58:61], v[172:175], v[164:167], v[58:61]
	v_mfma_f32_16x16x32_bf16 v[58:61], v[176:179], v[168:171], v[58:61]
	v_mfma_f32_16x16x32_bf16 v[54:57], v[180:183], v[156:159], v[54:57]
	v_mfma_f32_16x16x32_bf16 v[54:57], v[184:187], v[160:163], v[54:57]
	v_mfma_f32_16x16x32_bf16 v[50:53], v[180:183], v[164:167], v[50:53]
	v_mfma_f32_16x16x32_bf16 v[50:53], v[184:187], v[168:171], v[50:53]
	v_mfma_f32_16x16x32_bf16 v[46:49], v[188:191], v[156:159], v[46:49]
	v_mfma_f32_16x16x32_bf16 v[46:49], v[192:195], v[160:163], v[46:49]
	v_mfma_f32_16x16x32_bf16 v[42:45], v[188:191], v[164:167], v[42:45]
	v_mfma_f32_16x16x32_bf16 v[42:45], v[192:195], v[168:171], v[42:45]
	v_mfma_f32_16x16x32_bf16 v[38:41], v[196:199], v[156:159], v[38:41]
	v_mfma_f32_16x16x32_bf16 v[38:41], v[200:203], v[160:163], v[38:41]
	v_mfma_f32_16x16x32_bf16 v[34:37], v[196:199], v[164:167], v[34:37]
	v_mfma_f32_16x16x32_bf16 v[34:37], v[200:203], v[168:171], v[34:37]
	v_mfma_f32_16x16x32_bf16 v[30:33], v[172:175], v[206:209], v[30:33]
	v_mfma_f32_16x16x32_bf16 v[30:33], v[176:179], v[210:213], v[30:33]
	v_mfma_f32_16x16x32_bf16 v[26:29], v[172:175], v[214:217], v[26:29]
	v_mfma_f32_16x16x32_bf16 v[26:29], v[176:179], v[218:221], v[26:29]
	v_mfma_f32_16x16x32_bf16 v[22:25], v[180:183], v[206:209], v[22:25]
	v_mfma_f32_16x16x32_bf16 v[22:25], v[184:187], v[210:213], v[22:25]
	v_mfma_f32_16x16x32_bf16 v[18:21], v[180:183], v[214:217], v[18:21]
	v_mfma_f32_16x16x32_bf16 v[18:21], v[184:187], v[218:221], v[18:21]
	v_mfma_f32_16x16x32_bf16 v[14:17], v[188:191], v[206:209], v[14:17]
	v_mfma_f32_16x16x32_bf16 v[14:17], v[192:195], v[210:213], v[14:17]
	v_mfma_f32_16x16x32_bf16 v[10:13], v[188:191], v[214:217], v[10:13]
	v_mfma_f32_16x16x32_bf16 v[10:13], v[192:195], v[218:221], v[10:13]
	v_mfma_f32_16x16x32_bf16 v[6:9], v[196:199], v[206:209], v[6:9]
	v_mfma_f32_16x16x32_bf16 v[6:9], v[200:203], v[210:213], v[6:9]
	v_mfma_f32_16x16x32_bf16 v[2:5], v[196:199], v[214:217], v[2:5]
	v_mfma_f32_16x16x32_bf16 v[2:5], v[200:203], v[218:221], v[2:5]
	s_add_i32 s18, s18, 2
	s_add_u32 s12, s12, 0x100
	s_addc_u32 s13, s13, 0
	s_add_u32 s14, s14, 0x100
	s_addc_u32 s15, s15, 0
	s_add_u32 s16, s16, 0x100
	s_addc_u32 s17, s17, 0
	s_cmp_lt_u32 s18, 12
	s_barrier
	s_cbranch_scc1 .LBB0_169
	s_mov_b64 s[0:1], 0x780
	ds_read_b128 v[138:141], v149
	ds_read_b128 v[142:145], v149 offset:1024
	ds_read_b128 v[156:159], v149 offset:2048
	ds_read_b128 v[160:163], v149 offset:3072
	ds_read_b128 v[164:167], v132
	ds_read_b128 v[168:171], v132 offset:1024
	ds_read_b128 v[172:175], v150
	ds_read_b128 v[176:179], v150 offset:1024
	ds_read_b128 v[180:183], v151
	ds_read_b128 v[184:187], v151 offset:1024
	ds_read_b128 v[188:191], v152
	ds_read_b128 v[192:195], v152 offset:1024
	v_lshl_add_u64 v[148:149], v[130:131], 0, s[0:1]
	v_readfirstlane_b32 s0, v153
	s_mov_b32 m0, s0
	s_mov_b64 s[0:1], 0x20780
	v_lshl_add_u64 v[130:131], v[130:131], 0, s[0:1]
	v_readfirstlane_b32 s0, v154
	global_load_lds_dwordx4 v[148:149], off
	s_mov_b32 m0, s0
	s_nop 0
	global_load_lds_dwordx4 v[130:131], off
	s_waitcnt vmcnt(8)
	s_barrier
	s_waitcnt lgkmcnt(0)
	s_setprio 1
	s_waitcnt lgkmcnt(0)
	v_mfma_f32_16x16x32_bf16 v[126:129], v[164:167], v[138:141], v[126:129]
	v_mfma_f32_16x16x32_bf16 v[118:121], v[172:175], v[138:141], v[118:121]
	v_mfma_f32_16x16x32_bf16 v[110:113], v[180:183], v[138:141], v[110:113]
	v_mfma_f32_16x16x32_bf16 v[102:105], v[188:191], v[138:141], v[102:105]
	v_mfma_f32_16x16x32_bf16 v[126:129], v[168:171], v[142:145], v[126:129]
	v_mfma_f32_16x16x32_bf16 v[122:125], v[164:167], v[156:159], v[122:125]
	v_mfma_f32_16x16x32_bf16 v[118:121], v[176:179], v[142:145], v[118:121]
	v_mfma_f32_16x16x32_bf16 v[114:117], v[172:175], v[156:159], v[114:117]
	v_mfma_f32_16x16x32_bf16 v[110:113], v[184:187], v[142:145], v[110:113]
	v_mfma_f32_16x16x32_bf16 v[106:109], v[180:183], v[156:159], v[106:109]
	v_mfma_f32_16x16x32_bf16 v[102:105], v[192:195], v[142:145], v[102:105]
	v_mfma_f32_16x16x32_bf16 v[98:101], v[188:191], v[156:159], v[98:101]
	v_mfma_f32_16x16x32_bf16 v[196:199], v[168:171], v[160:163], v[122:125]
	v_mfma_f32_16x16x32_bf16 v[200:203], v[176:179], v[160:163], v[114:117]
	v_mfma_f32_16x16x32_bf16 v[206:209], v[184:187], v[160:163], v[106:109]
	v_mfma_f32_16x16x32_bf16 v[210:213], v[192:195], v[160:163], v[98:101]
	s_setprio 0
	s_barrier
; #define LDA(dst, b, h) for (int m = 0; m < 4; ++m) for (int k = 0; k < 2; ++k) \
;     dst[m][k] = *reinterpret_cast<const bf16x8*>((char*)SA(b, h) + lds_byte(wr * 64 + m * 16 + fr, k * 32 + fq * 8))
; #define LDB(dst, b, h) for (int n = 0; n < 2; ++n) for (int k = 0; k < 2; ++k) \
;     dst[n][k] = *reinterpret_cast<const bf16x8*>((char*)SB(b, h) + lds_byte(wc * 32 + n * 16 + fr, k * 32 + fq * 8))
; #define MMA(ai, bj, At_, Bt_) do { __builtin_amdgcn_s_setprio(1); \
;     for (int m = 0; m < 4; ++m) for (int n = 0; n < 2; ++n) for (int k = 0; k < 2; ++k) \
;       acc[ai][bj][m][n] = MFMA16(At_[m][k], Bt_[n][k], acc[ai][bj][m][n]); \
;     __builtin_amdgcn_s_setprio(0); } while (0)
; #define WAIT_V(n) asm volatile("s_waitcnt vmcnt(" #n ")" ::: "memory")
; #define WAIT_L(n) asm volatile("s_waitcnt lgkmcnt(" #n ")" ::: "memory")
; #define BAR __builtin_amdgcn_s_barrier()
; DI void gemm_core(WVP char* smem, const u16* __restrict__ A, int lda, int ar0, int ar1,
;                   const u16* __restrict__ B, int ldb, int bc0, int K, AccT& acc) {
;     ...
;     LDB(B1, 0, 1); BAR; WAIT_L(0); MMA(0, 1, At, B1); BAR;
;     LDA(At, 0, 1); WAIT_V(4); BAR; WAIT_L(0); MMA(1, 0, At, B0); MMA(1, 1, At, B1); BAR; }
;   { LDB(B0, 1, 0); LDA(At, 1, 0); WAIT_V(2); BAR; WAIT_L(0); MMA(0, 0, At, B0); BAR;
	s_nop 1
	ds_read_b128 v[98:101], v147
	ds_read_b128 v[106:109], v147 offset:1024
	ds_read_b128 v[114:117], v147 offset:2048
	ds_read_b128 v[122:125], v147 offset:3072
	s_barrier
	s_waitcnt lgkmcnt(0)
	s_setprio 1
	s_waitcnt lgkmcnt(0)
	v_mfma_f32_16x16x32_bf16 v[94:97], v[164:167], v[98:101], v[94:97]
	v_mfma_f32_16x16x32_bf16 v[86:89], v[172:175], v[98:101], v[86:89]
	v_mfma_f32_16x16x32_bf16 v[78:81], v[180:183], v[98:101], v[78:81]
	v_mfma_f32_16x16x32_bf16 v[70:73], v[188:191], v[98:101], v[70:73]
	v_mfma_f32_16x16x32_bf16 v[94:97], v[168:171], v[106:109], v[94:97]
	v_mfma_f32_16x16x32_bf16 v[90:93], v[164:167], v[114:117], v[90:93]
	v_mfma_f32_16x16x32_bf16 v[86:89], v[176:179], v[106:109], v[86:89]
	v_mfma_f32_16x16x32_bf16 v[82:85], v[172:175], v[114:117], v[82:85]
	v_mfma_f32_16x16x32_bf16 v[78:81], v[184:187], v[106:109], v[78:81]
	v_mfma_f32_16x16x32_bf16 v[74:77], v[180:183], v[114:117], v[74:77]
	v_mfma_f32_16x16x32_bf16 v[70:73], v[192:195], v[106:109], v[70:73]
	v_mfma_f32_16x16x32_bf16 v[66:69], v[188:191], v[114:117], v[66:69]
	v_mfma_f32_16x16x32_bf16 v[146:149], v[168:171], v[122:125], v[90:93]
	v_mfma_f32_16x16x32_bf16 v[164:167], v[176:179], v[122:125], v[82:85]
	v_mfma_f32_16x16x32_bf16 v[168:171], v[184:187], v[122:125], v[74:77]
	v_mfma_f32_16x16x32_bf16 v[172:175], v[192:195], v[122:125], v[66:69]
	s_setprio 0
	s_barrier
	s_nop 1
	ds_read_b128 v[66:69], v132 offset:16384
	ds_read_b128 v[74:77], v132 offset:17408
	ds_read_b128 v[82:85], v150 offset:16384
	ds_read_b128 v[90:93], v150 offset:17408
	ds_read_b128 v[176:179], v151 offset:16384
	ds_read_b128 v[180:183], v151 offset:17408
	ds_read_b128 v[184:187], v152 offset:16384
	ds_read_b128 v[188:191], v152 offset:17408
	s_waitcnt vmcnt(4)
	s_barrier
	s_waitcnt lgkmcnt(0)
	s_setprio 1
	s_waitcnt lgkmcnt(0)
	v_mfma_f32_16x16x32_bf16 v[62:65], v[66:69], v[138:141], v[62:65]
	v_mfma_f32_16x16x32_bf16 v[54:57], v[82:85], v[138:141], v[54:57]
	v_mfma_f32_16x16x32_bf16 v[46:49], v[176:179], v[138:141], v[46:49]
	v_mfma_f32_16x16x32_bf16 v[38:41], v[184:187], v[138:141], v[38:41]
	v_mfma_f32_16x16x32_bf16 v[62:65], v[74:77], v[142:145], v[62:65]
	v_mfma_f32_16x16x32_bf16 v[58:61], v[66:69], v[156:159], v[58:61]
	v_mfma_f32_16x16x32_bf16 v[54:57], v[90:93], v[142:145], v[54:57]
	v_mfma_f32_16x16x32_bf16 v[50:53], v[82:85], v[156:159], v[50:53]
	v_mfma_f32_16x16x32_bf16 v[46:49], v[180:183], v[142:145], v[46:49]
	v_mfma_f32_16x16x32_bf16 v[42:45], v[176:179], v[156:159], v[42:45]
	v_mfma_f32_16x16x32_bf16 v[38:41], v[188:191], v[142:145], v[38:41]
	v_mfma_f32_16x16x32_bf16 v[34:37], v[184:187], v[156:159], v[34:37]
	v_mfma_f32_16x16x32_bf16 v[192:195], v[74:77], v[160:163], v[58:61]
	v_mfma_f32_16x16x32_bf16 v[214:217], v[90:93], v[160:163], v[50:53]
	v_mfma_f32_16x16x32_bf16 v[218:221], v[180:183], v[160:163], v[42:45]
	v_mfma_f32_16x16x32_bf16 v[138:141], v[188:191], v[160:163], v[34:37]
	s_setprio 0
	s_setprio 1
	v_mfma_f32_16x16x32_bf16 v[30:33], v[66:69], v[98:101], v[30:33]
	v_mfma_f32_16x16x32_bf16 v[22:25], v[82:85], v[98:101], v[22:25]
	v_mfma_f32_16x16x32_bf16 v[14:17], v[176:179], v[98:101], v[14:17]
	v_mfma_f32_16x16x32_bf16 v[6:9], v[184:187], v[98:101], v[6:9]
	v_mfma_f32_16x16x32_bf16 v[30:33], v[74:77], v[106:109], v[30:33]
	v_mfma_f32_16x16x32_bf16 v[26:29], v[66:69], v[114:117], v[26:29]
	v_mfma_f32_16x16x32_bf16 v[22:25], v[90:93], v[106:109], v[22:25]
	v_mfma_f32_16x16x32_bf16 v[18:21], v[82:85], v[114:117], v[18:21]
	v_mfma_f32_16x16x32_bf16 v[14:17], v[180:183], v[106:109], v[14:17]
	v_mfma_f32_16x16x32_bf16 v[10:13], v[176:179], v[114:117], v[10:13]
	v_mfma_f32_16x16x32_bf16 v[6:9], v[188:191], v[106:109], v[6:9]
	v_mfma_f32_16x16x32_bf16 v[2:5], v[184:187], v[114:117], v[2:5]
	v_mfma_f32_16x16x32_bf16 v[142:145], v[74:77], v[122:125], v[26:29]
	v_mfma_f32_16x16x32_bf16 v[154:157], v[90:93], v[122:125], v[18:21]
	v_mfma_f32_16x16x32_bf16 v[158:161], v[180:183], v[122:125], v[10:13]
	v_mfma_f32_16x16x32_bf16 v[176:179], v[188:191], v[122:125], v[2:5]
	s_setprio 0
	s_barrier
	ds_read_b128 v[180:183], v137
	ds_read_b128 v[184:187], v137 offset:1024
	ds_read_b128 v[188:191], v137 offset:2048
	ds_read_b128 v[222:225], v137 offset:3072
	ds_read_b128 v[2:5], v132 offset:32768
	ds_read_b128 v[10:13], v132 offset:33792
	ds_read_b128 v[18:21], v150 offset:32768
	ds_read_b128 v[26:29], v150 offset:33792
	ds_read_b128 v[226:229], v151 offset:32768
	ds_read_b128 v[230:233], v151 offset:33792
	ds_read_b128 v[234:237], v152 offset:32768
	ds_read_b128 v[238:241], v152 offset:33792
	s_waitcnt vmcnt(2)
	s_barrier
; #define LDA(dst, b, h) for (int m = 0; m < 4; ++m) for (int k = 0; k < 2; ++k) \
;     dst[m][k] = *reinterpret_cast<const bf16x8*>((char*)SA(b, h) + lds_byte(wr * 64 + m * 16 + fr, k * 32 + fq * 8))
; #define LDB(dst, b, h) for (int n = 0; n < 2; ++n) for (int k = 0; k < 2; ++k) \
;     dst[n][k] = *reinterpret_cast<const bf16x8*>((char*)SB(b, h) + lds_byte(wc * 32 + n * 16 + fr, k * 32 + fq * 8))
; #define MMA(ai, bj, At_, Bt_) do { __builtin_amdgcn_s_setprio(1); \
;     for (int m = 0; m < 4; ++m) for (int n = 0; n < 2; ++n) for (int k = 0; k < 2; ++k) \
;       acc[ai][bj][m][n] = MFMA16(At_[m][k], Bt_[n][k], acc[ai][bj][m][n]); \
;     __builtin_amdgcn_s_setprio(0); } while (0)
; #define WAIT_V(n) asm volatile("s_waitcnt vmcnt(" #n ")" ::: "memory")
; #define WAIT_L(n) asm volatile("s_waitcnt lgkmcnt(" #n ")" ::: "memory")
; #define BAR __builtin_amdgcn_s_barrier()
; DI void gemm_core(WVP char* smem, const u16* __restrict__ A, int lda, int ar0, int ar1,
;                   const u16* __restrict__ B, int ldb, int bc0, int K, AccT& acc) {
;     ...
;   { LDB(B0, 1, 0); LDA(At, 1, 0); WAIT_V(2); BAR; WAIT_L(0); MMA(0, 0, At, B0); BAR;
;     LDB(B1, 1, 1); WAIT_V(0); BAR; WAIT_L(0); MMA(0, 1, At, B1); BAR;
;     LDA(At, 1, 1); BAR; WAIT_L(0); MMA(1, 0, At, B0); MMA(1, 1, At, B1); BAR; }
;   if (wr == 0) BAR;
	s_waitcnt lgkmcnt(0)
	s_setprio 1
	s_waitcnt lgkmcnt(0)
	v_mfma_f32_16x16x32_bf16 v[34:37], v[2:5], v[180:183], v[126:129]
	v_mfma_f32_16x16x32_bf16 v[122:125], v[10:13], v[184:187], v[34:37]
	v_mfma_f32_16x16x32_bf16 v[34:37], v[2:5], v[188:191], v[196:199]
	v_mfma_f32_16x16x32_bf16 v[114:117], v[10:13], v[222:225], v[34:37]
	v_mfma_f32_16x16x32_bf16 v[34:37], v[18:21], v[180:183], v[118:121]
	v_mfma_f32_16x16x32_bf16 v[106:109], v[26:29], v[184:187], v[34:37]
	v_mfma_f32_16x16x32_bf16 v[34:37], v[18:21], v[188:191], v[200:203]
	v_mfma_f32_16x16x32_bf16 v[98:101], v[26:29], v[222:225], v[34:37]
	v_mfma_f32_16x16x32_bf16 v[34:37], v[226:229], v[180:183], v[110:113]
	v_mfma_f32_16x16x32_bf16 v[90:93], v[230:233], v[184:187], v[34:37]
	v_mfma_f32_16x16x32_bf16 v[34:37], v[226:229], v[188:191], v[206:209]
	v_mfma_f32_16x16x32_bf16 v[82:85], v[230:233], v[222:225], v[34:37]
	v_mfma_f32_16x16x32_bf16 v[34:37], v[234:237], v[180:183], v[102:105]
	v_mfma_f32_16x16x32_bf16 v[74:77], v[238:241], v[184:187], v[34:37]
	v_mfma_f32_16x16x32_bf16 v[34:37], v[234:237], v[188:191], v[210:213]
	v_mfma_f32_16x16x32_bf16 v[66:69], v[238:241], v[222:225], v[34:37]
	s_setprio 0
	s_barrier
	ds_read_b128 v[196:199], v134
	ds_read_b128 v[200:203], v134 offset:1024
	ds_read_b128 v[206:209], v134 offset:2048
	ds_read_b128 v[134:137], v134 offset:3072
	s_waitcnt vmcnt(0)
	s_barrier
	s_waitcnt lgkmcnt(0)
	s_setprio 1
	s_waitcnt lgkmcnt(0)
	v_mfma_f32_16x16x32_bf16 v[34:37], v[2:5], v[196:199], v[94:97]
	v_mfma_f32_16x16x32_bf16 v[2:5], v[2:5], v[206:209], v[146:149]
	v_mfma_f32_16x16x32_bf16 v[50:53], v[10:13], v[134:137], v[2:5]
	v_mfma_f32_16x16x32_bf16 v[2:5], v[18:21], v[196:199], v[86:89]
	v_mfma_f32_16x16x32_bf16 v[42:45], v[26:29], v[200:203], v[2:5]
	v_mfma_f32_16x16x32_bf16 v[2:5], v[18:21], v[206:209], v[164:167]
	v_mfma_f32_16x16x32_bf16 v[58:61], v[10:13], v[200:203], v[34:37]
	v_mfma_f32_16x16x32_bf16 v[34:37], v[26:29], v[134:137], v[2:5]
	v_mfma_f32_16x16x32_bf16 v[2:5], v[226:229], v[196:199], v[78:81]
	v_mfma_f32_16x16x32_bf16 v[26:29], v[230:233], v[200:203], v[2:5]
	v_mfma_f32_16x16x32_bf16 v[2:5], v[226:229], v[206:209], v[168:171]
	v_mfma_f32_16x16x32_bf16 v[18:21], v[230:233], v[134:137], v[2:5]
	v_mfma_f32_16x16x32_bf16 v[2:5], v[234:237], v[196:199], v[70:73]
	v_mfma_f32_16x16x32_bf16 v[10:13], v[238:241], v[200:203], v[2:5]
	v_mfma_f32_16x16x32_bf16 v[2:5], v[234:237], v[206:209], v[172:175]
	v_mfma_f32_16x16x32_bf16 v[2:5], v[238:241], v[134:137], v[2:5]
	s_setprio 0
	s_barrier
	ds_read_b128 v[146:149], v132 offset:49152
	ds_read_b128 v[130:133], v132 offset:50176
	ds_read_b128 v[162:165], v150 offset:49152
	ds_read_b128 v[166:169], v150 offset:50176
	ds_read_b128 v[170:173], v151 offset:49152
	ds_read_b128 v[210:213], v151 offset:50176
	ds_read_b128 v[226:229], v152 offset:49152
	ds_read_b128 v[150:153], v152 offset:50176
	s_barrier
	s_waitcnt lgkmcnt(0)
	s_setprio 1
	s_waitcnt lgkmcnt(0)
	v_mfma_f32_16x16x32_bf16 v[62:65], v[146:149], v[180:183], v[62:65]
	v_mfma_f32_16x16x32_bf16 v[54:57], v[162:165], v[180:183], v[54:57]
	v_mfma_f32_16x16x32_bf16 v[46:49], v[170:173], v[180:183], v[46:49]
	v_mfma_f32_16x16x32_bf16 v[38:41], v[226:229], v[180:183], v[38:41]
	v_mfma_f32_16x16x32_bf16 v[126:129], v[130:133], v[184:187], v[62:65]
	v_mfma_f32_16x16x32_bf16 v[62:65], v[146:149], v[188:191], v[192:195]
	v_mfma_f32_16x16x32_bf16 v[110:113], v[166:169], v[184:187], v[54:57]
	v_mfma_f32_16x16x32_bf16 v[54:57], v[162:165], v[188:191], v[214:217]
	v_mfma_f32_16x16x32_bf16 v[94:97], v[210:213], v[184:187], v[46:49]
	v_mfma_f32_16x16x32_bf16 v[46:49], v[170:173], v[188:191], v[218:221]
	v_mfma_f32_16x16x32_bf16 v[78:81], v[150:153], v[184:187], v[38:41]
	v_mfma_f32_16x16x32_bf16 v[38:41], v[226:229], v[188:191], v[138:141]
	v_mfma_f32_16x16x32_bf16 v[118:121], v[130:133], v[222:225], v[62:65]
	v_mfma_f32_16x16x32_bf16 v[102:105], v[166:169], v[222:225], v[54:57]
	v_mfma_f32_16x16x32_bf16 v[86:89], v[210:213], v[222:225], v[46:49]
	v_mfma_f32_16x16x32_bf16 v[70:73], v[150:153], v[222:225], v[38:41]
	s_setprio 0
	s_setprio 1
	v_mfma_f32_16x16x32_bf16 v[30:33], v[146:149], v[196:199], v[30:33]
	v_mfma_f32_16x16x32_bf16 v[62:65], v[130:133], v[200:203], v[30:33]
	v_mfma_f32_16x16x32_bf16 v[30:33], v[146:149], v[206:209], v[142:145]
	v_mfma_f32_16x16x32_bf16 v[22:25], v[162:165], v[196:199], v[22:25]
	v_mfma_f32_16x16x32_bf16 v[14:17], v[170:173], v[196:199], v[14:17]
	v_mfma_f32_16x16x32_bf16 v[54:57], v[130:133], v[134:137], v[30:33]
	v_mfma_f32_16x16x32_bf16 v[46:49], v[166:169], v[200:203], v[22:25]
	v_mfma_f32_16x16x32_bf16 v[22:25], v[162:165], v[206:209], v[154:157]
	v_mfma_f32_16x16x32_bf16 v[30:33], v[210:213], v[200:203], v[14:17]
	v_mfma_f32_16x16x32_bf16 v[14:17], v[170:173], v[206:209], v[158:161]
	v_mfma_f32_16x16x32_bf16 v[6:9], v[226:229], v[196:199], v[6:9]
	v_mfma_f32_16x16x32_bf16 v[38:41], v[166:169], v[134:137], v[22:25]
	v_mfma_f32_16x16x32_bf16 v[22:25], v[210:213], v[134:137], v[14:17]
	v_mfma_f32_16x16x32_bf16 v[14:17], v[150:153], v[200:203], v[6:9]
	v_mfma_f32_16x16x32_bf16 v[6:9], v[226:229], v[206:209], v[176:179]
	v_mfma_f32_16x16x32_bf16 v[6:9], v[150:153], v[134:137], v[6:9]
	s_setprio 0
	s_cmp_gt_u32 s5, 3
	s_movk_i32 s5, 0x1600
	s_barrier
	s_cbranch_scc1 .LBB0_164
	s_barrier
	s_branch .LBB0_164

; #define STAGE_A(P, br, kt) do { const char* _g = (const char*)(A + (long)(br) * lda + (long)(kt) * BK); \
;     __builtin_amdgcn_global_load_lds((const unsigned*)(_g + (size_t)offA0), (unsigned*)((char*)(P) + sb0), 16, 0, 0); \
;     __builtin_amdgcn_global_load_lds((const unsigned*)(_g + (size_t)lda * 128 + (size_t)offA0), (unsigned*)((char*)(P) + sb1), 16, 0, 0); } while (0)
; #define STAGE_B(P, br, kt) do { const char* _g = (const char*)(B + (long)(br) * ldb + (long)(kt) * BK); \
;     __builtin_amdgcn_global_load_lds((const unsigned*)(_g + (size_t)offB0), (unsigned*)((char*)(P) + sb0), 16, 0, 0); \
;     __builtin_amdgcn_global_load_lds((const unsigned*)(_g + (size_t)ldb * 128 + (size_t)offB0), (unsigned*)((char*)(P) + sb1), 16, 0, 0); } while (0)
; #define LDA(dst, b, h) for (int m = 0; m < 4; ++m) for (int k = 0; k < 2; ++k) \
;     dst[m][k] = *reinterpret_cast<const bf16x8*>((char*)SA(b, h) + lds_byte(wr * 64 + m * 16 + fr, k * 32 + fq * 8))
; #define LDB(dst, b, h) for (int n = 0; n < 2; ++n) for (int k = 0; k < 2; ++k) \
;     dst[n][k] = *reinterpret_cast<const bf16x8*>((char*)SB(b, h) + lds_byte(wc * 32 + n * 16 + fr, k * 32 + fq * 8))
; #define MMA(ai, bj, At_, Bt_) do { __builtin_amdgcn_s_setprio(1); \
;     for (int m = 0; m < 4; ++m) for (int n = 0; n < 2; ++n) for (int k = 0; k < 2; ++k) \
;       acc[ai][bj][m][n] = MFMA16(At_[m][k], Bt_[n][k], acc[ai][bj][m][n]); \
;     __builtin_amdgcn_s_setprio(0); } while (0)
; #define WAIT_V(n) asm volatile("s_waitcnt vmcnt(" #n ")" ::: "memory")
; #define WAIT_L(n) asm volatile("s_waitcnt lgkmcnt(" #n ")" ::: "memory")
; #define BAR __builtin_amdgcn_s_barrier()
; #define SCHED __builtin_amdgcn_sched_barrier(0)
; DI void gemm_core(WVP char* smem, const u16* __restrict__ A, int lda, int ar0, int ar1,
;                   const u16* __restrict__ B, int ldb, int bc0, int K, AccT& acc) {
;     ...
;     LDB(B0, 0, 0); SCHED; LDA(At, 0, 0); STAGE_A(SA(1, 1), ac1, t + 1);
;     WAIT_L(8); BAR; WAIT_L(0); MMA(0, 0, At, B0); BAR; SCHED;
;     LDB(B1, 0, 1); STAGE_B(SB(0, 0), bb0, t + 2);
;     BAR; WAIT_L(0); MMA(0, 1, At, B1); BAR;
;     LDA(At, 0, 1); STAGE_A(SA(0, 0), ac0, t + 2);
;     BAR; WAIT_L(0); MMA(1, 0, At, B0); BAR; SCHED;
;     STAGE_B(SB(0, 1), bb1, t + 2);
;     WAIT_V(6); BAR; MMA(1, 1, At, B1); BAR;
.LBB0_187:
	v_add_u32_e32 v150, s0, v148
	v_add_u32_e32 v151, s1, v148
	v_add_u32_e32 v152, s20, v148
	ds_read_b128 v[156:159], v149
	ds_read_b128 v[160:163], v149 offset:1024
	ds_read_b128 v[164:167], v149 offset:2048
	ds_read_b128 v[168:171], v149 offset:3072
	ds_read_b128 v[172:175], v132
	ds_read_b128 v[176:179], v132 offset:1024
	ds_read_b128 v[180:183], v150
	ds_read_b128 v[184:187], v150 offset:1024
	ds_read_b128 v[188:191], v151
	ds_read_b128 v[192:195], v151 offset:1024
	ds_read_b128 v[196:199], v152
	ds_read_b128 v[200:203], v152 offset:1024
	ds_read_b128 v[206:209], v146
	ds_read_b128 v[210:213], v146 offset:1024
	ds_read_b128 v[214:217], v146 offset:2048
	ds_read_b128 v[218:221], v146 offset:3072
	v_add_u32_e32 v153, 0xc000, v135
	v_lshl_add_u64 v[224:225], s[18:19], 0, v[0:1]
	s_mov_b64 s[22:23], 0x1e6c0080
	v_lshl_add_u64 v[222:223], v[224:225], 0, s[22:23]
	v_readfirstlane_b32 s22, v153
	s_mov_b32 m0, s22
	s_nop 0
	global_load_lds_dwordx4 v[222:223], off
	v_add_u32_e32 v154, 0xe000, v135
	v_lshl_add_u64 v[224:225], s[18:19], 0, v[0:1]
	s_mov_b64 s[22:23], 0x1e6e0080
	v_lshl_add_u64 v[222:223], v[224:225], 0, s[22:23]
	v_readfirstlane_b32 s22, v154
	s_mov_b32 m0, s22
	s_nop 0
	global_load_lds_dwordx4 v[222:223], off
	s_waitcnt vmcnt(8)
	s_waitcnt lgkmcnt(0)
	s_barrier
	v_mfma_f32_16x16x32_bf16 v[126:129], v[172:175], v[156:159], v[126:129]
	v_mfma_f32_16x16x32_bf16 v[126:129], v[176:179], v[160:163], v[126:129]
	v_mfma_f32_16x16x32_bf16 v[122:125], v[172:175], v[164:167], v[122:125]
	v_mfma_f32_16x16x32_bf16 v[122:125], v[176:179], v[168:171], v[122:125]
	v_mfma_f32_16x16x32_bf16 v[118:121], v[180:183], v[156:159], v[118:121]
	v_mfma_f32_16x16x32_bf16 v[118:121], v[184:187], v[160:163], v[118:121]
	v_mfma_f32_16x16x32_bf16 v[114:117], v[180:183], v[164:167], v[114:117]
	v_mfma_f32_16x16x32_bf16 v[114:117], v[184:187], v[168:171], v[114:117]
	v_mfma_f32_16x16x32_bf16 v[110:113], v[188:191], v[156:159], v[110:113]
	v_mfma_f32_16x16x32_bf16 v[110:113], v[192:195], v[160:163], v[110:113]
	v_mfma_f32_16x16x32_bf16 v[106:109], v[188:191], v[164:167], v[106:109]
	v_mfma_f32_16x16x32_bf16 v[106:109], v[192:195], v[168:171], v[106:109]
	v_mfma_f32_16x16x32_bf16 v[102:105], v[196:199], v[156:159], v[102:105]
	v_mfma_f32_16x16x32_bf16 v[102:105], v[200:203], v[160:163], v[102:105]
	v_mfma_f32_16x16x32_bf16 v[98:101], v[196:199], v[164:167], v[98:101]
	v_mfma_f32_16x16x32_bf16 v[98:101], v[200:203], v[168:171], v[98:101]
	v_mfma_f32_16x16x32_bf16 v[94:97], v[172:175], v[206:209], v[94:97]
	v_mfma_f32_16x16x32_bf16 v[94:97], v[176:179], v[210:213], v[94:97]
	v_mfma_f32_16x16x32_bf16 v[82:85], v[172:175], v[214:217], v[82:85]
	v_mfma_f32_16x16x32_bf16 v[82:85], v[176:179], v[218:221], v[82:85]
	v_mfma_f32_16x16x32_bf16 v[66:69], v[180:183], v[206:209], v[66:69]
	v_mfma_f32_16x16x32_bf16 v[66:69], v[184:187], v[210:213], v[66:69]
	v_mfma_f32_16x16x32_bf16 v[54:57], v[180:183], v[214:217], v[54:57]
	v_mfma_f32_16x16x32_bf16 v[54:57], v[184:187], v[218:221], v[54:57]
	v_mfma_f32_16x16x32_bf16 v[50:53], v[188:191], v[206:209], v[50:53]
	v_mfma_f32_16x16x32_bf16 v[50:53], v[192:195], v[210:213], v[50:53]
	v_mfma_f32_16x16x32_bf16 v[46:49], v[188:191], v[214:217], v[46:49]
	v_mfma_f32_16x16x32_bf16 v[46:49], v[192:195], v[218:221], v[46:49]
	v_mfma_f32_16x16x32_bf16 v[42:45], v[196:199], v[206:209], v[42:45]
	v_mfma_f32_16x16x32_bf16 v[42:45], v[200:203], v[210:213], v[42:45]
	v_mfma_f32_16x16x32_bf16 v[38:41], v[196:199], v[214:217], v[38:41]
	v_mfma_f32_16x16x32_bf16 v[38:41], v[200:203], v[218:221], v[38:41]
	s_barrier
	ds_read_b128 v[172:175], v132 offset:16384
	ds_read_b128 v[176:179], v132 offset:17408
	ds_read_b128 v[180:183], v150 offset:16384
	ds_read_b128 v[184:187], v150 offset:17408
	ds_read_b128 v[188:191], v151 offset:16384
	ds_read_b128 v[192:195], v151 offset:17408
	ds_read_b128 v[196:199], v152 offset:16384
	ds_read_b128 v[200:203], v152 offset:17408
	v_lshl_add_u64 v[224:225], s[8:9], 0, v[0:1]
	s_mov_b64 s[22:23], 0x19000100
	v_lshl_add_u64 v[222:223], v[224:225], 0, s[22:23]
	v_readfirstlane_b32 s22, v134
	s_mov_b32 m0, s22
	s_nop 0
	global_load_lds_dwordx4 v[222:223], off
	v_add_u32_e32 v155, 0x2000, v134
	v_lshl_add_u64 v[224:225], s[8:9], 0, v[0:1]
	s_mov_b64 s[22:23], 0x19020100
	v_lshl_add_u64 v[222:223], v[224:225], 0, s[22:23]
	v_readfirstlane_b32 s22, v155
	s_mov_b32 m0, s22
	s_nop 0
	global_load_lds_dwordx4 v[222:223], off
	v_lshl_add_u64 v[224:225], s[18:19], 0, v[0:1]
	s_mov_b64 s[22:23], 0x1e680100
	v_lshl_add_u64 v[222:223], v[224:225], 0, s[22:23]
	v_readfirstlane_b32 s22, v135
	s_mov_b32 m0, s22
	s_nop 0
	global_load_lds_dwordx4 v[222:223], off
	v_lshl_add_u64 v[224:225], s[18:19], 0, v[0:1]
	s_mov_b64 s[22:23], 0x1e6a0100
	v_lshl_add_u64 v[222:223], v[224:225], 0, s[22:23]
	v_readfirstlane_b32 s22, v136
	s_mov_b32 m0, s22
	s_nop 0
	global_load_lds_dwordx4 v[222:223], off
	v_lshl_add_u64 v[224:225], s[8:9], 0, v[0:1]
	s_mov_b64 s[22:23], 0x19040100
	v_lshl_add_u64 v[222:223], v[224:225], 0, s[22:23]
	v_readfirstlane_b32 s22, v138
	s_mov_b32 m0, s22
	s_nop 0
	global_load_lds_dwordx4 v[222:223], off
	v_add_u32_e32 v155, 0x2000, v138
	v_lshl_add_u64 v[224:225], s[8:9], 0, v[0:1]
	s_mov_b64 s[22:23], 0x19060100
	v_lshl_add_u64 v[222:223], v[224:225], 0, s[22:23]
	v_readfirstlane_b32 s22, v155
	s_mov_b32 m0, s22
	s_nop 0
	global_load_lds_dwordx4 v[222:223], off
	s_waitcnt vmcnt(8)
	s_waitcnt lgkmcnt(0)
	s_barrier
; #define STAGE_A(P, br, kt) do { const char* _g = (const char*)(A + (long)(br) * lda + (long)(kt) * BK); \
;     __builtin_amdgcn_global_load_lds((const unsigned*)(_g + (size_t)offA0), (unsigned*)((char*)(P) + sb0), 16, 0, 0); \
;     __builtin_amdgcn_global_load_lds((const unsigned*)(_g + (size_t)lda * 128 + (size_t)offA0), (unsigned*)((char*)(P) + sb1), 16, 0, 0); } while (0)
; #define STAGE_B(P, br, kt) do { const char* _g = (const char*)(B + (long)(br) * ldb + (long)(kt) * BK); \
;     __builtin_amdgcn_global_load_lds((const unsigned*)(_g + (size_t)offB0), (unsigned*)((char*)(P) + sb0), 16, 0, 0); \
;     __builtin_amdgcn_global_load_lds((const unsigned*)(_g + (size_t)ldb * 128 + (size_t)offB0), (unsigned*)((char*)(P) + sb1), 16, 0, 0); } while (0)
; #define LDA(dst, b, h) for (int m = 0; m < 4; ++m) for (int k = 0; k < 2; ++k) \
;     dst[m][k] = *reinterpret_cast<const bf16x8*>((char*)SA(b, h) + lds_byte(wr * 64 + m * 16 + fr, k * 32 + fq * 8))
; #define LDB(dst, b, h) for (int n = 0; n < 2; ++n) for (int k = 0; k < 2; ++k) \
;     dst[n][k] = *reinterpret_cast<const bf16x8*>((char*)SB(b, h) + lds_byte(wc * 32 + n * 16 + fr, k * 32 + fq * 8))
; #define MMA(ai, bj, At_, Bt_) do { __builtin_amdgcn_s_setprio(1); \
;     for (int m = 0; m < 4; ++m) for (int n = 0; n < 2; ++n) for (int k = 0; k < 2; ++k) \
;       acc[ai][bj][m][n] = MFMA16(At_[m][k], Bt_[n][k], acc[ai][bj][m][n]); \
;     __builtin_amdgcn_s_setprio(0); } while (0)
; #define WAIT_V(n) asm volatile("s_waitcnt vmcnt(" #n ")" ::: "memory")
; #define WAIT_L(n) asm volatile("s_waitcnt lgkmcnt(" #n ")" ::: "memory")
; #define BAR __builtin_amdgcn_s_barrier()
; #define SCHED __builtin_amdgcn_sched_barrier(0)
; DI void gemm_core(WVP char* smem, const u16* __restrict__ A, int lda, int ar0, int ar1,
;                   const u16* __restrict__ B, int ldb, int bc0, int K, AccT& acc) {
;     ...
;     WAIT_V(6); BAR; MMA(1, 1, At, B1); BAR;
;     LDB(B0, 1, 0); SCHED; LDA(At, 1, 0); STAGE_A(SA(0, 1), ac1, t + 2);
;     WAIT_L(8); BAR; WAIT_L(0); MMA(0, 0, At, B0); BAR; SCHED;
;     LDB(B1, 1, 1); STAGE_B(SB(1, 0), bb0, t + 3);
;     BAR; WAIT_L(0); MMA(0, 1, At, B1); BAR;
	v_mfma_f32_16x16x32_bf16 v[34:37], v[172:175], v[156:159], v[34:37]
	v_mfma_f32_16x16x32_bf16 v[34:37], v[176:179], v[160:163], v[34:37]
	v_mfma_f32_16x16x32_bf16 v[30:33], v[172:175], v[164:167], v[30:33]
	v_mfma_f32_16x16x32_bf16 v[30:33], v[176:179], v[168:171], v[30:33]
	v_mfma_f32_16x16x32_bf16 v[26:29], v[180:183], v[156:159], v[26:29]
	v_mfma_f32_16x16x32_bf16 v[26:29], v[184:187], v[160:163], v[26:29]
	v_mfma_f32_16x16x32_bf16 v[22:25], v[180:183], v[164:167], v[22:25]
	v_mfma_f32_16x16x32_bf16 v[22:25], v[184:187], v[168:171], v[22:25]
	v_mfma_f32_16x16x32_bf16 v[18:21], v[188:191], v[156:159], v[18:21]
	v_mfma_f32_16x16x32_bf16 v[18:21], v[192:195], v[160:163], v[18:21]
	v_mfma_f32_16x16x32_bf16 v[14:17], v[188:191], v[164:167], v[14:17]
	v_mfma_f32_16x16x32_bf16 v[14:17], v[192:195], v[168:171], v[14:17]
	v_mfma_f32_16x16x32_bf16 v[10:13], v[196:199], v[156:159], v[10:13]
	v_mfma_f32_16x16x32_bf16 v[10:13], v[200:203], v[160:163], v[10:13]
	v_mfma_f32_16x16x32_bf16 v[6:9], v[196:199], v[164:167], v[6:9]
	v_mfma_f32_16x16x32_bf16 v[6:9], v[200:203], v[168:171], v[6:9]
	v_mfma_f32_16x16x32_bf16 v[2:5], v[172:175], v[206:209], v[2:5]
	v_mfma_f32_16x16x32_bf16 v[2:5], v[176:179], v[210:213], v[2:5]
	v_mfma_f32_16x16x32_bf16 v[58:61], v[172:175], v[214:217], v[58:61]
	v_mfma_f32_16x16x32_bf16 v[58:61], v[176:179], v[218:221], v[58:61]
	v_mfma_f32_16x16x32_bf16 v[62:65], v[180:183], v[206:209], v[62:65]
	v_mfma_f32_16x16x32_bf16 v[62:65], v[184:187], v[210:213], v[62:65]
	v_mfma_f32_16x16x32_bf16 v[70:73], v[180:183], v[214:217], v[70:73]
	v_mfma_f32_16x16x32_bf16 v[70:73], v[184:187], v[218:221], v[70:73]
	v_mfma_f32_16x16x32_bf16 v[74:77], v[188:191], v[206:209], v[74:77]
	v_mfma_f32_16x16x32_bf16 v[74:77], v[192:195], v[210:213], v[74:77]
	v_mfma_f32_16x16x32_bf16 v[78:81], v[188:191], v[214:217], v[78:81]
	v_mfma_f32_16x16x32_bf16 v[78:81], v[192:195], v[218:221], v[78:81]
	v_mfma_f32_16x16x32_bf16 v[86:89], v[196:199], v[206:209], v[86:89]
	v_mfma_f32_16x16x32_bf16 v[86:89], v[200:203], v[210:213], v[86:89]
	v_mfma_f32_16x16x32_bf16 v[90:93], v[196:199], v[214:217], v[90:93]
	v_mfma_f32_16x16x32_bf16 v[90:93], v[200:203], v[218:221], v[90:93]
	s_barrier
	ds_read_b128 v[156:159], v137
	ds_read_b128 v[160:163], v137 offset:1024
	ds_read_b128 v[164:167], v137 offset:2048
	ds_read_b128 v[168:171], v137 offset:3072
	ds_read_b128 v[172:175], v132 offset:32768
	ds_read_b128 v[176:179], v132 offset:33792
	ds_read_b128 v[180:183], v150 offset:32768
	ds_read_b128 v[184:187], v150 offset:33792
	ds_read_b128 v[188:191], v151 offset:32768
	ds_read_b128 v[192:195], v151 offset:33792
	ds_read_b128 v[196:199], v152 offset:32768
	ds_read_b128 v[200:203], v152 offset:33792
	ds_read_b128 v[206:209], v133
	ds_read_b128 v[210:213], v133 offset:1024
	ds_read_b128 v[214:217], v133 offset:2048
	ds_read_b128 v[218:221], v133 offset:3072
	v_lshl_add_u64 v[224:225], s[18:19], 0, v[0:1]
	s_mov_b64 s[22:23], 0x1e6c0100
	v_lshl_add_u64 v[222:223], v[224:225], 0, s[22:23]
	v_readfirstlane_b32 s22, v139
	s_mov_b32 m0, s22
	s_nop 0
	global_load_lds_dwordx4 v[222:223], off
	v_lshl_add_u64 v[224:225], s[18:19], 0, v[0:1]
	s_mov_b64 s[22:23], 0x1e6e0100
	v_lshl_add_u64 v[222:223], v[224:225], 0, s[22:23]
	v_readfirstlane_b32 s22, v140
	s_mov_b32 m0, s22
	s_nop 0
	global_load_lds_dwordx4 v[222:223], off
	s_waitcnt vmcnt(8)
	s_waitcnt lgkmcnt(0)
	s_barrier
	v_mfma_f32_16x16x32_bf16 v[126:129], v[172:175], v[156:159], v[126:129]
	v_mfma_f32_16x16x32_bf16 v[126:129], v[176:179], v[160:163], v[126:129]
	v_mfma_f32_16x16x32_bf16 v[122:125], v[172:175], v[164:167], v[122:125]
	v_mfma_f32_16x16x32_bf16 v[122:125], v[176:179], v[168:171], v[122:125]
	v_mfma_f32_16x16x32_bf16 v[118:121], v[180:183], v[156:159], v[118:121]
	v_mfma_f32_16x16x32_bf16 v[118:121], v[184:187], v[160:163], v[118:121]
	v_mfma_f32_16x16x32_bf16 v[114:117], v[180:183], v[164:167], v[114:117]
	v_mfma_f32_16x16x32_bf16 v[114:117], v[184:187], v[168:171], v[114:117]
	v_mfma_f32_16x16x32_bf16 v[110:113], v[188:191], v[156:159], v[110:113]
	v_mfma_f32_16x16x32_bf16 v[110:113], v[192:195], v[160:163], v[110:113]
	v_mfma_f32_16x16x32_bf16 v[106:109], v[188:191], v[164:167], v[106:109]
	v_mfma_f32_16x16x32_bf16 v[106:109], v[192:195], v[168:171], v[106:109]
	v_mfma_f32_16x16x32_bf16 v[102:105], v[196:199], v[156:159], v[102:105]
	v_mfma_f32_16x16x32_bf16 v[102:105], v[200:203], v[160:163], v[102:105]
	v_mfma_f32_16x16x32_bf16 v[98:101], v[196:199], v[164:167], v[98:101]
	v_mfma_f32_16x16x32_bf16 v[98:101], v[200:203], v[168:171], v[98:101]
	v_mfma_f32_16x16x32_bf16 v[94:97], v[172:175], v[206:209], v[94:97]
	v_mfma_f32_16x16x32_bf16 v[94:97], v[176:179], v[210:213], v[94:97]
	v_mfma_f32_16x16x32_bf16 v[82:85], v[172:175], v[214:217], v[82:85]
	v_mfma_f32_16x16x32_bf16 v[82:85], v[176:179], v[218:221], v[82:85]
	v_mfma_f32_16x16x32_bf16 v[66:69], v[180:183], v[206:209], v[66:69]
	v_mfma_f32_16x16x32_bf16 v[66:69], v[184:187], v[210:213], v[66:69]
	v_mfma_f32_16x16x32_bf16 v[54:57], v[180:183], v[214:217], v[54:57]
	v_mfma_f32_16x16x32_bf16 v[54:57], v[184:187], v[218:221], v[54:57]
	v_mfma_f32_16x16x32_bf16 v[50:53], v[188:191], v[206:209], v[50:53]
	v_mfma_f32_16x16x32_bf16 v[50:53], v[192:195], v[210:213], v[50:53]
	v_mfma_f32_16x16x32_bf16 v[46:49], v[188:191], v[214:217], v[46:49]
	v_mfma_f32_16x16x32_bf16 v[46:49], v[192:195], v[218:221], v[46:49]
	v_mfma_f32_16x16x32_bf16 v[42:45], v[196:199], v[206:209], v[42:45]
	v_mfma_f32_16x16x32_bf16 v[42:45], v[200:203], v[210:213], v[42:45]
	v_mfma_f32_16x16x32_bf16 v[38:41], v[196:199], v[214:217], v[38:41]
	v_mfma_f32_16x16x32_bf16 v[38:41], v[200:203], v[218:221], v[38:41]
	s_barrier
; #define STAGE_A(P, br, kt) do { const char* _g = (const char*)(A + (long)(br) * lda + (long)(kt) * BK); \
;     __builtin_amdgcn_global_load_lds((const unsigned*)(_g + (size_t)offA0), (unsigned*)((char*)(P) + sb0), 16, 0, 0); \
;     __builtin_amdgcn_global_load_lds((const unsigned*)(_g + (size_t)lda * 128 + (size_t)offA0), (unsigned*)((char*)(P) + sb1), 16, 0, 0); } while (0)
; #define STAGE_B(P, br, kt) do { const char* _g = (const char*)(B + (long)(br) * ldb + (long)(kt) * BK); \
;     __builtin_amdgcn_global_load_lds((const unsigned*)(_g + (size_t)offB0), (unsigned*)((char*)(P) + sb0), 16, 0, 0); \
;     __builtin_amdgcn_global_load_lds((const unsigned*)(_g + (size_t)ldb * 128 + (size_t)offB0), (unsigned*)((char*)(P) + sb1), 16, 0, 0); } while (0)
; #define LDA(dst, b, h) for (int m = 0; m < 4; ++m) for (int k = 0; k < 2; ++k) \
;     dst[m][k] = *reinterpret_cast<const bf16x8*>((char*)SA(b, h) + lds_byte(wr * 64 + m * 16 + fr, k * 32 + fq * 8))
; #define LDB(dst, b, h) for (int n = 0; n < 2; ++n) for (int k = 0; k < 2; ++k) \
;     dst[n][k] = *reinterpret_cast<const bf16x8*>((char*)SB(b, h) + lds_byte(wc * 32 + n * 16 + fr, k * 32 + fq * 8))
; #define MMA(ai, bj, At_, Bt_) do { __builtin_amdgcn_s_setprio(1); \
;     for (int m = 0; m < 4; ++m) for (int n = 0; n < 2; ++n) for (int k = 0; k < 2; ++k) \
;       acc[ai][bj][m][n] = MFMA16(At_[m][k], Bt_[n][k], acc[ai][bj][m][n]); \
;     __builtin_amdgcn_s_setprio(0); } while (0)
; #define WAIT_V(n) asm volatile("s_waitcnt vmcnt(" #n ")" ::: "memory")
; #define WAIT_L(n) asm volatile("s_waitcnt lgkmcnt(" #n ")" ::: "memory")
; #define BAR __builtin_amdgcn_s_barrier()
; #define SCHED __builtin_amdgcn_sched_barrier(0)
; DI void gemm_core(WVP char* smem, const u16* __restrict__ A, int lda, int ar0, int ar1,
;                   const u16* __restrict__ B, int ldb, int bc0, int K, AccT& acc) {
;     ...
;     LDA(At, 1, 1); STAGE_A(SA(1, 0), ac0, t + 3);
;     BAR; WAIT_L(0); MMA(1, 0, At, B0); BAR; SCHED;
;     STAGE_B(SB(1, 1), bb1, t + 3);
;     WAIT_V(6); BAR; MMA(1, 1, At, B1); BAR;
;   }
;   { LDB(B0, 0, 0); LDA(At, 0, 0); STAGE_A(SA(1, 1), ac1, nt - 1);
;     BAR; WAIT_L(0); MMA(0, 0, At, B0); BAR;
	ds_read_b128 v[172:175], v132 offset:49152
	ds_read_b128 v[176:179], v132 offset:50176
	ds_read_b128 v[180:183], v150 offset:49152
	ds_read_b128 v[184:187], v150 offset:50176
	ds_read_b128 v[188:191], v151 offset:49152
	ds_read_b128 v[192:195], v151 offset:50176
	ds_read_b128 v[196:199], v152 offset:49152
	ds_read_b128 v[200:203], v152 offset:50176
	v_lshl_add_u64 v[224:225], s[8:9], 0, v[0:1]
	s_mov_b64 s[22:23], 0x19000180
	v_lshl_add_u64 v[222:223], v[224:225], 0, s[22:23]
	v_readfirstlane_b32 s22, v141
	s_mov_b32 m0, s22
	s_nop 0
	global_load_lds_dwordx4 v[222:223], off
	v_lshl_add_u64 v[224:225], s[8:9], 0, v[0:1]
	s_mov_b64 s[22:23], 0x19020180
	v_lshl_add_u64 v[222:223], v[224:225], 0, s[22:23]
	v_readfirstlane_b32 s22, v142
	s_mov_b32 m0, s22
	s_nop 0
	global_load_lds_dwordx4 v[222:223], off
	v_lshl_add_u64 v[224:225], s[18:19], 0, v[0:1]
	s_mov_b64 s[22:23], 0x1e680180
	v_lshl_add_u64 v[222:223], v[224:225], 0, s[22:23]
	v_readfirstlane_b32 s22, v143
	s_mov_b32 m0, s22
	s_nop 0
	global_load_lds_dwordx4 v[222:223], off
	v_lshl_add_u64 v[224:225], s[18:19], 0, v[0:1]
	s_mov_b64 s[22:23], 0x1e6a0180
	v_lshl_add_u64 v[222:223], v[224:225], 0, s[22:23]
	v_readfirstlane_b32 s22, v144
	s_mov_b32 m0, s22
	s_nop 0
	global_load_lds_dwordx4 v[222:223], off
	v_lshl_add_u64 v[224:225], s[8:9], 0, v[0:1]
	s_mov_b64 s[22:23], 0x19040180
	v_lshl_add_u64 v[222:223], v[224:225], 0, s[22:23]
	v_readfirstlane_b32 s22, v145
	s_mov_b32 m0, s22
	s_nop 0
	global_load_lds_dwordx4 v[222:223], off
	v_lshl_add_u64 v[224:225], s[8:9], 0, v[0:1]
	s_mov_b64 s[22:23], 0x19060180
	v_lshl_add_u64 v[222:223], v[224:225], 0, s[22:23]
	v_readfirstlane_b32 s22, v147
	s_mov_b32 m0, s22
	s_nop 0
	global_load_lds_dwordx4 v[222:223], off
	s_waitcnt vmcnt(8)
	s_waitcnt lgkmcnt(0)
	s_barrier
	v_mfma_f32_16x16x32_bf16 v[34:37], v[172:175], v[156:159], v[34:37]
	v_mfma_f32_16x16x32_bf16 v[34:37], v[176:179], v[160:163], v[34:37]
	v_mfma_f32_16x16x32_bf16 v[30:33], v[172:175], v[164:167], v[30:33]
	v_mfma_f32_16x16x32_bf16 v[30:33], v[176:179], v[168:171], v[30:33]
	v_mfma_f32_16x16x32_bf16 v[26:29], v[180:183], v[156:159], v[26:29]
	v_mfma_f32_16x16x32_bf16 v[26:29], v[184:187], v[160:163], v[26:29]
	v_mfma_f32_16x16x32_bf16 v[22:25], v[180:183], v[164:167], v[22:25]
	v_mfma_f32_16x16x32_bf16 v[22:25], v[184:187], v[168:171], v[22:25]
	v_mfma_f32_16x16x32_bf16 v[18:21], v[188:191], v[156:159], v[18:21]
	v_mfma_f32_16x16x32_bf16 v[18:21], v[192:195], v[160:163], v[18:21]
	v_mfma_f32_16x16x32_bf16 v[14:17], v[188:191], v[164:167], v[14:17]
	v_mfma_f32_16x16x32_bf16 v[14:17], v[192:195], v[168:171], v[14:17]
	v_mfma_f32_16x16x32_bf16 v[10:13], v[196:199], v[156:159], v[10:13]
	v_mfma_f32_16x16x32_bf16 v[10:13], v[200:203], v[160:163], v[10:13]
	v_mfma_f32_16x16x32_bf16 v[6:9], v[196:199], v[164:167], v[6:9]
	v_mfma_f32_16x16x32_bf16 v[6:9], v[200:203], v[168:171], v[6:9]
	v_mfma_f32_16x16x32_bf16 v[2:5], v[172:175], v[206:209], v[2:5]
	v_mfma_f32_16x16x32_bf16 v[2:5], v[176:179], v[210:213], v[2:5]
	v_mfma_f32_16x16x32_bf16 v[58:61], v[172:175], v[214:217], v[58:61]
	v_mfma_f32_16x16x32_bf16 v[58:61], v[176:179], v[218:221], v[58:61]
	v_mfma_f32_16x16x32_bf16 v[62:65], v[180:183], v[206:209], v[62:65]
	v_mfma_f32_16x16x32_bf16 v[62:65], v[184:187], v[210:213], v[62:65]
	v_mfma_f32_16x16x32_bf16 v[70:73], v[180:183], v[214:217], v[70:73]
	v_mfma_f32_16x16x32_bf16 v[70:73], v[184:187], v[218:221], v[70:73]
	v_mfma_f32_16x16x32_bf16 v[74:77], v[188:191], v[206:209], v[74:77]
	v_mfma_f32_16x16x32_bf16 v[74:77], v[192:195], v[210:213], v[74:77]
	v_mfma_f32_16x16x32_bf16 v[78:81], v[188:191], v[214:217], v[78:81]
	v_mfma_f32_16x16x32_bf16 v[78:81], v[192:195], v[218:221], v[78:81]
	v_mfma_f32_16x16x32_bf16 v[86:89], v[196:199], v[206:209], v[86:89]
	v_mfma_f32_16x16x32_bf16 v[86:89], v[200:203], v[210:213], v[86:89]
	v_mfma_f32_16x16x32_bf16 v[90:93], v[196:199], v[214:217], v[90:93]
	v_mfma_f32_16x16x32_bf16 v[90:93], v[200:203], v[218:221], v[90:93]
	s_add_i32 s21, s21, 2
	s_add_u32 s8, s8, 0x100
	s_addc_u32 s9, s9, 0
	s_add_u32 s18, s18, 0x100
	s_addc_u32 s19, s19, 0
	s_cmp_lt_u32 s21, 12
	s_barrier
	s_cbranch_scc1 .LBB0_187
	s_mov_b64 s[0:1], 0x780
	v_lshl_add_u64 v[134:135], v[130:131], 0, s[0:1]
	v_readfirstlane_b32 s0, v153
	s_mov_b32 m0, s0
	s_mov_b64 s[0:1], 0x20780
	v_lshl_add_u64 v[130:131], v[130:131], 0, s[0:1]
	v_readfirstlane_b32 s0, v154
	ds_read_b128 v[138:141], v149
	ds_read_b128 v[142:145], v149 offset:1024
	ds_read_b128 v[156:159], v149 offset:2048
	ds_read_b128 v[160:163], v149 offset:3072
	ds_read_b128 v[164:167], v132
	ds_read_b128 v[168:171], v132 offset:1024
	ds_read_b128 v[172:175], v150
	ds_read_b128 v[176:179], v150 offset:1024
	ds_read_b128 v[180:183], v151
	ds_read_b128 v[184:187], v151 offset:1024
	ds_read_b128 v[188:191], v152
	ds_read_b128 v[192:195], v152 offset:1024
	global_load_lds_dwordx4 v[134:135], off
	s_mov_b32 m0, s0
	s_nop 0
	global_load_lds_dwordx4 v[130:131], off
	s_waitcnt vmcnt(8)
	s_barrier
	s_waitcnt lgkmcnt(0)
	s_setprio 1
	s_waitcnt lgkmcnt(0)
	v_mfma_f32_16x16x32_bf16 v[126:129], v[164:167], v[138:141], v[126:129]
	v_mfma_f32_16x16x32_bf16 v[122:125], v[164:167], v[156:159], v[122:125]
	v_mfma_f32_16x16x32_bf16 v[118:121], v[172:175], v[138:141], v[118:121]
	v_mfma_f32_16x16x32_bf16 v[114:117], v[172:175], v[156:159], v[114:117]
	v_mfma_f32_16x16x32_bf16 v[106:109], v[180:183], v[156:159], v[106:109]
	v_mfma_f32_16x16x32_bf16 v[126:129], v[168:171], v[142:145], v[126:129]
	v_mfma_f32_16x16x32_bf16 v[122:125], v[168:171], v[160:163], v[122:125]
	v_mfma_f32_16x16x32_bf16 v[118:121], v[176:179], v[142:145], v[118:121]
	v_mfma_f32_16x16x32_bf16 v[114:117], v[176:179], v[160:163], v[114:117]
	v_mfma_f32_16x16x32_bf16 v[110:113], v[180:183], v[138:141], v[110:113]
	v_mfma_f32_16x16x32_bf16 v[106:109], v[184:187], v[160:163], v[106:109]
	v_mfma_f32_16x16x32_bf16 v[102:105], v[188:191], v[138:141], v[102:105]
	v_mfma_f32_16x16x32_bf16 v[98:101], v[188:191], v[156:159], v[98:101]
	v_mfma_f32_16x16x32_bf16 v[196:199], v[184:187], v[142:145], v[110:113]
	v_mfma_f32_16x16x32_bf16 v[200:203], v[192:195], v[142:145], v[102:105]
	v_mfma_f32_16x16x32_bf16 v[206:209], v[192:195], v[160:163], v[98:101]
	s_setprio 0
	s_barrier
; #define LDA(dst, b, h) for (int m = 0; m < 4; ++m) for (int k = 0; k < 2; ++k) \
;     dst[m][k] = *reinterpret_cast<const bf16x8*>((char*)SA(b, h) + lds_byte(wr * 64 + m * 16 + fr, k * 32 + fq * 8))
; #define LDB(dst, b, h) for (int n = 0; n < 2; ++n) for (int k = 0; k < 2; ++k) \
;     dst[n][k] = *reinterpret_cast<const bf16x8*>((char*)SB(b, h) + lds_byte(wc * 32 + n * 16 + fr, k * 32 + fq * 8))
; #define MMA(ai, bj, At_, Bt_) do { __builtin_amdgcn_s_setprio(1); \
;     for (int m = 0; m < 4; ++m) for (int n = 0; n < 2; ++n) for (int k = 0; k < 2; ++k) \
;       acc[ai][bj][m][n] = MFMA16(At_[m][k], Bt_[n][k], acc[ai][bj][m][n]); \
;     __builtin_amdgcn_s_setprio(0); } while (0)
; #define WAIT_V(n) asm volatile("s_waitcnt vmcnt(" #n ")" ::: "memory")
; #define WAIT_L(n) asm volatile("s_waitcnt lgkmcnt(" #n ")" ::: "memory")
; #define BAR __builtin_amdgcn_s_barrier()
; DI void gemm_core(WVP char* smem, const u16* __restrict__ A, int lda, int ar0, int ar1,
;                   const u16* __restrict__ B, int ldb, int bc0, int K, AccT& acc) {
;     ...
;     LDB(B1, 0, 1); BAR; WAIT_L(0); MMA(0, 1, At, B1); BAR;
;     LDA(At, 0, 1); WAIT_V(4); BAR; WAIT_L(0); MMA(1, 0, At, B0); MMA(1, 1, At, B1); BAR; }
;   { LDB(B0, 1, 0); LDA(At, 1, 0); WAIT_V(2); BAR; WAIT_L(0); MMA(0, 0, At, B0); BAR;
	s_nop 2
	ds_read_b128 v[98:101], v146
	ds_read_b128 v[102:105], v146 offset:1024
	ds_read_b128 v[110:113], v146 offset:2048
	ds_read_b128 v[146:149], v146 offset:3072
	s_barrier
	s_waitcnt lgkmcnt(0)
	s_setprio 1
	s_waitcnt lgkmcnt(0)
	v_mfma_f32_16x16x32_bf16 v[94:97], v[164:167], v[98:101], v[94:97]
	v_mfma_f32_16x16x32_bf16 v[82:85], v[164:167], v[110:113], v[82:85]
	v_mfma_f32_16x16x32_bf16 v[54:57], v[172:175], v[110:113], v[54:57]
	v_mfma_f32_16x16x32_bf16 v[46:49], v[180:183], v[110:113], v[46:49]
	v_mfma_f32_16x16x32_bf16 v[38:41], v[188:191], v[110:113], v[38:41]
	v_mfma_f32_16x16x32_bf16 v[94:97], v[168:171], v[102:105], v[94:97]
	v_mfma_f32_16x16x32_bf16 v[82:85], v[168:171], v[146:149], v[82:85]
	v_mfma_f32_16x16x32_bf16 v[66:69], v[172:175], v[98:101], v[66:69]
	v_mfma_f32_16x16x32_bf16 v[54:57], v[176:179], v[146:149], v[54:57]
	v_mfma_f32_16x16x32_bf16 v[50:53], v[180:183], v[98:101], v[50:53]
	v_mfma_f32_16x16x32_bf16 v[46:49], v[184:187], v[146:149], v[46:49]
	v_mfma_f32_16x16x32_bf16 v[42:45], v[188:191], v[98:101], v[42:45]
	v_mfma_f32_16x16x32_bf16 v[38:41], v[192:195], v[146:149], v[38:41]
	v_mfma_f32_16x16x32_bf16 v[164:167], v[176:179], v[102:105], v[66:69]
	v_mfma_f32_16x16x32_bf16 v[168:171], v[184:187], v[102:105], v[50:53]
	v_mfma_f32_16x16x32_bf16 v[172:175], v[192:195], v[102:105], v[42:45]
	s_setprio 0
	s_barrier
	s_nop 1
	ds_read_b128 v[42:45], v132 offset:16384
	ds_read_b128 v[50:53], v132 offset:17408
	ds_read_b128 v[66:69], v150 offset:16384
	ds_read_b128 v[176:179], v150 offset:17408
	ds_read_b128 v[180:183], v151 offset:16384
	ds_read_b128 v[184:187], v151 offset:17408
	ds_read_b128 v[188:191], v152 offset:16384
	ds_read_b128 v[192:195], v152 offset:17408
	s_waitcnt vmcnt(4)
	s_barrier
	s_waitcnt lgkmcnt(0)
	s_setprio 1
	s_waitcnt lgkmcnt(0)
	v_mfma_f32_16x16x32_bf16 v[30:33], v[42:45], v[156:159], v[30:33]
	v_mfma_f32_16x16x32_bf16 v[26:29], v[66:69], v[138:141], v[26:29]
	v_mfma_f32_16x16x32_bf16 v[14:17], v[180:183], v[156:159], v[14:17]
	v_mfma_f32_16x16x32_bf16 v[6:9], v[188:191], v[156:159], v[6:9]
	v_mfma_f32_16x16x32_bf16 v[34:37], v[42:45], v[138:141], v[34:37]
	v_mfma_f32_16x16x32_bf16 v[30:33], v[50:53], v[160:163], v[30:33]
	v_mfma_f32_16x16x32_bf16 v[26:29], v[176:179], v[142:145], v[26:29]
	v_mfma_f32_16x16x32_bf16 v[22:25], v[66:69], v[156:159], v[22:25]
	v_mfma_f32_16x16x32_bf16 v[18:21], v[180:183], v[138:141], v[18:21]
	v_mfma_f32_16x16x32_bf16 v[14:17], v[184:187], v[160:163], v[14:17]
	v_mfma_f32_16x16x32_bf16 v[10:13], v[188:191], v[138:141], v[10:13]
	v_mfma_f32_16x16x32_bf16 v[6:9], v[192:195], v[160:163], v[6:9]
	v_mfma_f32_16x16x32_bf16 v[210:213], v[50:53], v[142:145], v[34:37]
	v_mfma_f32_16x16x32_bf16 v[214:217], v[176:179], v[160:163], v[22:25]
	v_mfma_f32_16x16x32_bf16 v[218:221], v[184:187], v[142:145], v[18:21]
	v_mfma_f32_16x16x32_bf16 v[138:141], v[192:195], v[142:145], v[10:13]
	s_setprio 0
	s_setprio 1
	v_mfma_f32_16x16x32_bf16 v[2:5], v[42:45], v[98:101], v[2:5]
	v_mfma_f32_16x16x32_bf16 v[142:145], v[50:53], v[102:105], v[2:5]
	v_mfma_f32_16x16x32_bf16 v[2:5], v[42:45], v[110:113], v[58:61]
	v_mfma_f32_16x16x32_bf16 v[154:157], v[50:53], v[146:149], v[2:5]
	v_mfma_f32_16x16x32_bf16 v[2:5], v[66:69], v[98:101], v[62:65]
	v_mfma_f32_16x16x32_bf16 v[158:161], v[176:179], v[102:105], v[2:5]
	v_mfma_f32_16x16x32_bf16 v[2:5], v[66:69], v[110:113], v[70:73]
	v_mfma_f32_16x16x32_bf16 v[176:179], v[176:179], v[146:149], v[2:5]
	v_mfma_f32_16x16x32_bf16 v[2:5], v[180:183], v[98:101], v[74:77]
	v_mfma_f32_16x16x32_bf16 v[222:225], v[184:187], v[102:105], v[2:5]
	v_mfma_f32_16x16x32_bf16 v[2:5], v[180:183], v[110:113], v[78:81]
	v_mfma_f32_16x16x32_bf16 v[180:183], v[184:187], v[146:149], v[2:5]
	v_mfma_f32_16x16x32_bf16 v[2:5], v[188:191], v[98:101], v[86:89]
	v_mfma_f32_16x16x32_bf16 v[184:187], v[192:195], v[102:105], v[2:5]
	v_mfma_f32_16x16x32_bf16 v[2:5], v[188:191], v[110:113], v[90:93]
	v_mfma_f32_16x16x32_bf16 v[146:149], v[192:195], v[146:149], v[2:5]
	s_setprio 0
	s_barrier
	ds_read_b128 v[62:65], v137
	ds_read_b128 v[74:77], v137 offset:1024
	ds_read_b128 v[86:89], v137 offset:2048
	ds_read_b128 v[134:137], v137 offset:3072
	s_nop 0
	ds_read_b128 v[2:5], v132 offset:32768
	ds_read_b128 v[10:13], v132 offset:33792
	ds_read_b128 v[18:21], v150 offset:32768
	ds_read_b128 v[22:25], v150 offset:33792
	ds_read_b128 v[188:191], v151 offset:32768
	ds_read_b128 v[192:195], v151 offset:33792
	ds_read_b128 v[226:229], v152 offset:32768
	ds_read_b128 v[230:233], v152 offset:33792
	s_waitcnt vmcnt(2)
	s_barrier
; #define LDA(dst, b, h) for (int m = 0; m < 4; ++m) for (int k = 0; k < 2; ++k) \
;     dst[m][k] = *reinterpret_cast<const bf16x8*>((char*)SA(b, h) + lds_byte(wr * 64 + m * 16 + fr, k * 32 + fq * 8))
; #define LDB(dst, b, h) for (int n = 0; n < 2; ++n) for (int k = 0; k < 2; ++k) \
;     dst[n][k] = *reinterpret_cast<const bf16x8*>((char*)SB(b, h) + lds_byte(wc * 32 + n * 16 + fr, k * 32 + fq * 8))
; #define MMA(ai, bj, At_, Bt_) do { __builtin_amdgcn_s_setprio(1); \
;     for (int m = 0; m < 4; ++m) for (int n = 0; n < 2; ++n) for (int k = 0; k < 2; ++k) \
;       acc[ai][bj][m][n] = MFMA16(At_[m][k], Bt_[n][k], acc[ai][bj][m][n]); \
;     __builtin_amdgcn_s_setprio(0); } while (0)
; #define WAIT_V(n) asm volatile("s_waitcnt vmcnt(" #n ")" ::: "memory")
; #define WAIT_L(n) asm volatile("s_waitcnt lgkmcnt(" #n ")" ::: "memory")
; #define BAR __builtin_amdgcn_s_barrier()
; DI void gemm_core(WVP char* smem, const u16* __restrict__ A, int lda, int ar0, int ar1,
;                   const u16* __restrict__ B, int ldb, int bc0, int K, AccT& acc) {
;     ...
;   { LDB(B0, 1, 0); LDA(At, 1, 0); WAIT_V(2); BAR; WAIT_L(0); MMA(0, 0, At, B0); BAR;
;     LDB(B1, 1, 1); WAIT_V(0); BAR; WAIT_L(0); MMA(0, 1, At, B1); BAR;
;     LDA(At, 1, 1); BAR; WAIT_L(0); MMA(1, 0, At, B0); MMA(1, 1, At, B1); BAR; }
;   if (wr == 0) BAR;
	s_waitcnt lgkmcnt(0)
	s_setprio 1
	s_waitcnt lgkmcnt(0)
	v_mfma_f32_16x16x32_bf16 v[34:37], v[2:5], v[62:65], v[126:129]
	v_mfma_f32_16x16x32_bf16 v[98:101], v[10:13], v[74:77], v[34:37]
	v_mfma_f32_16x16x32_bf16 v[34:37], v[2:5], v[86:89], v[122:125]
	v_mfma_f32_16x16x32_bf16 v[122:125], v[10:13], v[134:137], v[34:37]
	v_mfma_f32_16x16x32_bf16 v[34:37], v[18:21], v[62:65], v[118:121]
	v_mfma_f32_16x16x32_bf16 v[110:113], v[22:25], v[74:77], v[34:37]
	v_mfma_f32_16x16x32_bf16 v[34:37], v[18:21], v[86:89], v[114:117]
	v_mfma_f32_16x16x32_bf16 v[102:105], v[22:25], v[134:137], v[34:37]
	v_mfma_f32_16x16x32_bf16 v[34:37], v[188:191], v[62:65], v[196:199]
	v_mfma_f32_16x16x32_bf16 v[78:81], v[192:195], v[74:77], v[34:37]
	v_mfma_f32_16x16x32_bf16 v[34:37], v[188:191], v[86:89], v[106:109]
	v_mfma_f32_16x16x32_bf16 v[90:93], v[192:195], v[134:137], v[34:37]
	v_mfma_f32_16x16x32_bf16 v[34:37], v[226:229], v[62:65], v[200:203]
	v_mfma_f32_16x16x32_bf16 v[66:69], v[230:233], v[74:77], v[34:37]
	v_mfma_f32_16x16x32_bf16 v[34:37], v[226:229], v[86:89], v[206:209]
	v_mfma_f32_16x16x32_bf16 v[70:73], v[230:233], v[134:137], v[34:37]
	s_setprio 0
	s_barrier
	ds_read_b128 v[196:199], v133
	ds_read_b128 v[200:203], v133 offset:1024
	ds_read_b128 v[206:209], v133 offset:2048
	ds_read_b128 v[234:237], v133 offset:3072
	s_waitcnt vmcnt(0)
	s_barrier
	s_waitcnt lgkmcnt(0)
	s_setprio 1
	s_waitcnt lgkmcnt(0)
	v_mfma_f32_16x16x32_bf16 v[34:37], v[2:5], v[196:199], v[94:97]
	v_mfma_f32_16x16x32_bf16 v[2:5], v[2:5], v[206:209], v[82:85]
	v_mfma_f32_16x16x32_bf16 v[58:61], v[10:13], v[234:237], v[2:5]
	v_mfma_f32_16x16x32_bf16 v[2:5], v[18:21], v[196:199], v[164:167]
	v_mfma_f32_16x16x32_bf16 v[42:45], v[22:25], v[200:203], v[2:5]
	v_mfma_f32_16x16x32_bf16 v[2:5], v[18:21], v[206:209], v[54:57]
	v_mfma_f32_16x16x32_bf16 v[50:53], v[10:13], v[200:203], v[34:37]
	v_mfma_f32_16x16x32_bf16 v[34:37], v[22:25], v[234:237], v[2:5]
	v_mfma_f32_16x16x32_bf16 v[2:5], v[188:191], v[196:199], v[168:171]
	v_mfma_f32_16x16x32_bf16 v[18:21], v[192:195], v[200:203], v[2:5]
	v_mfma_f32_16x16x32_bf16 v[2:5], v[188:191], v[206:209], v[46:49]
	v_mfma_f32_16x16x32_bf16 v[22:25], v[192:195], v[234:237], v[2:5]
	v_mfma_f32_16x16x32_bf16 v[2:5], v[226:229], v[196:199], v[172:175]
	v_mfma_f32_16x16x32_bf16 v[10:13], v[230:233], v[200:203], v[2:5]
	v_mfma_f32_16x16x32_bf16 v[2:5], v[226:229], v[206:209], v[38:41]
	v_mfma_f32_16x16x32_bf16 v[2:5], v[230:233], v[234:237], v[2:5]
	s_setprio 0
	s_barrier
	ds_read_b128 v[38:41], v132 offset:49152
	ds_read_b128 v[46:49], v132 offset:50176
	ds_read_b128 v[130:133], v150 offset:49152
	ds_read_b128 v[162:165], v150 offset:50176
	ds_read_b128 v[166:169], v151 offset:49152
	ds_read_b128 v[170:173], v151 offset:50176
	ds_read_b128 v[188:191], v152 offset:49152
	ds_read_b128 v[150:153], v152 offset:50176
	s_barrier
	s_waitcnt lgkmcnt(0)
	s_setprio 1
	s_waitcnt lgkmcnt(0)
	v_mfma_f32_16x16x32_bf16 v[26:29], v[130:133], v[62:65], v[26:29]
	v_mfma_f32_16x16x32_bf16 v[114:117], v[162:165], v[74:77], v[26:29]
	v_mfma_f32_16x16x32_bf16 v[26:29], v[130:133], v[86:89], v[214:217]
	v_mfma_f32_16x16x32_bf16 v[14:17], v[166:169], v[86:89], v[14:17]
	v_mfma_f32_16x16x32_bf16 v[54:57], v[38:41], v[62:65], v[210:213]
	v_mfma_f32_16x16x32_bf16 v[30:33], v[38:41], v[86:89], v[30:33]
	v_mfma_f32_16x16x32_bf16 v[118:121], v[162:165], v[134:137], v[26:29]
	v_mfma_f32_16x16x32_bf16 v[26:29], v[166:169], v[62:65], v[218:221]
	v_mfma_f32_16x16x32_bf16 v[94:97], v[170:173], v[134:137], v[14:17]
	v_mfma_f32_16x16x32_bf16 v[14:17], v[188:191], v[62:65], v[138:141]
	v_mfma_f32_16x16x32_bf16 v[6:9], v[188:191], v[86:89], v[6:9]
	v_mfma_f32_16x16x32_bf16 v[106:109], v[46:49], v[74:77], v[54:57]
	v_mfma_f32_16x16x32_bf16 v[126:129], v[46:49], v[134:137], v[30:33]
	v_mfma_f32_16x16x32_bf16 v[82:85], v[170:173], v[74:77], v[26:29]
	v_mfma_f32_16x16x32_bf16 v[74:77], v[150:153], v[74:77], v[14:17]
	v_mfma_f32_16x16x32_bf16 v[86:89], v[150:153], v[134:137], v[6:9]
	s_setprio 0
	s_setprio 1
	v_mfma_f32_16x16x32_bf16 v[6:9], v[38:41], v[196:199], v[142:145]
	v_mfma_f32_16x16x32_bf16 v[54:57], v[46:49], v[200:203], v[6:9]
	v_mfma_f32_16x16x32_bf16 v[6:9], v[38:41], v[206:209], v[154:157]
	v_mfma_f32_16x16x32_bf16 v[62:65], v[46:49], v[234:237], v[6:9]
	v_mfma_f32_16x16x32_bf16 v[6:9], v[130:133], v[196:199], v[158:161]
	v_mfma_f32_16x16x32_bf16 v[46:49], v[162:165], v[200:203], v[6:9]
	v_mfma_f32_16x16x32_bf16 v[6:9], v[130:133], v[206:209], v[176:179]
	v_mfma_f32_16x16x32_bf16 v[38:41], v[162:165], v[234:237], v[6:9]
	v_mfma_f32_16x16x32_bf16 v[6:9], v[166:169], v[196:199], v[222:225]
	v_mfma_f32_16x16x32_bf16 v[26:29], v[170:173], v[200:203], v[6:9]
	v_mfma_f32_16x16x32_bf16 v[6:9], v[166:169], v[206:209], v[180:183]
	v_mfma_f32_16x16x32_bf16 v[30:33], v[170:173], v[234:237], v[6:9]
	v_mfma_f32_16x16x32_bf16 v[6:9], v[188:191], v[196:199], v[184:187]
	v_mfma_f32_16x16x32_bf16 v[14:17], v[150:153], v[200:203], v[6:9]
	v_mfma_f32_16x16x32_bf16 v[6:9], v[188:191], v[206:209], v[146:149]
	v_mfma_f32_16x16x32_bf16 v[6:9], v[150:153], v[234:237], v[6:9]
	s_setprio 0
	s_cmp_gt_u32 s15, 3
	s_barrier
	s_cbranch_scc1 .LBB0_190
	s_barrier

; #define STAGE_A(P, br, kt) do { const char* _g = (const char*)(A + (long)(br) * lda + (long)(kt) * BK); \
;     __builtin_amdgcn_global_load_lds((const unsigned*)(_g + (size_t)offA0), (unsigned*)((char*)(P) + sb0), 16, 0, 0); \
;     __builtin_amdgcn_global_load_lds((const unsigned*)(_g + (size_t)lda * 128 + (size_t)offA0), (unsigned*)((char*)(P) + sb1), 16, 0, 0); } while (0)
; #define STAGE_B(P, br, kt) do { const char* _g = (const char*)(B + (long)(br) * ldb + (long)(kt) * BK); \
;     __builtin_amdgcn_global_load_lds((const unsigned*)(_g + (size_t)offB0), (unsigned*)((char*)(P) + sb0), 16, 0, 0); \
;     __builtin_amdgcn_global_load_lds((const unsigned*)(_g + (size_t)ldb * 128 + (size_t)offB0), (unsigned*)((char*)(P) + sb1), 16, 0, 0); } while (0)
; #define LDA(dst, b, h) for (int m = 0; m < 4; ++m) for (int k = 0; k < 2; ++k) \
;     dst[m][k] = *reinterpret_cast<const bf16x8*>((char*)SA(b, h) + lds_byte(wr * 64 + m * 16 + fr, k * 32 + fq * 8))
; #define LDB(dst, b, h) for (int n = 0; n < 2; ++n) for (int k = 0; k < 2; ++k) \
;     dst[n][k] = *reinterpret_cast<const bf16x8*>((char*)SB(b, h) + lds_byte(wc * 32 + n * 16 + fr, k * 32 + fq * 8))
; #define MMA(ai, bj, At_, Bt_) do { __builtin_amdgcn_s_setprio(1); \
;     for (int m = 0; m < 4; ++m) for (int n = 0; n < 2; ++n) for (int k = 0; k < 2; ++k) \
;       acc[ai][bj][m][n] = MFMA16(At_[m][k], Bt_[n][k], acc[ai][bj][m][n]); \
;     __builtin_amdgcn_s_setprio(0); } while (0)
; #define WAIT_V(n) asm volatile("s_waitcnt vmcnt(" #n ")" ::: "memory")
; #define WAIT_L(n) asm volatile("s_waitcnt lgkmcnt(" #n ")" ::: "memory")
; #define BAR __builtin_amdgcn_s_barrier()
; #define SCHED __builtin_amdgcn_sched_barrier(0)
; DI void gemm_core(WVP char* smem, const u16* __restrict__ A, int lda, int ar0, int ar1,
;                   const u16* __restrict__ B, int ldb, int bc0, int K, AccT& acc) {
;     ...
;   for (int t = 0; t < nt - 2; t += 2) {
;     LDB(B0, 0, 0); SCHED; LDA(At, 0, 0); STAGE_A(SA(1, 1), ac1, t + 1);
;     WAIT_L(8); BAR; WAIT_L(0); MMA(0, 0, At, B0); BAR; SCHED;
;     LDB(B1, 0, 1); STAGE_B(SB(0, 0), bb0, t + 2);
;     BAR; WAIT_L(0); MMA(0, 1, At, B1); BAR;
;     LDA(At, 0, 1); STAGE_A(SA(0, 0), ac0, t + 2);
;     BAR; WAIT_L(0); MMA(1, 0, At, B0); BAR; SCHED;
;     STAGE_B(SB(0, 1), bb1, t + 2);
;     WAIT_V(6); BAR; MMA(1, 1, At, B1); BAR;
.LBB0_227:
	v_add_u32_e32 v150, s0, v148
	v_add_u32_e32 v151, s1, v148
	v_add_u32_e32 v152, s50, v148
	ds_read_b128 v[156:159], v149
	ds_read_b128 v[160:163], v149 offset:1024
	ds_read_b128 v[164:167], v149 offset:2048
	ds_read_b128 v[168:171], v149 offset:3072
	ds_read_b128 v[172:175], v132
	ds_read_b128 v[176:179], v132 offset:1024
	ds_read_b128 v[180:183], v150
	ds_read_b128 v[184:187], v150 offset:1024
	ds_read_b128 v[188:191], v151
	ds_read_b128 v[192:195], v151 offset:1024
	ds_read_b128 v[196:199], v152
	ds_read_b128 v[200:203], v152 offset:1024
	ds_read_b128 v[206:209], v144
	ds_read_b128 v[210:213], v144 offset:1024
	ds_read_b128 v[214:217], v144 offset:2048
	ds_read_b128 v[218:221], v144 offset:3072
	v_add_u32_e32 v153, 0xc000, v136
	v_lshl_add_u64 v[224:225], s[52:53], 0, v[0:1]
	s_mov_b64 s[74:75], 0x3ff80
	v_lshl_add_u64 v[222:223], v[224:225], 0, s[74:75]
	v_readfirstlane_b32 s58, v153
	s_mov_b32 m0, s58
	s_nop 0
	global_load_lds_dwordx4 v[222:223], off
	v_add_u32_e32 v154, 0xe000, v136
	v_lshl_add_u64 v[224:225], s[52:53], 0, v[0:1]
	s_mov_b64 s[74:75], 0x5ff80
	v_lshl_add_u64 v[222:223], v[224:225], 0, s[74:75]
	v_readfirstlane_b32 s58, v154
	s_mov_b32 m0, s58
	s_nop 0
	global_load_lds_dwordx4 v[222:223], off
	s_waitcnt vmcnt(8)
	s_waitcnt lgkmcnt(0)
	s_barrier
	v_mfma_f32_16x16x32_bf16 v[126:129], v[172:175], v[156:159], v[126:129]
	v_mfma_f32_16x16x32_bf16 v[126:129], v[176:179], v[160:163], v[126:129]
	v_mfma_f32_16x16x32_bf16 v[122:125], v[172:175], v[164:167], v[122:125]
	v_mfma_f32_16x16x32_bf16 v[122:125], v[176:179], v[168:171], v[122:125]
	v_mfma_f32_16x16x32_bf16 v[118:121], v[180:183], v[156:159], v[118:121]
	v_mfma_f32_16x16x32_bf16 v[118:121], v[184:187], v[160:163], v[118:121]
	v_mfma_f32_16x16x32_bf16 v[114:117], v[180:183], v[164:167], v[114:117]
	v_mfma_f32_16x16x32_bf16 v[114:117], v[184:187], v[168:171], v[114:117]
	v_mfma_f32_16x16x32_bf16 v[110:113], v[188:191], v[156:159], v[110:113]
	v_mfma_f32_16x16x32_bf16 v[110:113], v[192:195], v[160:163], v[110:113]
	v_mfma_f32_16x16x32_bf16 v[106:109], v[188:191], v[164:167], v[106:109]
	v_mfma_f32_16x16x32_bf16 v[106:109], v[192:195], v[168:171], v[106:109]
	v_mfma_f32_16x16x32_bf16 v[102:105], v[196:199], v[156:159], v[102:105]
	v_mfma_f32_16x16x32_bf16 v[102:105], v[200:203], v[160:163], v[102:105]
	v_mfma_f32_16x16x32_bf16 v[98:101], v[196:199], v[164:167], v[98:101]
	v_mfma_f32_16x16x32_bf16 v[98:101], v[200:203], v[168:171], v[98:101]
	v_mfma_f32_16x16x32_bf16 v[94:97], v[172:175], v[206:209], v[94:97]
	v_mfma_f32_16x16x32_bf16 v[94:97], v[176:179], v[210:213], v[94:97]
	v_mfma_f32_16x16x32_bf16 v[90:93], v[172:175], v[214:217], v[90:93]
	v_mfma_f32_16x16x32_bf16 v[90:93], v[176:179], v[218:221], v[90:93]
	v_mfma_f32_16x16x32_bf16 v[86:89], v[180:183], v[206:209], v[86:89]
	v_mfma_f32_16x16x32_bf16 v[86:89], v[184:187], v[210:213], v[86:89]
	v_mfma_f32_16x16x32_bf16 v[82:85], v[180:183], v[214:217], v[82:85]
	v_mfma_f32_16x16x32_bf16 v[82:85], v[184:187], v[218:221], v[82:85]
	v_mfma_f32_16x16x32_bf16 v[78:81], v[188:191], v[206:209], v[78:81]
	v_mfma_f32_16x16x32_bf16 v[78:81], v[192:195], v[210:213], v[78:81]
	v_mfma_f32_16x16x32_bf16 v[74:77], v[188:191], v[214:217], v[74:77]
	v_mfma_f32_16x16x32_bf16 v[74:77], v[192:195], v[218:221], v[74:77]
	v_mfma_f32_16x16x32_bf16 v[70:73], v[196:199], v[206:209], v[70:73]
	v_mfma_f32_16x16x32_bf16 v[70:73], v[200:203], v[210:213], v[70:73]
	v_mfma_f32_16x16x32_bf16 v[66:69], v[196:199], v[214:217], v[66:69]
	v_mfma_f32_16x16x32_bf16 v[66:69], v[200:203], v[218:221], v[66:69]
	s_barrier
	ds_read_b128 v[172:175], v132 offset:16384
	ds_read_b128 v[176:179], v132 offset:17408
	ds_read_b128 v[180:183], v150 offset:16384
	ds_read_b128 v[184:187], v150 offset:17408
	ds_read_b128 v[188:191], v151 offset:16384
	ds_read_b128 v[192:195], v151 offset:17408
	ds_read_b128 v[196:199], v152 offset:16384
	ds_read_b128 v[200:203], v152 offset:17408
	v_lshl_add_u64 v[224:225], vcc, 0, v[0:1]
	v_lshl_add_u64 v[222:223], v[224:225], 0, s[80:81]
	v_readfirstlane_b32 s58, v134
	s_mov_b32 m0, s58
	s_nop 0
	global_load_lds_dwordx4 v[222:223], off
	v_add_u32_e32 v155, 0x2000, v134
	v_lshl_add_u64 v[224:225], vcc, 0, v[0:1]
	v_lshl_add_u64 v[222:223], v[224:225], 0, s[82:83]
	v_readfirstlane_b32 s58, v155
	s_mov_b32 m0, s58
	s_nop 0
	global_load_lds_dwordx4 v[222:223], off
	v_lshl_add_u64 v[222:223], s[52:53], 0, v[0:1]
	v_readfirstlane_b32 s58, v136
	s_mov_b32 m0, s58
	s_nop 0
	global_load_lds_dwordx4 v[222:223], off
	v_lshl_add_u64 v[224:225], s[52:53], 0, v[0:1]
	v_lshl_add_u64 v[222:223], v[224:225], 0, s[76:77]
	v_readfirstlane_b32 s58, v137
	s_mov_b32 m0, s58
	s_nop 0
	global_load_lds_dwordx4 v[222:223], off
	v_lshl_add_u64 v[224:225], vcc, 0, v[0:1]
	v_lshl_add_u64 v[222:223], v[224:225], 0, s[88:89]
	v_readfirstlane_b32 s58, v138
	s_mov_b32 m0, s58
	s_nop 0
	global_load_lds_dwordx4 v[222:223], off
	v_add_u32_e32 v155, 0x2000, v138
	v_lshl_add_u64 v[224:225], vcc, 0, v[0:1]
	v_lshl_add_u64 v[222:223], v[224:225], 0, s[90:91]
	v_readfirstlane_b32 s58, v155
	s_mov_b32 m0, s58
	s_nop 0
	global_load_lds_dwordx4 v[222:223], off
	s_waitcnt vmcnt(8)
	s_waitcnt lgkmcnt(0)
	s_barrier
; #define STAGE_A(P, br, kt) do { const char* _g = (const char*)(A + (long)(br) * lda + (long)(kt) * BK); \
;     __builtin_amdgcn_global_load_lds((const unsigned*)(_g + (size_t)offA0), (unsigned*)((char*)(P) + sb0), 16, 0, 0); \
;     __builtin_amdgcn_global_load_lds((const unsigned*)(_g + (size_t)lda * 128 + (size_t)offA0), (unsigned*)((char*)(P) + sb1), 16, 0, 0); } while (0)
; #define STAGE_B(P, br, kt) do { const char* _g = (const char*)(B + (long)(br) * ldb + (long)(kt) * BK); \
;     __builtin_amdgcn_global_load_lds((const unsigned*)(_g + (size_t)offB0), (unsigned*)((char*)(P) + sb0), 16, 0, 0); \
;     __builtin_amdgcn_global_load_lds((const unsigned*)(_g + (size_t)ldb * 128 + (size_t)offB0), (unsigned*)((char*)(P) + sb1), 16, 0, 0); } while (0)
; #define LDA(dst, b, h) for (int m = 0; m < 4; ++m) for (int k = 0; k < 2; ++k) \
;     dst[m][k] = *reinterpret_cast<const bf16x8*>((char*)SA(b, h) + lds_byte(wr * 64 + m * 16 + fr, k * 32 + fq * 8))
; #define LDB(dst, b, h) for (int n = 0; n < 2; ++n) for (int k = 0; k < 2; ++k) \
;     dst[n][k] = *reinterpret_cast<const bf16x8*>((char*)SB(b, h) + lds_byte(wc * 32 + n * 16 + fr, k * 32 + fq * 8))
; #define MMA(ai, bj, At_, Bt_) do { __builtin_amdgcn_s_setprio(1); \
;     for (int m = 0; m < 4; ++m) for (int n = 0; n < 2; ++n) for (int k = 0; k < 2; ++k) \
;       acc[ai][bj][m][n] = MFMA16(At_[m][k], Bt_[n][k], acc[ai][bj][m][n]); \
;     __builtin_amdgcn_s_setprio(0); } while (0)
; #define WAIT_V(n) asm volatile("s_waitcnt vmcnt(" #n ")" ::: "memory")
; #define WAIT_L(n) asm volatile("s_waitcnt lgkmcnt(" #n ")" ::: "memory")
; #define BAR __builtin_amdgcn_s_barrier()
; #define SCHED __builtin_amdgcn_sched_barrier(0)
; DI void gemm_core(WVP char* smem, const u16* __restrict__ A, int lda, int ar0, int ar1,
;                   const u16* __restrict__ B, int ldb, int bc0, int K, AccT& acc) {
;     ...
;     BAR; WAIT_L(0); MMA(1, 0, At, B0); BAR; SCHED;
;     STAGE_B(SB(0, 1), bb1, t + 2);
;     WAIT_V(6); BAR; MMA(1, 1, At, B1); BAR;
;     LDB(B0, 1, 0); SCHED; LDA(At, 1, 0); STAGE_A(SA(0, 1), ac1, t + 2);
;     WAIT_L(8); BAR; WAIT_L(0); MMA(0, 0, At, B0); BAR; SCHED;
;     LDB(B1, 1, 1); STAGE_B(SB(1, 0), bb0, t + 3);
;     BAR; WAIT_L(0); MMA(0, 1, At, B1); BAR;
	v_mfma_f32_16x16x32_bf16 v[62:65], v[172:175], v[156:159], v[62:65]
	v_mfma_f32_16x16x32_bf16 v[62:65], v[176:179], v[160:163], v[62:65]
	v_mfma_f32_16x16x32_bf16 v[58:61], v[172:175], v[164:167], v[58:61]
	v_mfma_f32_16x16x32_bf16 v[58:61], v[176:179], v[168:171], v[58:61]
	v_mfma_f32_16x16x32_bf16 v[54:57], v[180:183], v[156:159], v[54:57]
	v_mfma_f32_16x16x32_bf16 v[54:57], v[184:187], v[160:163], v[54:57]
	v_mfma_f32_16x16x32_bf16 v[50:53], v[180:183], v[164:167], v[50:53]
	v_mfma_f32_16x16x32_bf16 v[50:53], v[184:187], v[168:171], v[50:53]
	v_mfma_f32_16x16x32_bf16 v[46:49], v[188:191], v[156:159], v[46:49]
	v_mfma_f32_16x16x32_bf16 v[46:49], v[192:195], v[160:163], v[46:49]
	v_mfma_f32_16x16x32_bf16 v[42:45], v[188:191], v[164:167], v[42:45]
	v_mfma_f32_16x16x32_bf16 v[42:45], v[192:195], v[168:171], v[42:45]
	v_mfma_f32_16x16x32_bf16 v[38:41], v[196:199], v[156:159], v[38:41]
	v_mfma_f32_16x16x32_bf16 v[38:41], v[200:203], v[160:163], v[38:41]
	v_mfma_f32_16x16x32_bf16 v[34:37], v[196:199], v[164:167], v[34:37]
	v_mfma_f32_16x16x32_bf16 v[34:37], v[200:203], v[168:171], v[34:37]
	v_mfma_f32_16x16x32_bf16 v[30:33], v[172:175], v[206:209], v[30:33]
	v_mfma_f32_16x16x32_bf16 v[30:33], v[176:179], v[210:213], v[30:33]
	v_mfma_f32_16x16x32_bf16 v[26:29], v[172:175], v[214:217], v[26:29]
	v_mfma_f32_16x16x32_bf16 v[26:29], v[176:179], v[218:221], v[26:29]
	v_mfma_f32_16x16x32_bf16 v[22:25], v[180:183], v[206:209], v[22:25]
	v_mfma_f32_16x16x32_bf16 v[22:25], v[184:187], v[210:213], v[22:25]
	v_mfma_f32_16x16x32_bf16 v[18:21], v[180:183], v[214:217], v[18:21]
	v_mfma_f32_16x16x32_bf16 v[18:21], v[184:187], v[218:221], v[18:21]
	v_mfma_f32_16x16x32_bf16 v[14:17], v[188:191], v[206:209], v[14:17]
	v_mfma_f32_16x16x32_bf16 v[14:17], v[192:195], v[210:213], v[14:17]
	v_mfma_f32_16x16x32_bf16 v[10:13], v[188:191], v[214:217], v[10:13]
	v_mfma_f32_16x16x32_bf16 v[10:13], v[192:195], v[218:221], v[10:13]
	v_mfma_f32_16x16x32_bf16 v[6:9], v[196:199], v[206:209], v[6:9]
	v_mfma_f32_16x16x32_bf16 v[6:9], v[200:203], v[210:213], v[6:9]
	v_mfma_f32_16x16x32_bf16 v[2:5], v[196:199], v[214:217], v[2:5]
	v_mfma_f32_16x16x32_bf16 v[2:5], v[200:203], v[218:221], v[2:5]
	s_barrier
	ds_read_b128 v[156:159], v135
	ds_read_b128 v[160:163], v135 offset:1024
	ds_read_b128 v[164:167], v135 offset:2048
	ds_read_b128 v[168:171], v135 offset:3072
	ds_read_b128 v[172:175], v132 offset:32768
	ds_read_b128 v[176:179], v132 offset:33792
	ds_read_b128 v[180:183], v150 offset:32768
	ds_read_b128 v[184:187], v150 offset:33792
	ds_read_b128 v[188:191], v151 offset:32768
	ds_read_b128 v[192:195], v151 offset:33792
	ds_read_b128 v[196:199], v152 offset:32768
	ds_read_b128 v[200:203], v152 offset:33792
	ds_read_b128 v[206:209], v133
	ds_read_b128 v[210:213], v133 offset:1024
	ds_read_b128 v[214:217], v133 offset:2048
	ds_read_b128 v[218:221], v133 offset:3072
	v_lshl_add_u64 v[224:225], s[52:53], 0, v[0:1]
	s_mov_b64 s[74:75], 0x40000
	v_lshl_add_u64 v[222:223], v[224:225], 0, s[74:75]
	v_readfirstlane_b32 s58, v139
	s_mov_b32 m0, s58
	s_nop 0
	global_load_lds_dwordx4 v[222:223], off
	v_lshl_add_u64 v[224:225], s[52:53], 0, v[0:1]
	s_mov_b64 s[74:75], 0x60000
	v_lshl_add_u64 v[222:223], v[224:225], 0, s[74:75]
	v_readfirstlane_b32 s58, v140
	s_mov_b32 m0, s58
	s_nop 0
	global_load_lds_dwordx4 v[222:223], off
	s_waitcnt vmcnt(8)
	s_waitcnt lgkmcnt(0)
	s_barrier
	v_mfma_f32_16x16x32_bf16 v[126:129], v[172:175], v[156:159], v[126:129]
	v_mfma_f32_16x16x32_bf16 v[126:129], v[176:179], v[160:163], v[126:129]
	v_mfma_f32_16x16x32_bf16 v[122:125], v[172:175], v[164:167], v[122:125]
	v_mfma_f32_16x16x32_bf16 v[122:125], v[176:179], v[168:171], v[122:125]
	v_mfma_f32_16x16x32_bf16 v[118:121], v[180:183], v[156:159], v[118:121]
	v_mfma_f32_16x16x32_bf16 v[118:121], v[184:187], v[160:163], v[118:121]
	v_mfma_f32_16x16x32_bf16 v[114:117], v[180:183], v[164:167], v[114:117]
	v_mfma_f32_16x16x32_bf16 v[114:117], v[184:187], v[168:171], v[114:117]
	v_mfma_f32_16x16x32_bf16 v[110:113], v[188:191], v[156:159], v[110:113]
	v_mfma_f32_16x16x32_bf16 v[110:113], v[192:195], v[160:163], v[110:113]
	v_mfma_f32_16x16x32_bf16 v[106:109], v[188:191], v[164:167], v[106:109]
	v_mfma_f32_16x16x32_bf16 v[106:109], v[192:195], v[168:171], v[106:109]
	v_mfma_f32_16x16x32_bf16 v[102:105], v[196:199], v[156:159], v[102:105]
	v_mfma_f32_16x16x32_bf16 v[102:105], v[200:203], v[160:163], v[102:105]
	v_mfma_f32_16x16x32_bf16 v[98:101], v[196:199], v[164:167], v[98:101]
	v_mfma_f32_16x16x32_bf16 v[98:101], v[200:203], v[168:171], v[98:101]
	v_mfma_f32_16x16x32_bf16 v[94:97], v[172:175], v[206:209], v[94:97]
	v_mfma_f32_16x16x32_bf16 v[94:97], v[176:179], v[210:213], v[94:97]
	v_mfma_f32_16x16x32_bf16 v[90:93], v[172:175], v[214:217], v[90:93]
	v_mfma_f32_16x16x32_bf16 v[90:93], v[176:179], v[218:221], v[90:93]
	v_mfma_f32_16x16x32_bf16 v[86:89], v[180:183], v[206:209], v[86:89]
	v_mfma_f32_16x16x32_bf16 v[86:89], v[184:187], v[210:213], v[86:89]
	v_mfma_f32_16x16x32_bf16 v[82:85], v[180:183], v[214:217], v[82:85]
	v_mfma_f32_16x16x32_bf16 v[82:85], v[184:187], v[218:221], v[82:85]
	v_mfma_f32_16x16x32_bf16 v[78:81], v[188:191], v[206:209], v[78:81]
	v_mfma_f32_16x16x32_bf16 v[78:81], v[192:195], v[210:213], v[78:81]
	v_mfma_f32_16x16x32_bf16 v[74:77], v[188:191], v[214:217], v[74:77]
	v_mfma_f32_16x16x32_bf16 v[74:77], v[192:195], v[218:221], v[74:77]
	v_mfma_f32_16x16x32_bf16 v[70:73], v[196:199], v[206:209], v[70:73]
	v_mfma_f32_16x16x32_bf16 v[70:73], v[200:203], v[210:213], v[70:73]
	v_mfma_f32_16x16x32_bf16 v[66:69], v[196:199], v[214:217], v[66:69]
	v_mfma_f32_16x16x32_bf16 v[66:69], v[200:203], v[218:221], v[66:69]
	s_barrier
; #define STAGE_A(P, br, kt) do { const char* _g = (const char*)(A + (long)(br) * lda + (long)(kt) * BK); \
;     __builtin_amdgcn_global_load_lds((const unsigned*)(_g + (size_t)offA0), (unsigned*)((char*)(P) + sb0), 16, 0, 0); \
;     __builtin_amdgcn_global_load_lds((const unsigned*)(_g + (size_t)lda * 128 + (size_t)offA0), (unsigned*)((char*)(P) + sb1), 16, 0, 0); } while (0)
; #define STAGE_B(P, br, kt) do { const char* _g = (const char*)(B + (long)(br) * ldb + (long)(kt) * BK); \
;     __builtin_amdgcn_global_load_lds((const unsigned*)(_g + (size_t)offB0), (unsigned*)((char*)(P) + sb0), 16, 0, 0); \
;     __builtin_amdgcn_global_load_lds((const unsigned*)(_g + (size_t)ldb * 128 + (size_t)offB0), (unsigned*)((char*)(P) + sb1), 16, 0, 0); } while (0)
; #define LDA(dst, b, h) for (int m = 0; m < 4; ++m) for (int k = 0; k < 2; ++k) \
;     dst[m][k] = *reinterpret_cast<const bf16x8*>((char*)SA(b, h) + lds_byte(wr * 64 + m * 16 + fr, k * 32 + fq * 8))
; #define LDB(dst, b, h) for (int n = 0; n < 2; ++n) for (int k = 0; k < 2; ++k) \
;     dst[n][k] = *reinterpret_cast<const bf16x8*>((char*)SB(b, h) + lds_byte(wc * 32 + n * 16 + fr, k * 32 + fq * 8))
; #define MMA(ai, bj, At_, Bt_) do { __builtin_amdgcn_s_setprio(1); \
;     for (int m = 0; m < 4; ++m) for (int n = 0; n < 2; ++n) for (int k = 0; k < 2; ++k) \
;       acc[ai][bj][m][n] = MFMA16(At_[m][k], Bt_[n][k], acc[ai][bj][m][n]); \
;     __builtin_amdgcn_s_setprio(0); } while (0)
; #define WAIT_V(n) asm volatile("s_waitcnt vmcnt(" #n ")" ::: "memory")
; #define WAIT_L(n) asm volatile("s_waitcnt lgkmcnt(" #n ")" ::: "memory")
; #define BAR __builtin_amdgcn_s_barrier()
; #define SCHED __builtin_amdgcn_sched_barrier(0)
; DI void gemm_core(WVP char* smem, const u16* __restrict__ A, int lda, int ar0, int ar1,
;                   const u16* __restrict__ B, int ldb, int bc0, int K, AccT& acc) {
;     ...
;     BAR; WAIT_L(0); MMA(0, 1, At, B1); BAR;
;     LDA(At, 1, 1); STAGE_A(SA(1, 0), ac0, t + 3);
;     BAR; WAIT_L(0); MMA(1, 0, At, B0); BAR; SCHED;
;     STAGE_B(SB(1, 1), bb1, t + 3);
;     WAIT_V(6); BAR; MMA(1, 1, At, B1); BAR;
;   }
;   { LDB(B0, 0, 0); LDA(At, 0, 0); STAGE_A(SA(1, 1), ac1, nt - 1);
;     BAR; WAIT_L(0); MMA(0, 0, At, B0); BAR;
;     LDB(B1, 0, 1); BAR; WAIT_L(0); MMA(0, 1, At, B1); BAR;
;     LDA(At, 0, 1); WAIT_V(4); BAR; WAIT_L(0); MMA(1, 0, At, B0); MMA(1, 1, At, B1); BAR; }
	ds_read_b128 v[172:175], v132 offset:49152
	ds_read_b128 v[176:179], v132 offset:50176
	ds_read_b128 v[180:183], v150 offset:49152
	ds_read_b128 v[184:187], v150 offset:50176
	ds_read_b128 v[188:191], v151 offset:49152
	ds_read_b128 v[192:195], v151 offset:50176
	ds_read_b128 v[196:199], v152 offset:49152
	ds_read_b128 v[200:203], v152 offset:50176
	v_lshl_add_u64 v[224:225], vcc, 0, v[0:1]
	v_lshl_add_u64 v[222:223], v[224:225], 0, s[92:93]
	v_readfirstlane_b32 s58, v141
	s_mov_b32 m0, s58
	s_nop 0
	global_load_lds_dwordx4 v[222:223], off
	v_lshl_add_u64 v[224:225], vcc, 0, v[0:1]
	v_lshl_add_u64 v[222:223], v[224:225], 0, s[94:95]
	v_readfirstlane_b32 s58, v142
	s_mov_b32 m0, s58
	s_nop 0
	global_load_lds_dwordx4 v[222:223], off
	v_lshl_add_u64 v[224:225], s[52:53], 0, v[0:1]
	v_lshl_add_u64 v[222:223], v[224:225], 0, s[64:65]
	v_readfirstlane_b32 s58, v143
	s_mov_b32 m0, s58
	s_nop 0
	global_load_lds_dwordx4 v[222:223], off
	v_lshl_add_u64 v[224:225], s[52:53], 0, v[0:1]
	v_lshl_add_u64 v[222:223], v[224:225], 0, s[78:79]
	v_readfirstlane_b32 s58, v145
	s_mov_b32 m0, s58
	s_nop 0
	global_load_lds_dwordx4 v[222:223], off
	v_lshl_add_u64 v[224:225], vcc, 0, v[0:1]
	v_lshl_add_u64 v[222:223], v[224:225], 0, s[96:97]
	v_readfirstlane_b32 s58, v146
	s_mov_b32 m0, s58
	s_nop 0
	global_load_lds_dwordx4 v[222:223], off
	v_lshl_add_u64 v[224:225], vcc, 0, v[0:1]
	v_lshl_add_u64 v[222:223], v[224:225], 0, s[72:73]
	v_readfirstlane_b32 s58, v147
	s_mov_b32 m0, s58
	s_nop 0
	global_load_lds_dwordx4 v[222:223], off
	s_waitcnt vmcnt(8)
	s_waitcnt lgkmcnt(0)
	s_barrier
	v_mfma_f32_16x16x32_bf16 v[62:65], v[172:175], v[156:159], v[62:65]
	v_mfma_f32_16x16x32_bf16 v[62:65], v[176:179], v[160:163], v[62:65]
	v_mfma_f32_16x16x32_bf16 v[58:61], v[172:175], v[164:167], v[58:61]
	v_mfma_f32_16x16x32_bf16 v[58:61], v[176:179], v[168:171], v[58:61]
	v_mfma_f32_16x16x32_bf16 v[54:57], v[180:183], v[156:159], v[54:57]
	v_mfma_f32_16x16x32_bf16 v[54:57], v[184:187], v[160:163], v[54:57]
	v_mfma_f32_16x16x32_bf16 v[50:53], v[180:183], v[164:167], v[50:53]
	v_mfma_f32_16x16x32_bf16 v[50:53], v[184:187], v[168:171], v[50:53]
	v_mfma_f32_16x16x32_bf16 v[46:49], v[188:191], v[156:159], v[46:49]
	v_mfma_f32_16x16x32_bf16 v[46:49], v[192:195], v[160:163], v[46:49]
	v_mfma_f32_16x16x32_bf16 v[42:45], v[188:191], v[164:167], v[42:45]
	v_mfma_f32_16x16x32_bf16 v[42:45], v[192:195], v[168:171], v[42:45]
	v_mfma_f32_16x16x32_bf16 v[38:41], v[196:199], v[156:159], v[38:41]
	v_mfma_f32_16x16x32_bf16 v[38:41], v[200:203], v[160:163], v[38:41]
	v_mfma_f32_16x16x32_bf16 v[34:37], v[196:199], v[164:167], v[34:37]
	v_mfma_f32_16x16x32_bf16 v[34:37], v[200:203], v[168:171], v[34:37]
	v_mfma_f32_16x16x32_bf16 v[30:33], v[172:175], v[206:209], v[30:33]
	v_mfma_f32_16x16x32_bf16 v[30:33], v[176:179], v[210:213], v[30:33]
	v_mfma_f32_16x16x32_bf16 v[26:29], v[172:175], v[214:217], v[26:29]
	v_mfma_f32_16x16x32_bf16 v[26:29], v[176:179], v[218:221], v[26:29]
	v_mfma_f32_16x16x32_bf16 v[22:25], v[180:183], v[206:209], v[22:25]
	v_mfma_f32_16x16x32_bf16 v[22:25], v[184:187], v[210:213], v[22:25]
	v_mfma_f32_16x16x32_bf16 v[18:21], v[180:183], v[214:217], v[18:21]
	v_mfma_f32_16x16x32_bf16 v[18:21], v[184:187], v[218:221], v[18:21]
	v_mfma_f32_16x16x32_bf16 v[14:17], v[188:191], v[206:209], v[14:17]
	v_mfma_f32_16x16x32_bf16 v[14:17], v[192:195], v[210:213], v[14:17]
	v_mfma_f32_16x16x32_bf16 v[10:13], v[188:191], v[214:217], v[10:13]
	v_mfma_f32_16x16x32_bf16 v[10:13], v[192:195], v[218:221], v[10:13]
	v_mfma_f32_16x16x32_bf16 v[6:9], v[196:199], v[206:209], v[6:9]
	v_mfma_f32_16x16x32_bf16 v[6:9], v[200:203], v[210:213], v[6:9]
	v_mfma_f32_16x16x32_bf16 v[2:5], v[196:199], v[214:217], v[2:5]
	v_mfma_f32_16x16x32_bf16 v[2:5], v[200:203], v[218:221], v[2:5]
	s_add_i32 s57, s57, 2
	s_add_u32 vcc_lo, vcc_lo, 0x100
	s_addc_u32 vcc_hi, vcc_hi, 0
	s_add_u32 s52, s52, 0x100
	s_addc_u32 s53, s53, 0
	s_cmp_lt_u32 s57, 12
	s_barrier
	s_cbranch_scc1 .LBB0_227
	s_mov_b64 s[0:1], 0x780
	v_lshl_add_u64 v[192:193], v[130:131], 0, s[0:1]
	v_readfirstlane_b32 s0, v153
	s_mov_b32 m0, s0
	s_mov_b64 s[0:1], 0x20780
	v_lshl_add_u64 v[130:131], v[130:131], 0, s[0:1]
	v_readfirstlane_b32 s0, v154
	ds_read_b128 v[136:139], v149
	ds_read_b128 v[140:143], v149 offset:1024
	ds_read_b128 v[156:159], v149 offset:2048
	ds_read_b128 v[146:149], v149 offset:3072
	ds_read_b128 v[160:163], v132
	ds_read_b128 v[164:167], v132 offset:1024
	ds_read_b128 v[168:171], v150
	ds_read_b128 v[172:175], v150 offset:1024
	ds_read_b128 v[176:179], v151
	ds_read_b128 v[180:183], v151 offset:1024
	ds_read_b128 v[184:187], v152
	ds_read_b128 v[188:191], v152 offset:1024
	global_load_lds_dwordx4 v[192:193], off
	s_mov_b32 m0, s0
	s_nop 0
	global_load_lds_dwordx4 v[130:131], off
	s_waitcnt vmcnt(8)
	s_barrier
	s_waitcnt lgkmcnt(0)
	s_setprio 1
	s_waitcnt lgkmcnt(0)
	v_mfma_f32_16x16x32_bf16 v[126:129], v[160:163], v[136:139], v[126:129]
	v_mfma_f32_16x16x32_bf16 v[118:121], v[168:171], v[136:139], v[118:121]
	v_mfma_f32_16x16x32_bf16 v[110:113], v[176:179], v[136:139], v[110:113]
	v_mfma_f32_16x16x32_bf16 v[102:105], v[184:187], v[136:139], v[102:105]
	v_mfma_f32_16x16x32_bf16 v[126:129], v[164:167], v[140:143], v[126:129]
	v_mfma_f32_16x16x32_bf16 v[122:125], v[160:163], v[156:159], v[122:125]
	v_mfma_f32_16x16x32_bf16 v[118:121], v[172:175], v[140:143], v[118:121]
	v_mfma_f32_16x16x32_bf16 v[114:117], v[168:171], v[156:159], v[114:117]
	v_mfma_f32_16x16x32_bf16 v[110:113], v[180:183], v[140:143], v[110:113]
	v_mfma_f32_16x16x32_bf16 v[106:109], v[176:179], v[156:159], v[106:109]
	v_mfma_f32_16x16x32_bf16 v[102:105], v[188:191], v[140:143], v[102:105]
	v_mfma_f32_16x16x32_bf16 v[98:101], v[184:187], v[156:159], v[98:101]
	v_mfma_f32_16x16x32_bf16 v[192:195], v[164:167], v[146:149], v[122:125]
	v_mfma_f32_16x16x32_bf16 v[196:199], v[172:175], v[146:149], v[114:117]
	v_mfma_f32_16x16x32_bf16 v[200:203], v[180:183], v[146:149], v[106:109]
	v_mfma_f32_16x16x32_bf16 v[206:209], v[188:191], v[146:149], v[98:101]
	s_setprio 0
	s_barrier
; #define STAGE_A(P, br, kt) do { const char* _g = (const char*)(A + (long)(br) * lda + (long)(kt) * BK); \
;     __builtin_amdgcn_global_load_lds((const unsigned*)(_g + (size_t)offA0), (unsigned*)((char*)(P) + sb0), 16, 0, 0); \
;     __builtin_amdgcn_global_load_lds((const unsigned*)(_g + (size_t)lda * 128 + (size_t)offA0), (unsigned*)((char*)(P) + sb1), 16, 0, 0); } while (0)
; #define LDA(dst, b, h) for (int m = 0; m < 4; ++m) for (int k = 0; k < 2; ++k) \
;     dst[m][k] = *reinterpret_cast<const bf16x8*>((char*)SA(b, h) + lds_byte(wr * 64 + m * 16 + fr, k * 32 + fq * 8))
; #define LDB(dst, b, h) for (int n = 0; n < 2; ++n) for (int k = 0; k < 2; ++k) \
;     dst[n][k] = *reinterpret_cast<const bf16x8*>((char*)SB(b, h) + lds_byte(wc * 32 + n * 16 + fr, k * 32 + fq * 8))
; #define MMA(ai, bj, At_, Bt_) do { __builtin_amdgcn_s_setprio(1); \
;     for (int m = 0; m < 4; ++m) for (int n = 0; n < 2; ++n) for (int k = 0; k < 2; ++k) \
;       acc[ai][bj][m][n] = MFMA16(At_[m][k], Bt_[n][k], acc[ai][bj][m][n]); \
;     __builtin_amdgcn_s_setprio(0); } while (0)
; #define WAIT_V(n) asm volatile("s_waitcnt vmcnt(" #n ")" ::: "memory")
; #define WAIT_L(n) asm volatile("s_waitcnt lgkmcnt(" #n ")" ::: "memory")
; #define BAR __builtin_amdgcn_s_barrier()
; DI void gemm_core(WVP char* smem, const u16* __restrict__ A, int lda, int ar0, int ar1,
;                   const u16* __restrict__ B, int ldb, int bc0, int K, AccT& acc) {
;     ...
;   { LDB(B0, 0, 0); LDA(At, 0, 0); STAGE_A(SA(1, 1), ac1, nt - 1);
;     BAR; WAIT_L(0); MMA(0, 0, At, B0); BAR;
;     LDB(B1, 0, 1); BAR; WAIT_L(0); MMA(0, 1, At, B1); BAR;
;     LDA(At, 0, 1); WAIT_V(4); BAR; WAIT_L(0); MMA(1, 0, At, B0); MMA(1, 1, At, B1); BAR; }
;   { LDB(B0, 1, 0); LDA(At, 1, 0); WAIT_V(2); BAR; WAIT_L(0); MMA(0, 0, At, B0); BAR;
	s_nop 1
	ds_read_b128 v[98:101], v144
	ds_read_b128 v[106:109], v144 offset:1024
	ds_read_b128 v[114:117], v144 offset:2048
	ds_read_b128 v[122:125], v144 offset:3072
	s_barrier
	s_waitcnt lgkmcnt(0)
	s_setprio 1
	s_waitcnt lgkmcnt(0)
	v_mfma_f32_16x16x32_bf16 v[94:97], v[160:163], v[98:101], v[94:97]
	v_mfma_f32_16x16x32_bf16 v[86:89], v[168:171], v[98:101], v[86:89]
	v_mfma_f32_16x16x32_bf16 v[78:81], v[176:179], v[98:101], v[78:81]
	v_mfma_f32_16x16x32_bf16 v[70:73], v[184:187], v[98:101], v[70:73]
	v_mfma_f32_16x16x32_bf16 v[94:97], v[164:167], v[106:109], v[94:97]
	v_mfma_f32_16x16x32_bf16 v[90:93], v[160:163], v[114:117], v[90:93]
	v_mfma_f32_16x16x32_bf16 v[86:89], v[172:175], v[106:109], v[86:89]
	v_mfma_f32_16x16x32_bf16 v[82:85], v[168:171], v[114:117], v[82:85]
	v_mfma_f32_16x16x32_bf16 v[78:81], v[180:183], v[106:109], v[78:81]
	v_mfma_f32_16x16x32_bf16 v[74:77], v[176:179], v[114:117], v[74:77]
	v_mfma_f32_16x16x32_bf16 v[70:73], v[188:191], v[106:109], v[70:73]
	v_mfma_f32_16x16x32_bf16 v[66:69], v[184:187], v[114:117], v[66:69]
	v_mfma_f32_16x16x32_bf16 v[160:163], v[164:167], v[122:125], v[90:93]
	v_mfma_f32_16x16x32_bf16 v[164:167], v[172:175], v[122:125], v[82:85]
	v_mfma_f32_16x16x32_bf16 v[168:171], v[180:183], v[122:125], v[74:77]
	v_mfma_f32_16x16x32_bf16 v[172:175], v[188:191], v[122:125], v[66:69]
	s_setprio 0
	s_barrier
	s_nop 1
	ds_read_b128 v[66:69], v132 offset:16384
	ds_read_b128 v[74:77], v132 offset:17408
	ds_read_b128 v[82:85], v150 offset:16384
	ds_read_b128 v[90:93], v150 offset:17408
	ds_read_b128 v[176:179], v151 offset:16384
	ds_read_b128 v[180:183], v151 offset:17408
	ds_read_b128 v[184:187], v152 offset:16384
	ds_read_b128 v[188:191], v152 offset:17408
	s_waitcnt vmcnt(4)
	s_barrier
	s_waitcnt lgkmcnt(0)
	s_setprio 1
	s_waitcnt lgkmcnt(0)
	v_mfma_f32_16x16x32_bf16 v[62:65], v[66:69], v[136:139], v[62:65]
	v_mfma_f32_16x16x32_bf16 v[54:57], v[82:85], v[136:139], v[54:57]
	v_mfma_f32_16x16x32_bf16 v[46:49], v[176:179], v[136:139], v[46:49]
	v_mfma_f32_16x16x32_bf16 v[38:41], v[184:187], v[136:139], v[38:41]
	v_mfma_f32_16x16x32_bf16 v[62:65], v[74:77], v[140:143], v[62:65]
	v_mfma_f32_16x16x32_bf16 v[58:61], v[66:69], v[156:159], v[58:61]
	v_mfma_f32_16x16x32_bf16 v[54:57], v[90:93], v[140:143], v[54:57]
	v_mfma_f32_16x16x32_bf16 v[50:53], v[82:85], v[156:159], v[50:53]
	v_mfma_f32_16x16x32_bf16 v[46:49], v[180:183], v[140:143], v[46:49]
	v_mfma_f32_16x16x32_bf16 v[42:45], v[176:179], v[156:159], v[42:45]
	v_mfma_f32_16x16x32_bf16 v[38:41], v[188:191], v[140:143], v[38:41]
	v_mfma_f32_16x16x32_bf16 v[34:37], v[184:187], v[156:159], v[34:37]
	v_mfma_f32_16x16x32_bf16 v[210:213], v[74:77], v[146:149], v[58:61]
	v_mfma_f32_16x16x32_bf16 v[214:217], v[90:93], v[146:149], v[50:53]
	v_mfma_f32_16x16x32_bf16 v[218:221], v[180:183], v[146:149], v[42:45]
	v_mfma_f32_16x16x32_bf16 v[136:139], v[188:191], v[146:149], v[34:37]
	s_setprio 0
	s_setprio 1
	v_mfma_f32_16x16x32_bf16 v[30:33], v[66:69], v[98:101], v[30:33]
	v_mfma_f32_16x16x32_bf16 v[22:25], v[82:85], v[98:101], v[22:25]
	v_mfma_f32_16x16x32_bf16 v[14:17], v[176:179], v[98:101], v[14:17]
	v_mfma_f32_16x16x32_bf16 v[6:9], v[184:187], v[98:101], v[6:9]
	v_mfma_f32_16x16x32_bf16 v[30:33], v[74:77], v[106:109], v[30:33]
	v_mfma_f32_16x16x32_bf16 v[26:29], v[66:69], v[114:117], v[26:29]
	v_mfma_f32_16x16x32_bf16 v[22:25], v[90:93], v[106:109], v[22:25]
	v_mfma_f32_16x16x32_bf16 v[18:21], v[82:85], v[114:117], v[18:21]
	v_mfma_f32_16x16x32_bf16 v[14:17], v[180:183], v[106:109], v[14:17]
	v_mfma_f32_16x16x32_bf16 v[10:13], v[176:179], v[114:117], v[10:13]
	v_mfma_f32_16x16x32_bf16 v[6:9], v[188:191], v[106:109], v[6:9]
	v_mfma_f32_16x16x32_bf16 v[2:5], v[184:187], v[114:117], v[2:5]
	v_mfma_f32_16x16x32_bf16 v[140:143], v[74:77], v[122:125], v[26:29]
	v_mfma_f32_16x16x32_bf16 v[144:147], v[90:93], v[122:125], v[18:21]
	v_mfma_f32_16x16x32_bf16 v[154:157], v[180:183], v[122:125], v[10:13]
	v_mfma_f32_16x16x32_bf16 v[176:179], v[188:191], v[122:125], v[2:5]
	s_setprio 0
	s_barrier
	ds_read_b128 v[180:183], v135
	ds_read_b128 v[184:187], v135 offset:1024
	ds_read_b128 v[188:191], v135 offset:2048
	ds_read_b128 v[222:225], v135 offset:3072
	ds_read_b128 v[2:5], v132 offset:32768
	ds_read_b128 v[10:13], v132 offset:33792
	ds_read_b128 v[18:21], v150 offset:32768
	ds_read_b128 v[26:29], v150 offset:33792
	ds_read_b128 v[226:229], v151 offset:32768
	ds_read_b128 v[230:233], v151 offset:33792
	ds_read_b128 v[234:237], v152 offset:32768
	ds_read_b128 v[238:241], v152 offset:33792
	s_waitcnt vmcnt(2)
	s_barrier
; #define LDA(dst, b, h) for (int m = 0; m < 4; ++m) for (int k = 0; k < 2; ++k) \
;     dst[m][k] = *reinterpret_cast<const bf16x8*>((char*)SA(b, h) + lds_byte(wr * 64 + m * 16 + fr, k * 32 + fq * 8))
; #define LDB(dst, b, h) for (int n = 0; n < 2; ++n) for (int k = 0; k < 2; ++k) \
;     dst[n][k] = *reinterpret_cast<const bf16x8*>((char*)SB(b, h) + lds_byte(wc * 32 + n * 16 + fr, k * 32 + fq * 8))
; #define MMA(ai, bj, At_, Bt_) do { __builtin_amdgcn_s_setprio(1); \
;     for (int m = 0; m < 4; ++m) for (int n = 0; n < 2; ++n) for (int k = 0; k < 2; ++k) \
;       acc[ai][bj][m][n] = MFMA16(At_[m][k], Bt_[n][k], acc[ai][bj][m][n]); \
;     __builtin_amdgcn_s_setprio(0); } while (0)
; #define WAIT_V(n) asm volatile("s_waitcnt vmcnt(" #n ")" ::: "memory")
; #define WAIT_L(n) asm volatile("s_waitcnt lgkmcnt(" #n ")" ::: "memory")
; #define BAR __builtin_amdgcn_s_barrier()
; DI void gemm_core(WVP char* smem, const u16* __restrict__ A, int lda, int ar0, int ar1,
;                   const u16* __restrict__ B, int ldb, int bc0, int K, AccT& acc) {
;     ...
;     LDA(At, 0, 1); WAIT_V(4); BAR; WAIT_L(0); MMA(1, 0, At, B0); MMA(1, 1, At, B1); BAR; }
;   { LDB(B0, 1, 0); LDA(At, 1, 0); WAIT_V(2); BAR; WAIT_L(0); MMA(0, 0, At, B0); BAR;
;     LDB(B1, 1, 1); WAIT_V(0); BAR; WAIT_L(0); MMA(0, 1, At, B1); BAR;
;     LDA(At, 1, 1); BAR; WAIT_L(0); MMA(1, 0, At, B0); MMA(1, 1, At, B1); BAR; }
;   if (wr == 0) BAR;
	s_waitcnt lgkmcnt(0)
	s_setprio 1
	s_waitcnt lgkmcnt(0)
	v_mfma_f32_16x16x32_bf16 v[34:37], v[2:5], v[180:183], v[126:129]
	v_mfma_f32_16x16x32_bf16 v[122:125], v[10:13], v[184:187], v[34:37]
	v_mfma_f32_16x16x32_bf16 v[34:37], v[2:5], v[188:191], v[192:195]
	v_mfma_f32_16x16x32_bf16 v[114:117], v[10:13], v[222:225], v[34:37]
	v_mfma_f32_16x16x32_bf16 v[34:37], v[18:21], v[180:183], v[118:121]
	v_mfma_f32_16x16x32_bf16 v[106:109], v[26:29], v[184:187], v[34:37]
	v_mfma_f32_16x16x32_bf16 v[34:37], v[18:21], v[188:191], v[196:199]
	v_mfma_f32_16x16x32_bf16 v[98:101], v[26:29], v[222:225], v[34:37]
	v_mfma_f32_16x16x32_bf16 v[34:37], v[226:229], v[180:183], v[110:113]
	v_mfma_f32_16x16x32_bf16 v[90:93], v[230:233], v[184:187], v[34:37]
	v_mfma_f32_16x16x32_bf16 v[34:37], v[226:229], v[188:191], v[200:203]
	v_mfma_f32_16x16x32_bf16 v[82:85], v[230:233], v[222:225], v[34:37]
	v_mfma_f32_16x16x32_bf16 v[34:37], v[234:237], v[180:183], v[102:105]
	v_mfma_f32_16x16x32_bf16 v[74:77], v[238:241], v[184:187], v[34:37]
	v_mfma_f32_16x16x32_bf16 v[34:37], v[234:237], v[188:191], v[206:209]
	v_mfma_f32_16x16x32_bf16 v[66:69], v[238:241], v[222:225], v[34:37]
	s_setprio 0
	s_barrier
	ds_read_b128 v[192:195], v133
	ds_read_b128 v[196:199], v133 offset:1024
	ds_read_b128 v[200:203], v133 offset:2048
	ds_read_b128 v[206:209], v133 offset:3072
	s_waitcnt vmcnt(0)
	s_barrier
	s_waitcnt lgkmcnt(0)
	s_setprio 1
	s_waitcnt lgkmcnt(0)
	v_mfma_f32_16x16x32_bf16 v[34:37], v[2:5], v[192:195], v[94:97]
	v_mfma_f32_16x16x32_bf16 v[2:5], v[2:5], v[200:203], v[160:163]
	v_mfma_f32_16x16x32_bf16 v[50:53], v[10:13], v[206:209], v[2:5]
	v_mfma_f32_16x16x32_bf16 v[2:5], v[18:21], v[192:195], v[86:89]
	v_mfma_f32_16x16x32_bf16 v[42:45], v[26:29], v[196:199], v[2:5]
	v_mfma_f32_16x16x32_bf16 v[2:5], v[18:21], v[200:203], v[164:167]
	v_mfma_f32_16x16x32_bf16 v[58:61], v[10:13], v[196:199], v[34:37]
	v_mfma_f32_16x16x32_bf16 v[34:37], v[26:29], v[206:209], v[2:5]
	v_mfma_f32_16x16x32_bf16 v[2:5], v[226:229], v[192:195], v[78:81]
	v_mfma_f32_16x16x32_bf16 v[26:29], v[230:233], v[196:199], v[2:5]
	v_mfma_f32_16x16x32_bf16 v[2:5], v[226:229], v[200:203], v[168:171]
	v_mfma_f32_16x16x32_bf16 v[18:21], v[230:233], v[206:209], v[2:5]
	v_mfma_f32_16x16x32_bf16 v[2:5], v[234:237], v[192:195], v[70:73]
	v_mfma_f32_16x16x32_bf16 v[10:13], v[238:241], v[196:199], v[2:5]
	v_mfma_f32_16x16x32_bf16 v[2:5], v[234:237], v[200:203], v[172:175]
	v_mfma_f32_16x16x32_bf16 v[2:5], v[238:241], v[206:209], v[2:5]
	s_setprio 0
	s_barrier
	ds_read_b128 v[158:161], v132 offset:49152
	ds_read_b128 v[130:133], v132 offset:50176
	ds_read_b128 v[162:165], v150 offset:49152
	ds_read_b128 v[166:169], v150 offset:50176
	ds_read_b128 v[170:173], v151 offset:49152
	ds_read_b128 v[148:151], v151 offset:50176
	ds_read_b128 v[226:229], v152 offset:49152
	ds_read_b128 v[230:233], v152 offset:50176
	s_barrier
	s_waitcnt lgkmcnt(0)
	s_setprio 1
	s_waitcnt lgkmcnt(0)
	v_mfma_f32_16x16x32_bf16 v[62:65], v[158:161], v[180:183], v[62:65]
	v_mfma_f32_16x16x32_bf16 v[54:57], v[162:165], v[180:183], v[54:57]
	v_mfma_f32_16x16x32_bf16 v[46:49], v[170:173], v[180:183], v[46:49]
	v_mfma_f32_16x16x32_bf16 v[38:41], v[226:229], v[180:183], v[38:41]
	v_mfma_f32_16x16x32_bf16 v[126:129], v[130:133], v[184:187], v[62:65]
	v_mfma_f32_16x16x32_bf16 v[62:65], v[158:161], v[188:191], v[210:213]
	v_mfma_f32_16x16x32_bf16 v[110:113], v[166:169], v[184:187], v[54:57]
	v_mfma_f32_16x16x32_bf16 v[54:57], v[162:165], v[188:191], v[214:217]
	v_mfma_f32_16x16x32_bf16 v[94:97], v[148:151], v[184:187], v[46:49]
	v_mfma_f32_16x16x32_bf16 v[46:49], v[170:173], v[188:191], v[218:221]
	v_mfma_f32_16x16x32_bf16 v[78:81], v[230:233], v[184:187], v[38:41]
	v_mfma_f32_16x16x32_bf16 v[38:41], v[226:229], v[188:191], v[136:139]
	v_mfma_f32_16x16x32_bf16 v[118:121], v[130:133], v[222:225], v[62:65]
	v_mfma_f32_16x16x32_bf16 v[102:105], v[166:169], v[222:225], v[54:57]
	v_mfma_f32_16x16x32_bf16 v[86:89], v[148:151], v[222:225], v[46:49]
	v_mfma_f32_16x16x32_bf16 v[70:73], v[230:233], v[222:225], v[38:41]
	s_setprio 0
	s_setprio 1
	v_mfma_f32_16x16x32_bf16 v[30:33], v[158:161], v[192:195], v[30:33]
	v_mfma_f32_16x16x32_bf16 v[62:65], v[130:133], v[196:199], v[30:33]
	v_mfma_f32_16x16x32_bf16 v[30:33], v[158:161], v[200:203], v[140:143]
	v_mfma_f32_16x16x32_bf16 v[22:25], v[162:165], v[192:195], v[22:25]
	v_mfma_f32_16x16x32_bf16 v[14:17], v[170:173], v[192:195], v[14:17]
	v_mfma_f32_16x16x32_bf16 v[54:57], v[130:133], v[206:209], v[30:33]
	v_mfma_f32_16x16x32_bf16 v[46:49], v[166:169], v[196:199], v[22:25]
	v_mfma_f32_16x16x32_bf16 v[22:25], v[162:165], v[200:203], v[144:147]
	v_mfma_f32_16x16x32_bf16 v[30:33], v[148:151], v[196:199], v[14:17]
	v_mfma_f32_16x16x32_bf16 v[14:17], v[170:173], v[200:203], v[154:157]
	v_mfma_f32_16x16x32_bf16 v[6:9], v[226:229], v[192:195], v[6:9]
	v_mfma_f32_16x16x32_bf16 v[38:41], v[166:169], v[206:209], v[22:25]
	v_mfma_f32_16x16x32_bf16 v[22:25], v[148:151], v[206:209], v[14:17]
	v_mfma_f32_16x16x32_bf16 v[14:17], v[230:233], v[196:199], v[6:9]
	v_mfma_f32_16x16x32_bf16 v[6:9], v[226:229], v[200:203], v[176:179]
	v_mfma_f32_16x16x32_bf16 v[6:9], v[230:233], v[206:209], v[6:9]
	s_setprio 0
	s_cmp_gt_u32 s47, 3
	s_barrier
	s_cbranch_scc1 .LBB0_213
	s_barrier
	s_branch .LBB0_213

; #define STAGE_A(P, br, kt) do { const char* _g = (const char*)(A + (long)(br) * lda + (long)(kt) * BK); \
;     __builtin_amdgcn_global_load_lds((const unsigned*)(_g + (size_t)offA0), (unsigned*)((char*)(P) + sb0), 16, 0, 0); \
;     __builtin_amdgcn_global_load_lds((const unsigned*)(_g + (size_t)lda * 128 + (size_t)offA0), (unsigned*)((char*)(P) + sb1), 16, 0, 0); } while (0)
; #define STAGE_B(P, br, kt) do { const char* _g = (const char*)(B + (long)(br) * ldb + (long)(kt) * BK); \
;     __builtin_amdgcn_global_load_lds((const unsigned*)(_g + (size_t)offB0), (unsigned*)((char*)(P) + sb0), 16, 0, 0); \
;     __builtin_amdgcn_global_load_lds((const unsigned*)(_g + (size_t)ldb * 128 + (size_t)offB0), (unsigned*)((char*)(P) + sb1), 16, 0, 0); } while (0)
; #define LDA(dst, b, h) for (int m = 0; m < 4; ++m) for (int k = 0; k < 2; ++k) \
;     dst[m][k] = *reinterpret_cast<const bf16x8*>((char*)SA(b, h) + lds_byte(wr * 64 + m * 16 + fr, k * 32 + fq * 8))
; #define LDB(dst, b, h) for (int n = 0; n < 2; ++n) for (int k = 0; k < 2; ++k) \
;     dst[n][k] = *reinterpret_cast<const bf16x8*>((char*)SB(b, h) + lds_byte(wc * 32 + n * 16 + fr, k * 32 + fq * 8))
; #define MMA(ai, bj, At_, Bt_) do { __builtin_amdgcn_s_setprio(1); \
;     for (int m = 0; m < 4; ++m) for (int n = 0; n < 2; ++n) for (int k = 0; k < 2; ++k) \
;       acc[ai][bj][m][n] = MFMA16(At_[m][k], Bt_[n][k], acc[ai][bj][m][n]); \
;     __builtin_amdgcn_s_setprio(0); } while (0)
; #define WAIT_V(n) asm volatile("s_waitcnt vmcnt(" #n ")" ::: "memory")
; #define WAIT_L(n) asm volatile("s_waitcnt lgkmcnt(" #n ")" ::: "memory")
; #define BAR __builtin_amdgcn_s_barrier()
; #define SCHED __builtin_amdgcn_sched_barrier(0)
; DI void gemm_core(WVP char* smem, const u16* __restrict__ A, int lda, int ar0, int ar1,
;                   const u16* __restrict__ B, int ldb, int bc0, int K, AccT& acc) {
;     ...
;   for (int t = 0; t < nt - 2; t += 2) {
;     LDB(B0, 0, 0); SCHED; LDA(At, 0, 0); STAGE_A(SA(1, 1), ac1, t + 1);
;     WAIT_L(8); BAR; WAIT_L(0); MMA(0, 0, At, B0); BAR; SCHED;
;     LDB(B1, 0, 1); STAGE_B(SB(0, 0), bb0, t + 2);
;     BAR; WAIT_L(0); MMA(0, 1, At, B1); BAR;
;     LDA(At, 0, 1); STAGE_A(SA(0, 0), ac0, t + 2);
;     BAR; WAIT_L(0); MMA(1, 0, At, B0); BAR; SCHED;
;     STAGE_B(SB(0, 1), bb1, t + 2);
;     WAIT_V(6); BAR; MMA(1, 1, At, B1); BAR;
.LBB0_237:
	v_add_u32_e32 v164, s37, v161
	v_add_u32_e32 v165, s38, v161
	v_add_u32_e32 v166, s39, v161
	ds_read_b128 v[170:173], v163
	ds_read_b128 v[174:177], v163 offset:1024
	ds_read_b128 v[178:181], v163 offset:2048
	ds_read_b128 v[182:185], v163 offset:3072
	ds_read_b128 v[186:189], v150
	ds_read_b128 v[190:193], v150 offset:1024
	ds_read_b128 v[194:197], v164
	ds_read_b128 v[198:201], v164 offset:1024
	ds_read_b128 v[206:209], v165
	ds_read_b128 v[210:213], v165 offset:1024
	ds_read_b128 v[214:217], v166
	ds_read_b128 v[218:221], v166 offset:1024
	ds_read_b128 v[222:225], v162
	ds_read_b128 v[226:229], v162 offset:1024
	ds_read_b128 v[230:233], v162 offset:2048
	ds_read_b128 v[234:237], v162 offset:3072
	v_add_u32_e32 v168, 0xc000, v147
	v_lshl_add_u64 v[238:239], v[142:143], 0, s[28:29]
	v_lshl_add_u64 v[202:203], v[238:239], 0, s[6:7]
	v_readfirstlane_b32 s31, v168
	s_mov_b32 m0, s31
	s_nop 0
	global_load_lds_dwordx4 v[202:203], off
	v_add_u32_e32 v167, 0xe000, v147
	v_lshl_add_u64 v[238:239], v[144:145], 0, s[28:29]
	v_lshl_add_u64 v[202:203], v[238:239], 0, s[6:7]
	v_readfirstlane_b32 s31, v167
	s_mov_b32 m0, s31
	s_nop 0
	global_load_lds_dwordx4 v[202:203], off
	s_waitcnt vmcnt(8)
	s_waitcnt lgkmcnt(0)
	s_barrier
	v_mfma_f32_16x16x32_bf16 v[126:129], v[186:189], v[170:173], v[126:129]
	v_mfma_f32_16x16x32_bf16 v[126:129], v[190:193], v[174:177], v[126:129]
	v_mfma_f32_16x16x32_bf16 v[118:121], v[186:189], v[178:181], v[118:121]
	v_mfma_f32_16x16x32_bf16 v[118:121], v[190:193], v[182:185], v[118:121]
	v_mfma_f32_16x16x32_bf16 v[110:113], v[194:197], v[170:173], v[110:113]
	v_mfma_f32_16x16x32_bf16 v[110:113], v[198:201], v[174:177], v[110:113]
	v_mfma_f32_16x16x32_bf16 v[102:105], v[194:197], v[178:181], v[102:105]
	v_mfma_f32_16x16x32_bf16 v[102:105], v[198:201], v[182:185], v[102:105]
	v_mfma_f32_16x16x32_bf16 v[98:101], v[206:209], v[170:173], v[98:101]
	v_mfma_f32_16x16x32_bf16 v[98:101], v[210:213], v[174:177], v[98:101]
	v_mfma_f32_16x16x32_bf16 v[86:89], v[206:209], v[178:181], v[86:89]
	v_mfma_f32_16x16x32_bf16 v[86:89], v[210:213], v[182:185], v[86:89]
	v_mfma_f32_16x16x32_bf16 v[78:81], v[214:217], v[170:173], v[78:81]
	v_mfma_f32_16x16x32_bf16 v[78:81], v[218:221], v[174:177], v[78:81]
	v_mfma_f32_16x16x32_bf16 v[70:73], v[214:217], v[178:181], v[70:73]
	v_mfma_f32_16x16x32_bf16 v[70:73], v[218:221], v[182:185], v[70:73]
	v_mfma_f32_16x16x32_bf16 v[66:69], v[186:189], v[222:225], v[66:69]
	v_mfma_f32_16x16x32_bf16 v[66:69], v[190:193], v[226:229], v[66:69]
	v_mfma_f32_16x16x32_bf16 v[54:57], v[186:189], v[230:233], v[54:57]
	v_mfma_f32_16x16x32_bf16 v[54:57], v[190:193], v[234:237], v[54:57]
	v_mfma_f32_16x16x32_bf16 v[46:49], v[194:197], v[222:225], v[46:49]
	v_mfma_f32_16x16x32_bf16 v[46:49], v[198:201], v[226:229], v[46:49]
	v_mfma_f32_16x16x32_bf16 v[38:41], v[194:197], v[230:233], v[38:41]
	v_mfma_f32_16x16x32_bf16 v[38:41], v[198:201], v[234:237], v[38:41]
	v_mfma_f32_16x16x32_bf16 v[34:37], v[206:209], v[222:225], v[34:37]
	v_mfma_f32_16x16x32_bf16 v[34:37], v[210:213], v[226:229], v[34:37]
	v_mfma_f32_16x16x32_bf16 v[22:25], v[206:209], v[230:233], v[22:25]
	v_mfma_f32_16x16x32_bf16 v[22:25], v[210:213], v[234:237], v[22:25]
	v_mfma_f32_16x16x32_bf16 v[14:17], v[214:217], v[222:225], v[14:17]
	v_mfma_f32_16x16x32_bf16 v[14:17], v[218:221], v[226:229], v[14:17]
	v_mfma_f32_16x16x32_bf16 v[6:9], v[214:217], v[230:233], v[6:9]
	v_mfma_f32_16x16x32_bf16 v[6:9], v[218:221], v[234:237], v[6:9]
	s_barrier
	ds_read_b128 v[186:189], v150 offset:16384
	ds_read_b128 v[190:193], v150 offset:17408
	ds_read_b128 v[194:197], v164 offset:16384
	ds_read_b128 v[198:201], v164 offset:17408
	ds_read_b128 v[206:209], v165 offset:16384
	ds_read_b128 v[210:213], v165 offset:17408
	ds_read_b128 v[214:217], v166 offset:16384
	ds_read_b128 v[218:221], v166 offset:17408
	v_lshl_add_u64 v[238:239], v[130:131], 0, s[28:29]
	v_lshl_add_u64 v[202:203], v[238:239], 0, s[68:69]
	v_readfirstlane_b32 s31, v146
	s_mov_b32 m0, s31
	s_nop 0
	global_load_lds_dwordx4 v[202:203], off
	v_add_u32_e32 v169, 0x2000, v146
	v_lshl_add_u64 v[238:239], v[132:133], 0, s[28:29]
	v_lshl_add_u64 v[202:203], v[238:239], 0, s[68:69]
	v_readfirstlane_b32 s31, v169
	s_mov_b32 m0, s31
	s_nop 0
	global_load_lds_dwordx4 v[202:203], off
	v_lshl_add_u64 v[238:239], v[134:135], 0, s[28:29]
	v_lshl_add_u64 v[202:203], v[238:239], 0, s[48:49]
	v_readfirstlane_b32 s31, v147
	s_mov_b32 m0, s31
	s_nop 0
	global_load_lds_dwordx4 v[202:203], off
	v_lshl_add_u64 v[238:239], v[136:137], 0, s[28:29]
	v_lshl_add_u64 v[202:203], v[238:239], 0, s[48:49]
	v_readfirstlane_b32 s31, v148
	s_mov_b32 m0, s31
	s_nop 0
	global_load_lds_dwordx4 v[202:203], off
	v_lshl_add_u64 v[238:239], v[138:139], 0, s[28:29]
	v_lshl_add_u64 v[202:203], v[238:239], 0, s[68:69]
	v_readfirstlane_b32 s31, v149
	s_mov_b32 m0, s31
	s_nop 0
	global_load_lds_dwordx4 v[202:203], off
	v_add_u32_e32 v169, 0x2000, v149
	v_lshl_add_u64 v[238:239], v[140:141], 0, s[28:29]
	v_lshl_add_u64 v[202:203], v[238:239], 0, s[68:69]
	v_readfirstlane_b32 s31, v169
	s_mov_b32 m0, s31
	s_nop 0
	global_load_lds_dwordx4 v[202:203], off
	s_waitcnt vmcnt(8)
	s_waitcnt lgkmcnt(0)
	s_barrier
; #define STAGE_A(P, br, kt) do { const char* _g = (const char*)(A + (long)(br) * lda + (long)(kt) * BK); \
;     __builtin_amdgcn_global_load_lds((const unsigned*)(_g + (size_t)offA0), (unsigned*)((char*)(P) + sb0), 16, 0, 0); \
;     __builtin_amdgcn_global_load_lds((const unsigned*)(_g + (size_t)lda * 128 + (size_t)offA0), (unsigned*)((char*)(P) + sb1), 16, 0, 0); } while (0)
; #define STAGE_B(P, br, kt) do { const char* _g = (const char*)(B + (long)(br) * ldb + (long)(kt) * BK); \
;     __builtin_amdgcn_global_load_lds((const unsigned*)(_g + (size_t)offB0), (unsigned*)((char*)(P) + sb0), 16, 0, 0); \
;     __builtin_amdgcn_global_load_lds((const unsigned*)(_g + (size_t)ldb * 128 + (size_t)offB0), (unsigned*)((char*)(P) + sb1), 16, 0, 0); } while (0)
; #define LDA(dst, b, h) for (int m = 0; m < 4; ++m) for (int k = 0; k < 2; ++k) \
;     dst[m][k] = *reinterpret_cast<const bf16x8*>((char*)SA(b, h) + lds_byte(wr * 64 + m * 16 + fr, k * 32 + fq * 8))
; #define LDB(dst, b, h) for (int n = 0; n < 2; ++n) for (int k = 0; k < 2; ++k) \
;     dst[n][k] = *reinterpret_cast<const bf16x8*>((char*)SB(b, h) + lds_byte(wc * 32 + n * 16 + fr, k * 32 + fq * 8))
; #define MMA(ai, bj, At_, Bt_) do { __builtin_amdgcn_s_setprio(1); \
;     for (int m = 0; m < 4; ++m) for (int n = 0; n < 2; ++n) for (int k = 0; k < 2; ++k) \
;       acc[ai][bj][m][n] = MFMA16(At_[m][k], Bt_[n][k], acc[ai][bj][m][n]); \
;     __builtin_amdgcn_s_setprio(0); } while (0)
; #define WAIT_V(n) asm volatile("s_waitcnt vmcnt(" #n ")" ::: "memory")
; #define WAIT_L(n) asm volatile("s_waitcnt lgkmcnt(" #n ")" ::: "memory")
; #define BAR __builtin_amdgcn_s_barrier()
; #define SCHED __builtin_amdgcn_sched_barrier(0)
; DI void gemm_core(WVP char* smem, const u16* __restrict__ A, int lda, int ar0, int ar1,
;                   const u16* __restrict__ B, int ldb, int bc0, int K, AccT& acc) {
;     ...
;     BAR; WAIT_L(0); MMA(1, 0, At, B0); BAR; SCHED;
;     STAGE_B(SB(0, 1), bb1, t + 2);
;     WAIT_V(6); BAR; MMA(1, 1, At, B1); BAR;
;     LDB(B0, 1, 0); SCHED; LDA(At, 1, 0); STAGE_A(SA(0, 1), ac1, t + 2);
;     WAIT_L(8); BAR; WAIT_L(0); MMA(0, 0, At, B0); BAR; SCHED;
;     LDB(B1, 1, 1); STAGE_B(SB(1, 0), bb0, t + 3);
;     BAR; WAIT_L(0); MMA(0, 1, At, B1); BAR;
	v_mfma_f32_16x16x32_bf16 v[122:125], v[186:189], v[170:173], v[122:125]
	v_mfma_f32_16x16x32_bf16 v[122:125], v[190:193], v[174:177], v[122:125]
	v_mfma_f32_16x16x32_bf16 v[114:117], v[186:189], v[178:181], v[114:117]
	v_mfma_f32_16x16x32_bf16 v[114:117], v[190:193], v[182:185], v[114:117]
	v_mfma_f32_16x16x32_bf16 v[106:109], v[194:197], v[170:173], v[106:109]
	v_mfma_f32_16x16x32_bf16 v[106:109], v[198:201], v[174:177], v[106:109]
	v_mfma_f32_16x16x32_bf16 v[94:97], v[194:197], v[178:181], v[94:97]
	v_mfma_f32_16x16x32_bf16 v[94:97], v[198:201], v[182:185], v[94:97]
	v_mfma_f32_16x16x32_bf16 v[90:93], v[206:209], v[170:173], v[90:93]
	v_mfma_f32_16x16x32_bf16 v[90:93], v[210:213], v[174:177], v[90:93]
	v_mfma_f32_16x16x32_bf16 v[82:85], v[206:209], v[178:181], v[82:85]
	v_mfma_f32_16x16x32_bf16 v[82:85], v[210:213], v[182:185], v[82:85]
	v_mfma_f32_16x16x32_bf16 v[74:77], v[214:217], v[170:173], v[74:77]
	v_mfma_f32_16x16x32_bf16 v[74:77], v[218:221], v[174:177], v[74:77]
	v_mfma_f32_16x16x32_bf16 v[62:65], v[214:217], v[178:181], v[62:65]
	v_mfma_f32_16x16x32_bf16 v[62:65], v[218:221], v[182:185], v[62:65]
	v_mfma_f32_16x16x32_bf16 v[58:61], v[186:189], v[222:225], v[58:61]
	v_mfma_f32_16x16x32_bf16 v[58:61], v[190:193], v[226:229], v[58:61]
	v_mfma_f32_16x16x32_bf16 v[50:53], v[186:189], v[230:233], v[50:53]
	v_mfma_f32_16x16x32_bf16 v[50:53], v[190:193], v[234:237], v[50:53]
	v_mfma_f32_16x16x32_bf16 v[42:45], v[194:197], v[222:225], v[42:45]
	v_mfma_f32_16x16x32_bf16 v[42:45], v[198:201], v[226:229], v[42:45]
	v_mfma_f32_16x16x32_bf16 v[30:33], v[194:197], v[230:233], v[30:33]
	v_mfma_f32_16x16x32_bf16 v[30:33], v[198:201], v[234:237], v[30:33]
	v_mfma_f32_16x16x32_bf16 v[26:29], v[206:209], v[222:225], v[26:29]
	v_mfma_f32_16x16x32_bf16 v[26:29], v[210:213], v[226:229], v[26:29]
	v_mfma_f32_16x16x32_bf16 v[18:21], v[206:209], v[230:233], v[18:21]
	v_mfma_f32_16x16x32_bf16 v[18:21], v[210:213], v[234:237], v[18:21]
	v_mfma_f32_16x16x32_bf16 v[10:13], v[214:217], v[222:225], v[10:13]
	v_mfma_f32_16x16x32_bf16 v[10:13], v[218:221], v[226:229], v[10:13]
	v_mfma_f32_16x16x32_bf16 v[2:5], v[214:217], v[230:233], v[2:5]
	v_mfma_f32_16x16x32_bf16 v[2:5], v[218:221], v[234:237], v[2:5]
	s_barrier
	ds_read_b128 v[170:173], v154
	ds_read_b128 v[174:177], v154 offset:1024
	ds_read_b128 v[178:181], v154 offset:2048
	ds_read_b128 v[182:185], v154 offset:3072
	ds_read_b128 v[186:189], v150 offset:32768
	ds_read_b128 v[190:193], v150 offset:33792
	ds_read_b128 v[194:197], v164 offset:32768
	ds_read_b128 v[198:201], v164 offset:33792
	ds_read_b128 v[206:209], v165 offset:32768
	ds_read_b128 v[210:213], v165 offset:33792
	ds_read_b128 v[214:217], v166 offset:32768
	ds_read_b128 v[218:221], v166 offset:33792
	ds_read_b128 v[222:225], v153
	ds_read_b128 v[226:229], v153 offset:1024
	ds_read_b128 v[230:233], v153 offset:2048
	ds_read_b128 v[234:237], v153 offset:3072
	v_lshl_add_u64 v[238:239], v[142:143], 0, s[28:29]
	v_lshl_add_u64 v[202:203], v[238:239], 0, s[48:49]
	v_readfirstlane_b32 s31, v151
	s_mov_b32 m0, s31
	s_nop 0
	global_load_lds_dwordx4 v[202:203], off
	v_lshl_add_u64 v[238:239], v[144:145], 0, s[28:29]
	v_lshl_add_u64 v[202:203], v[238:239], 0, s[48:49]
	v_readfirstlane_b32 s31, v152
	s_mov_b32 m0, s31
	s_nop 0
	global_load_lds_dwordx4 v[202:203], off
	s_waitcnt vmcnt(8)
	s_waitcnt lgkmcnt(0)
	s_barrier
	v_mfma_f32_16x16x32_bf16 v[126:129], v[186:189], v[170:173], v[126:129]
	v_mfma_f32_16x16x32_bf16 v[126:129], v[190:193], v[174:177], v[126:129]
	v_mfma_f32_16x16x32_bf16 v[118:121], v[186:189], v[178:181], v[118:121]
	v_mfma_f32_16x16x32_bf16 v[118:121], v[190:193], v[182:185], v[118:121]
	v_mfma_f32_16x16x32_bf16 v[110:113], v[194:197], v[170:173], v[110:113]
	v_mfma_f32_16x16x32_bf16 v[110:113], v[198:201], v[174:177], v[110:113]
	v_mfma_f32_16x16x32_bf16 v[102:105], v[194:197], v[178:181], v[102:105]
	v_mfma_f32_16x16x32_bf16 v[102:105], v[198:201], v[182:185], v[102:105]
	v_mfma_f32_16x16x32_bf16 v[98:101], v[206:209], v[170:173], v[98:101]
	v_mfma_f32_16x16x32_bf16 v[98:101], v[210:213], v[174:177], v[98:101]
	v_mfma_f32_16x16x32_bf16 v[86:89], v[206:209], v[178:181], v[86:89]
	v_mfma_f32_16x16x32_bf16 v[86:89], v[210:213], v[182:185], v[86:89]
	v_mfma_f32_16x16x32_bf16 v[78:81], v[214:217], v[170:173], v[78:81]
	v_mfma_f32_16x16x32_bf16 v[78:81], v[218:221], v[174:177], v[78:81]
	v_mfma_f32_16x16x32_bf16 v[70:73], v[214:217], v[178:181], v[70:73]
	v_mfma_f32_16x16x32_bf16 v[70:73], v[218:221], v[182:185], v[70:73]
	v_mfma_f32_16x16x32_bf16 v[66:69], v[186:189], v[222:225], v[66:69]
	v_mfma_f32_16x16x32_bf16 v[66:69], v[190:193], v[226:229], v[66:69]
	v_mfma_f32_16x16x32_bf16 v[54:57], v[186:189], v[230:233], v[54:57]
	v_mfma_f32_16x16x32_bf16 v[54:57], v[190:193], v[234:237], v[54:57]
	v_mfma_f32_16x16x32_bf16 v[46:49], v[194:197], v[222:225], v[46:49]
	v_mfma_f32_16x16x32_bf16 v[46:49], v[198:201], v[226:229], v[46:49]
	v_mfma_f32_16x16x32_bf16 v[38:41], v[194:197], v[230:233], v[38:41]
	v_mfma_f32_16x16x32_bf16 v[38:41], v[198:201], v[234:237], v[38:41]
	v_mfma_f32_16x16x32_bf16 v[34:37], v[206:209], v[222:225], v[34:37]
	v_mfma_f32_16x16x32_bf16 v[34:37], v[210:213], v[226:229], v[34:37]
	v_mfma_f32_16x16x32_bf16 v[22:25], v[206:209], v[230:233], v[22:25]
	v_mfma_f32_16x16x32_bf16 v[22:25], v[210:213], v[234:237], v[22:25]
	v_mfma_f32_16x16x32_bf16 v[14:17], v[214:217], v[222:225], v[14:17]
	v_mfma_f32_16x16x32_bf16 v[14:17], v[218:221], v[226:229], v[14:17]
	v_mfma_f32_16x16x32_bf16 v[6:9], v[214:217], v[230:233], v[6:9]
	v_mfma_f32_16x16x32_bf16 v[6:9], v[218:221], v[234:237], v[6:9]
	s_barrier
; #define STAGE_A(P, br, kt) do { const char* _g = (const char*)(A + (long)(br) * lda + (long)(kt) * BK); \
;     __builtin_amdgcn_global_load_lds((const unsigned*)(_g + (size_t)offA0), (unsigned*)((char*)(P) + sb0), 16, 0, 0); \
;     __builtin_amdgcn_global_load_lds((const unsigned*)(_g + (size_t)lda * 128 + (size_t)offA0), (unsigned*)((char*)(P) + sb1), 16, 0, 0); } while (0)
; #define STAGE_B(P, br, kt) do { const char* _g = (const char*)(B + (long)(br) * ldb + (long)(kt) * BK); \
;     __builtin_amdgcn_global_load_lds((const unsigned*)(_g + (size_t)offB0), (unsigned*)((char*)(P) + sb0), 16, 0, 0); \
;     __builtin_amdgcn_global_load_lds((const unsigned*)(_g + (size_t)ldb * 128 + (size_t)offB0), (unsigned*)((char*)(P) + sb1), 16, 0, 0); } while (0)
; #define LDA(dst, b, h) for (int m = 0; m < 4; ++m) for (int k = 0; k < 2; ++k) \
;     dst[m][k] = *reinterpret_cast<const bf16x8*>((char*)SA(b, h) + lds_byte(wr * 64 + m * 16 + fr, k * 32 + fq * 8))
; #define LDB(dst, b, h) for (int n = 0; n < 2; ++n) for (int k = 0; k < 2; ++k) \
;     dst[n][k] = *reinterpret_cast<const bf16x8*>((char*)SB(b, h) + lds_byte(wc * 32 + n * 16 + fr, k * 32 + fq * 8))
; #define MMA(ai, bj, At_, Bt_) do { __builtin_amdgcn_s_setprio(1); \
;     for (int m = 0; m < 4; ++m) for (int n = 0; n < 2; ++n) for (int k = 0; k < 2; ++k) \
;       acc[ai][bj][m][n] = MFMA16(At_[m][k], Bt_[n][k], acc[ai][bj][m][n]); \
;     __builtin_amdgcn_s_setprio(0); } while (0)
; #define WAIT_V(n) asm volatile("s_waitcnt vmcnt(" #n ")" ::: "memory")
; #define WAIT_L(n) asm volatile("s_waitcnt lgkmcnt(" #n ")" ::: "memory")
; #define BAR __builtin_amdgcn_s_barrier()
; #define SCHED __builtin_amdgcn_sched_barrier(0)
; DI void gemm_core(WVP char* smem, const u16* __restrict__ A, int lda, int ar0, int ar1,
;                   const u16* __restrict__ B, int ldb, int bc0, int K, AccT& acc) {
;     ...
;     BAR; WAIT_L(0); MMA(0, 1, At, B1); BAR;
;     LDA(At, 1, 1); STAGE_A(SA(1, 0), ac0, t + 3);
;     BAR; WAIT_L(0); MMA(1, 0, At, B0); BAR; SCHED;
;     STAGE_B(SB(1, 1), bb1, t + 3);
;     WAIT_V(6); BAR; MMA(1, 1, At, B1); BAR;
;   }
;   { LDB(B0, 0, 0); LDA(At, 0, 0); STAGE_A(SA(1, 1), ac1, nt - 1);
;     BAR; WAIT_L(0); MMA(0, 0, At, B0); BAR;
;     LDB(B1, 0, 1); BAR; WAIT_L(0); MMA(0, 1, At, B1); BAR;
;     LDA(At, 0, 1); WAIT_V(4); BAR; WAIT_L(0); MMA(1, 0, At, B0); MMA(1, 1, At, B1); BAR; }
	ds_read_b128 v[186:189], v150 offset:49152
	ds_read_b128 v[190:193], v150 offset:50176
	ds_read_b128 v[194:197], v164 offset:49152
	ds_read_b128 v[198:201], v164 offset:50176
	ds_read_b128 v[206:209], v165 offset:49152
	ds_read_b128 v[210:213], v165 offset:50176
	ds_read_b128 v[214:217], v166 offset:49152
	ds_read_b128 v[218:221], v166 offset:50176
	v_lshl_add_u64 v[238:239], v[130:131], 0, s[28:29]
	v_lshl_add_u64 v[202:203], v[238:239], 0, s[70:71]
	v_readfirstlane_b32 s31, v155
	s_mov_b32 m0, s31
	s_nop 0
	global_load_lds_dwordx4 v[202:203], off
	v_lshl_add_u64 v[238:239], v[132:133], 0, s[28:29]
	v_lshl_add_u64 v[202:203], v[238:239], 0, s[70:71]
	v_readfirstlane_b32 s31, v156
	s_mov_b32 m0, s31
	s_nop 0
	global_load_lds_dwordx4 v[202:203], off
	v_lshl_add_u64 v[238:239], v[134:135], 0, s[28:29]
	v_lshl_add_u64 v[202:203], v[238:239], 0, s[62:63]
	v_readfirstlane_b32 s31, v157
	s_mov_b32 m0, s31
	s_nop 0
	global_load_lds_dwordx4 v[202:203], off
	v_lshl_add_u64 v[238:239], v[136:137], 0, s[28:29]
	v_lshl_add_u64 v[202:203], v[238:239], 0, s[62:63]
	v_readfirstlane_b32 s31, v158
	s_mov_b32 m0, s31
	s_nop 0
	global_load_lds_dwordx4 v[202:203], off
	v_lshl_add_u64 v[238:239], v[138:139], 0, s[28:29]
	v_lshl_add_u64 v[202:203], v[238:239], 0, s[70:71]
	v_readfirstlane_b32 s31, v159
	s_mov_b32 m0, s31
	s_nop 0
	global_load_lds_dwordx4 v[202:203], off
	v_lshl_add_u64 v[238:239], v[140:141], 0, s[28:29]
	v_lshl_add_u64 v[202:203], v[238:239], 0, s[70:71]
	v_readfirstlane_b32 s31, v160
	s_mov_b32 m0, s31
	s_nop 0
	global_load_lds_dwordx4 v[202:203], off
	s_waitcnt vmcnt(8)
	s_waitcnt lgkmcnt(0)
	s_barrier
	v_mfma_f32_16x16x32_bf16 v[122:125], v[186:189], v[170:173], v[122:125]
	v_mfma_f32_16x16x32_bf16 v[122:125], v[190:193], v[174:177], v[122:125]
	v_mfma_f32_16x16x32_bf16 v[114:117], v[186:189], v[178:181], v[114:117]
	v_mfma_f32_16x16x32_bf16 v[114:117], v[190:193], v[182:185], v[114:117]
	v_mfma_f32_16x16x32_bf16 v[106:109], v[194:197], v[170:173], v[106:109]
	v_mfma_f32_16x16x32_bf16 v[106:109], v[198:201], v[174:177], v[106:109]
	v_mfma_f32_16x16x32_bf16 v[94:97], v[194:197], v[178:181], v[94:97]
	v_mfma_f32_16x16x32_bf16 v[94:97], v[198:201], v[182:185], v[94:97]
	v_mfma_f32_16x16x32_bf16 v[90:93], v[206:209], v[170:173], v[90:93]
	v_mfma_f32_16x16x32_bf16 v[90:93], v[210:213], v[174:177], v[90:93]
	v_mfma_f32_16x16x32_bf16 v[82:85], v[206:209], v[178:181], v[82:85]
	v_mfma_f32_16x16x32_bf16 v[82:85], v[210:213], v[182:185], v[82:85]
	v_mfma_f32_16x16x32_bf16 v[74:77], v[214:217], v[170:173], v[74:77]
	v_mfma_f32_16x16x32_bf16 v[74:77], v[218:221], v[174:177], v[74:77]
	v_mfma_f32_16x16x32_bf16 v[62:65], v[214:217], v[178:181], v[62:65]
	v_mfma_f32_16x16x32_bf16 v[62:65], v[218:221], v[182:185], v[62:65]
	v_mfma_f32_16x16x32_bf16 v[58:61], v[186:189], v[222:225], v[58:61]
	v_mfma_f32_16x16x32_bf16 v[58:61], v[190:193], v[226:229], v[58:61]
	v_mfma_f32_16x16x32_bf16 v[50:53], v[186:189], v[230:233], v[50:53]
	v_mfma_f32_16x16x32_bf16 v[50:53], v[190:193], v[234:237], v[50:53]
	v_mfma_f32_16x16x32_bf16 v[42:45], v[194:197], v[222:225], v[42:45]
	v_mfma_f32_16x16x32_bf16 v[42:45], v[198:201], v[226:229], v[42:45]
	v_mfma_f32_16x16x32_bf16 v[30:33], v[194:197], v[230:233], v[30:33]
	v_mfma_f32_16x16x32_bf16 v[30:33], v[198:201], v[234:237], v[30:33]
	v_mfma_f32_16x16x32_bf16 v[26:29], v[206:209], v[222:225], v[26:29]
	v_mfma_f32_16x16x32_bf16 v[26:29], v[210:213], v[226:229], v[26:29]
	v_mfma_f32_16x16x32_bf16 v[18:21], v[206:209], v[230:233], v[18:21]
	v_mfma_f32_16x16x32_bf16 v[18:21], v[210:213], v[234:237], v[18:21]
	v_mfma_f32_16x16x32_bf16 v[10:13], v[214:217], v[222:225], v[10:13]
	v_mfma_f32_16x16x32_bf16 v[10:13], v[218:221], v[226:229], v[10:13]
	v_mfma_f32_16x16x32_bf16 v[2:5], v[214:217], v[230:233], v[2:5]
	v_mfma_f32_16x16x32_bf16 v[2:5], v[218:221], v[234:237], v[2:5]
	s_add_i32 s30, s30, 2
	s_add_u32 s28, s28, 0x100
	s_addc_u32 s29, s29, 0
	s_cmp_lt_u32 s30, s1
	s_barrier
	s_cbranch_scc1 .LBB0_237
	s_add_i32 s58, s0, -1
	s_lshl_b64 s[0:1], s[58:59], 7
	s_add_u32 s0, s24, s0
	s_addc_u32 s1, s25, s1
	v_lshl_add_u64 v[160:161], s[0:1], 0, v[0:1]
	v_readfirstlane_b32 s24, v168
	s_add_u32 s0, s0, s36
	s_mov_b32 m0, s24
	s_addc_u32 s1, s1, 0
	ds_read_b128 v[130:133], v163
	ds_read_b128 v[134:137], v163 offset:1024
	ds_read_b128 v[138:141], v163 offset:2048
	ds_read_b128 v[142:145], v163 offset:3072
	ds_read_b128 v[146:149], v150
	ds_read_b128 v[156:159], v150 offset:1024
	ds_read_b128 v[170:173], v164
	ds_read_b128 v[174:177], v164 offset:1024
	ds_read_b128 v[178:181], v165
	ds_read_b128 v[182:185], v165 offset:1024
	ds_read_b128 v[186:189], v166
	ds_read_b128 v[190:193], v166 offset:1024
	global_load_lds_dwordx4 v[160:161], off
	v_lshl_add_u64 v[160:161], s[0:1], 0, v[0:1]
	v_readfirstlane_b32 s0, v167
	s_mov_b32 m0, s0
	s_nop 0
	global_load_lds_dwordx4 v[160:161], off
	s_waitcnt vmcnt(8)
	s_barrier
	s_waitcnt lgkmcnt(0)
	s_setprio 1
	s_waitcnt lgkmcnt(0)
	v_mfma_f32_16x16x32_bf16 v[126:129], v[146:149], v[130:133], v[126:129]
	v_mfma_f32_16x16x32_bf16 v[118:121], v[146:149], v[138:141], v[118:121]
	v_mfma_f32_16x16x32_bf16 v[110:113], v[170:173], v[130:133], v[110:113]
	v_mfma_f32_16x16x32_bf16 v[102:105], v[170:173], v[138:141], v[102:105]
	v_mfma_f32_16x16x32_bf16 v[98:101], v[178:181], v[130:133], v[98:101]
	v_mfma_f32_16x16x32_bf16 v[86:89], v[178:181], v[138:141], v[86:89]
	v_mfma_f32_16x16x32_bf16 v[78:81], v[186:189], v[130:133], v[78:81]
	v_mfma_f32_16x16x32_bf16 v[70:73], v[186:189], v[138:141], v[70:73]
	v_mfma_f32_16x16x32_bf16 v[126:129], v[156:159], v[134:137], v[126:129]
	v_mfma_f32_16x16x32_bf16 v[118:121], v[156:159], v[142:145], v[118:121]
	v_mfma_f32_16x16x32_bf16 v[110:113], v[174:177], v[134:137], v[110:113]
	v_mfma_f32_16x16x32_bf16 v[102:105], v[174:177], v[142:145], v[102:105]
	v_mfma_f32_16x16x32_bf16 v[98:101], v[182:185], v[134:137], v[98:101]
	v_mfma_f32_16x16x32_bf16 v[86:89], v[182:185], v[142:145], v[86:89]
	v_mfma_f32_16x16x32_bf16 v[78:81], v[190:193], v[134:137], v[78:81]
	v_mfma_f32_16x16x32_bf16 v[70:73], v[190:193], v[142:145], v[70:73]
	s_setprio 0
	s_barrier
; #define STAGE_A(P, br, kt) do { const char* _g = (const char*)(A + (long)(br) * lda + (long)(kt) * BK); \
;     __builtin_amdgcn_global_load_lds((const unsigned*)(_g + (size_t)offA0), (unsigned*)((char*)(P) + sb0), 16, 0, 0); \
;     __builtin_amdgcn_global_load_lds((const unsigned*)(_g + (size_t)lda * 128 + (size_t)offA0), (unsigned*)((char*)(P) + sb1), 16, 0, 0); } while (0)
; #define LDA(dst, b, h) for (int m = 0; m < 4; ++m) for (int k = 0; k < 2; ++k) \
;     dst[m][k] = *reinterpret_cast<const bf16x8*>((char*)SA(b, h) + lds_byte(wr * 64 + m * 16 + fr, k * 32 + fq * 8))
; #define LDB(dst, b, h) for (int n = 0; n < 2; ++n) for (int k = 0; k < 2; ++k) \
;     dst[n][k] = *reinterpret_cast<const bf16x8*>((char*)SB(b, h) + lds_byte(wc * 32 + n * 16 + fr, k * 32 + fq * 8))
; #define MMA(ai, bj, At_, Bt_) do { __builtin_amdgcn_s_setprio(1); \
;     for (int m = 0; m < 4; ++m) for (int n = 0; n < 2; ++n) for (int k = 0; k < 2; ++k) \
;       acc[ai][bj][m][n] = MFMA16(At_[m][k], Bt_[n][k], acc[ai][bj][m][n]); \
;     __builtin_amdgcn_s_setprio(0); } while (0)
; #define WAIT_V(n) asm volatile("s_waitcnt vmcnt(" #n ")" ::: "memory")
; #define WAIT_L(n) asm volatile("s_waitcnt lgkmcnt(" #n ")" ::: "memory")
; #define BAR __builtin_amdgcn_s_barrier()
; DI void gemm_core(WVP char* smem, const u16* __restrict__ A, int lda, int ar0, int ar1,
;                   const u16* __restrict__ B, int ldb, int bc0, int K, AccT& acc) {
;     ...
;   { LDB(B0, 0, 0); LDA(At, 0, 0); STAGE_A(SA(1, 1), ac1, nt - 1);
;     BAR; WAIT_L(0); MMA(0, 0, At, B0); BAR;
;     LDB(B1, 0, 1); BAR; WAIT_L(0); MMA(0, 1, At, B1); BAR;
;     LDA(At, 0, 1); WAIT_V(4); BAR; WAIT_L(0); MMA(1, 0, At, B0); MMA(1, 1, At, B1); BAR; }
;   { LDB(B0, 1, 0); LDA(At, 1, 0); WAIT_V(2); BAR; WAIT_L(0); MMA(0, 0, At, B0); BAR;
	ds_read_b128 v[194:197], v162
	ds_read_b128 v[198:201], v162 offset:1024
	ds_read_b128 v[206:209], v162 offset:2048
	ds_read_b128 v[160:163], v162 offset:3072
	s_barrier
	s_waitcnt lgkmcnt(0)
	s_setprio 1
	s_waitcnt lgkmcnt(0)
	v_mfma_f32_16x16x32_bf16 v[66:69], v[146:149], v[194:197], v[66:69]
	v_mfma_f32_16x16x32_bf16 v[54:57], v[146:149], v[206:209], v[54:57]
	v_mfma_f32_16x16x32_bf16 v[46:49], v[170:173], v[194:197], v[46:49]
	v_mfma_f32_16x16x32_bf16 v[38:41], v[170:173], v[206:209], v[38:41]
	v_mfma_f32_16x16x32_bf16 v[34:37], v[178:181], v[194:197], v[34:37]
	v_mfma_f32_16x16x32_bf16 v[22:25], v[178:181], v[206:209], v[22:25]
	v_mfma_f32_16x16x32_bf16 v[14:17], v[186:189], v[194:197], v[14:17]
	v_mfma_f32_16x16x32_bf16 v[6:9], v[186:189], v[206:209], v[6:9]
	v_mfma_f32_16x16x32_bf16 v[66:69], v[156:159], v[198:201], v[66:69]
	v_mfma_f32_16x16x32_bf16 v[54:57], v[156:159], v[160:163], v[54:57]
	v_mfma_f32_16x16x32_bf16 v[46:49], v[174:177], v[198:201], v[46:49]
	v_mfma_f32_16x16x32_bf16 v[38:41], v[174:177], v[160:163], v[38:41]
	v_mfma_f32_16x16x32_bf16 v[34:37], v[182:185], v[198:201], v[34:37]
	v_mfma_f32_16x16x32_bf16 v[22:25], v[182:185], v[160:163], v[22:25]
	v_mfma_f32_16x16x32_bf16 v[14:17], v[190:193], v[198:201], v[14:17]
	v_mfma_f32_16x16x32_bf16 v[6:9], v[190:193], v[160:163], v[6:9]
	s_setprio 0
	s_barrier
	ds_read_b128 v[146:149], v150 offset:16384
	ds_read_b128 v[156:159], v150 offset:17408
	ds_read_b128 v[168:171], v164 offset:16384
	ds_read_b128 v[172:175], v164 offset:17408
	ds_read_b128 v[176:179], v165 offset:16384
	ds_read_b128 v[180:183], v165 offset:17408
	ds_read_b128 v[184:187], v166 offset:16384
	ds_read_b128 v[188:191], v166 offset:17408
	s_waitcnt vmcnt(4)
	s_barrier
	s_waitcnt lgkmcnt(0)
	s_setprio 1
	s_waitcnt lgkmcnt(0)
	v_mfma_f32_16x16x32_bf16 v[122:125], v[146:149], v[130:133], v[122:125]
	v_mfma_f32_16x16x32_bf16 v[114:117], v[146:149], v[138:141], v[114:117]
	v_mfma_f32_16x16x32_bf16 v[106:109], v[168:171], v[130:133], v[106:109]
	v_mfma_f32_16x16x32_bf16 v[94:97], v[168:171], v[138:141], v[94:97]
	v_mfma_f32_16x16x32_bf16 v[90:93], v[176:179], v[130:133], v[90:93]
	v_mfma_f32_16x16x32_bf16 v[82:85], v[176:179], v[138:141], v[82:85]
	v_mfma_f32_16x16x32_bf16 v[74:77], v[184:187], v[130:133], v[74:77]
	v_mfma_f32_16x16x32_bf16 v[62:65], v[184:187], v[138:141], v[62:65]
	v_mfma_f32_16x16x32_bf16 v[122:125], v[156:159], v[134:137], v[122:125]
	v_mfma_f32_16x16x32_bf16 v[114:117], v[156:159], v[142:145], v[114:117]
	v_mfma_f32_16x16x32_bf16 v[106:109], v[172:175], v[134:137], v[106:109]
	v_mfma_f32_16x16x32_bf16 v[94:97], v[172:175], v[142:145], v[94:97]
	v_mfma_f32_16x16x32_bf16 v[90:93], v[180:183], v[134:137], v[90:93]
	v_mfma_f32_16x16x32_bf16 v[82:85], v[180:183], v[142:145], v[82:85]
	v_mfma_f32_16x16x32_bf16 v[74:77], v[188:191], v[134:137], v[74:77]
	v_mfma_f32_16x16x32_bf16 v[62:65], v[188:191], v[142:145], v[62:65]
	s_setprio 0
	s_setprio 1
	v_mfma_f32_16x16x32_bf16 v[58:61], v[146:149], v[194:197], v[58:61]
	v_mfma_f32_16x16x32_bf16 v[50:53], v[146:149], v[206:209], v[50:53]
	v_mfma_f32_16x16x32_bf16 v[42:45], v[168:171], v[194:197], v[42:45]
	v_mfma_f32_16x16x32_bf16 v[30:33], v[168:171], v[206:209], v[30:33]
	v_mfma_f32_16x16x32_bf16 v[26:29], v[176:179], v[194:197], v[26:29]
	v_mfma_f32_16x16x32_bf16 v[18:21], v[176:179], v[206:209], v[18:21]
	v_mfma_f32_16x16x32_bf16 v[10:13], v[184:187], v[194:197], v[10:13]
	v_mfma_f32_16x16x32_bf16 v[2:5], v[184:187], v[206:209], v[2:5]
	v_mfma_f32_16x16x32_bf16 v[58:61], v[156:159], v[198:201], v[58:61]
	v_mfma_f32_16x16x32_bf16 v[50:53], v[156:159], v[160:163], v[50:53]
	v_mfma_f32_16x16x32_bf16 v[42:45], v[172:175], v[198:201], v[42:45]
	v_mfma_f32_16x16x32_bf16 v[30:33], v[172:175], v[160:163], v[30:33]
	v_mfma_f32_16x16x32_bf16 v[26:29], v[180:183], v[198:201], v[26:29]
	v_mfma_f32_16x16x32_bf16 v[18:21], v[180:183], v[160:163], v[18:21]
	v_mfma_f32_16x16x32_bf16 v[10:13], v[188:191], v[198:201], v[10:13]
	v_mfma_f32_16x16x32_bf16 v[2:5], v[188:191], v[160:163], v[2:5]
	s_setprio 0
	s_barrier
	ds_read_b128 v[130:133], v154
	ds_read_b128 v[134:137], v154 offset:1024
	ds_read_b128 v[138:141], v154 offset:2048
	ds_read_b128 v[142:145], v154 offset:3072
	ds_read_b128 v[146:149], v150 offset:32768
	ds_read_b128 v[154:157], v150 offset:33792
	ds_read_b128 v[158:161], v164 offset:32768
	ds_read_b128 v[168:171], v164 offset:33792
	ds_read_b128 v[172:175], v165 offset:32768
	ds_read_b128 v[176:179], v165 offset:33792
	ds_read_b128 v[180:183], v166 offset:32768
	ds_read_b128 v[184:187], v166 offset:33792
	s_waitcnt vmcnt(2)
	s_barrier
; #define LDA(dst, b, h) for (int m = 0; m < 4; ++m) for (int k = 0; k < 2; ++k) \
;     dst[m][k] = *reinterpret_cast<const bf16x8*>((char*)SA(b, h) + lds_byte(wr * 64 + m * 16 + fr, k * 32 + fq * 8))
; #define LDB(dst, b, h) for (int n = 0; n < 2; ++n) for (int k = 0; k < 2; ++k) \
;     dst[n][k] = *reinterpret_cast<const bf16x8*>((char*)SB(b, h) + lds_byte(wc * 32 + n * 16 + fr, k * 32 + fq * 8))
; #define MMA(ai, bj, At_, Bt_) do { __builtin_amdgcn_s_setprio(1); \
;     for (int m = 0; m < 4; ++m) for (int n = 0; n < 2; ++n) for (int k = 0; k < 2; ++k) \
;       acc[ai][bj][m][n] = MFMA16(At_[m][k], Bt_[n][k], acc[ai][bj][m][n]); \
;     __builtin_amdgcn_s_setprio(0); } while (0)
; #define WAIT_V(n) asm volatile("s_waitcnt vmcnt(" #n ")" ::: "memory")
; #define WAIT_L(n) asm volatile("s_waitcnt lgkmcnt(" #n ")" ::: "memory")
; #define BAR __builtin_amdgcn_s_barrier()
; DI void gemm_core(WVP char* smem, const u16* __restrict__ A, int lda, int ar0, int ar1,
;                   const u16* __restrict__ B, int ldb, int bc0, int K, AccT& acc) {
;     ...
;   { LDB(B0, 1, 0); LDA(At, 1, 0); WAIT_V(2); BAR; WAIT_L(0); MMA(0, 0, At, B0); BAR;
;     LDB(B1, 1, 1); WAIT_V(0); BAR; WAIT_L(0); MMA(0, 1, At, B1); BAR;
;     LDA(At, 1, 1); BAR; WAIT_L(0); MMA(1, 0, At, B0); MMA(1, 1, At, B1); BAR; }
;   if (wr == 0) BAR;
	s_waitcnt lgkmcnt(0)
	s_setprio 1
	s_waitcnt lgkmcnt(0)
	v_mfma_f32_16x16x32_bf16 v[126:129], v[146:149], v[130:133], v[126:129]
	v_mfma_f32_16x16x32_bf16 v[118:121], v[146:149], v[138:141], v[118:121]
	v_mfma_f32_16x16x32_bf16 v[110:113], v[158:161], v[130:133], v[110:113]
	v_mfma_f32_16x16x32_bf16 v[102:105], v[158:161], v[138:141], v[102:105]
	v_mfma_f32_16x16x32_bf16 v[98:101], v[172:175], v[130:133], v[98:101]
	v_mfma_f32_16x16x32_bf16 v[86:89], v[172:175], v[138:141], v[86:89]
	v_mfma_f32_16x16x32_bf16 v[78:81], v[180:183], v[130:133], v[78:81]
	v_mfma_f32_16x16x32_bf16 v[70:73], v[180:183], v[138:141], v[70:73]
	v_mfma_f32_16x16x32_bf16 v[126:129], v[154:157], v[134:137], v[126:129]
	v_mfma_f32_16x16x32_bf16 v[118:121], v[154:157], v[142:145], v[118:121]
	v_mfma_f32_16x16x32_bf16 v[110:113], v[168:171], v[134:137], v[110:113]
	v_mfma_f32_16x16x32_bf16 v[102:105], v[168:171], v[142:145], v[102:105]
	v_mfma_f32_16x16x32_bf16 v[98:101], v[176:179], v[134:137], v[98:101]
	v_mfma_f32_16x16x32_bf16 v[86:89], v[176:179], v[142:145], v[86:89]
	v_mfma_f32_16x16x32_bf16 v[78:81], v[184:187], v[134:137], v[78:81]
	v_mfma_f32_16x16x32_bf16 v[70:73], v[184:187], v[142:145], v[70:73]
	s_setprio 0
	s_barrier
	ds_read_b128 v[188:191], v153
	ds_read_b128 v[192:195], v153 offset:1024
	ds_read_b128 v[196:199], v153 offset:2048
	ds_read_b128 v[200:203], v153 offset:3072
	s_waitcnt vmcnt(0)
	s_barrier
	s_waitcnt lgkmcnt(0)
	s_setprio 1
	s_waitcnt lgkmcnt(0)
	v_mfma_f32_16x16x32_bf16 v[66:69], v[146:149], v[188:191], v[66:69]
	v_mfma_f32_16x16x32_bf16 v[54:57], v[146:149], v[196:199], v[54:57]
	v_mfma_f32_16x16x32_bf16 v[46:49], v[158:161], v[188:191], v[46:49]
	v_mfma_f32_16x16x32_bf16 v[38:41], v[158:161], v[196:199], v[38:41]
	v_mfma_f32_16x16x32_bf16 v[34:37], v[172:175], v[188:191], v[34:37]
	v_mfma_f32_16x16x32_bf16 v[22:25], v[172:175], v[196:199], v[22:25]
	v_mfma_f32_16x16x32_bf16 v[14:17], v[180:183], v[188:191], v[14:17]
	v_mfma_f32_16x16x32_bf16 v[6:9], v[180:183], v[196:199], v[6:9]
	v_mfma_f32_16x16x32_bf16 v[66:69], v[154:157], v[192:195], v[66:69]
	v_mfma_f32_16x16x32_bf16 v[54:57], v[154:157], v[200:203], v[54:57]
	v_mfma_f32_16x16x32_bf16 v[46:49], v[168:171], v[192:195], v[46:49]
	v_mfma_f32_16x16x32_bf16 v[38:41], v[168:171], v[200:203], v[38:41]
	v_mfma_f32_16x16x32_bf16 v[34:37], v[176:179], v[192:195], v[34:37]
	v_mfma_f32_16x16x32_bf16 v[22:25], v[176:179], v[200:203], v[22:25]
	v_mfma_f32_16x16x32_bf16 v[14:17], v[184:187], v[192:195], v[14:17]
	v_mfma_f32_16x16x32_bf16 v[6:9], v[184:187], v[200:203], v[6:9]
	s_setprio 0
	s_barrier
	ds_read_b128 v[146:149], v150 offset:49152
	ds_read_b128 v[150:153], v150 offset:50176
	ds_read_b128 v[154:157], v164 offset:49152
	ds_read_b128 v[158:161], v164 offset:50176
	ds_read_b128 v[168:171], v165 offset:49152
	ds_read_b128 v[162:165], v165 offset:50176
	ds_read_b128 v[172:175], v166 offset:49152
	ds_read_b128 v[176:179], v166 offset:50176
	s_barrier
	s_waitcnt lgkmcnt(0)
	s_setprio 1
	s_waitcnt lgkmcnt(0)
	v_mfma_f32_16x16x32_bf16 v[122:125], v[146:149], v[130:133], v[122:125]
	v_mfma_f32_16x16x32_bf16 v[114:117], v[146:149], v[138:141], v[114:117]
	v_mfma_f32_16x16x32_bf16 v[106:109], v[154:157], v[130:133], v[106:109]
	v_mfma_f32_16x16x32_bf16 v[94:97], v[154:157], v[138:141], v[94:97]
	v_mfma_f32_16x16x32_bf16 v[90:93], v[168:171], v[130:133], v[90:93]
	v_mfma_f32_16x16x32_bf16 v[82:85], v[168:171], v[138:141], v[82:85]
	v_mfma_f32_16x16x32_bf16 v[74:77], v[172:175], v[130:133], v[74:77]
	v_mfma_f32_16x16x32_bf16 v[62:65], v[172:175], v[138:141], v[62:65]
	v_mfma_f32_16x16x32_bf16 v[122:125], v[150:153], v[134:137], v[122:125]
	v_mfma_f32_16x16x32_bf16 v[114:117], v[150:153], v[142:145], v[114:117]
	v_mfma_f32_16x16x32_bf16 v[106:109], v[158:161], v[134:137], v[106:109]
	v_mfma_f32_16x16x32_bf16 v[94:97], v[158:161], v[142:145], v[94:97]
	v_mfma_f32_16x16x32_bf16 v[90:93], v[162:165], v[134:137], v[90:93]
	v_mfma_f32_16x16x32_bf16 v[82:85], v[162:165], v[142:145], v[82:85]
	v_mfma_f32_16x16x32_bf16 v[74:77], v[176:179], v[134:137], v[74:77]
	v_mfma_f32_16x16x32_bf16 v[62:65], v[176:179], v[142:145], v[62:65]
	s_setprio 0
	s_setprio 1
	v_mfma_f32_16x16x32_bf16 v[58:61], v[146:149], v[188:191], v[58:61]
	v_mfma_f32_16x16x32_bf16 v[50:53], v[146:149], v[196:199], v[50:53]
	v_mfma_f32_16x16x32_bf16 v[42:45], v[154:157], v[188:191], v[42:45]
	v_mfma_f32_16x16x32_bf16 v[30:33], v[154:157], v[196:199], v[30:33]
	v_mfma_f32_16x16x32_bf16 v[26:29], v[168:171], v[188:191], v[26:29]
	v_mfma_f32_16x16x32_bf16 v[18:21], v[168:171], v[196:199], v[18:21]
	v_mfma_f32_16x16x32_bf16 v[10:13], v[172:175], v[188:191], v[10:13]
	v_mfma_f32_16x16x32_bf16 v[2:5], v[172:175], v[196:199], v[2:5]
	v_mfma_f32_16x16x32_bf16 v[58:61], v[150:153], v[192:195], v[58:61]
	v_mfma_f32_16x16x32_bf16 v[50:53], v[150:153], v[200:203], v[50:53]
	v_mfma_f32_16x16x32_bf16 v[42:45], v[158:161], v[192:195], v[42:45]
	v_mfma_f32_16x16x32_bf16 v[30:33], v[158:161], v[200:203], v[30:33]
	v_mfma_f32_16x16x32_bf16 v[26:29], v[162:165], v[192:195], v[26:29]
	v_mfma_f32_16x16x32_bf16 v[18:21], v[162:165], v[200:203], v[18:21]
	v_mfma_f32_16x16x32_bf16 v[10:13], v[176:179], v[192:195], v[10:13]
	v_mfma_f32_16x16x32_bf16 v[2:5], v[176:179], v[200:203], v[2:5]
	s_setprio 0
	s_cmp_gt_u32 s35, 3
	s_barrier
	s_cbranch_scc0 .LBB0_240
	s_cmp_eq_u32 s34, 3
	s_cbranch_scc1 .LBB0_233
	s_branch .LBB0_241

; #define STAGE_A(P, br, kt) do { const char* _g = (const char*)(A + (long)(br) * lda + (long)(kt) * BK); \
;     __builtin_amdgcn_global_load_lds((const unsigned*)(_g + (size_t)offA0), (unsigned*)((char*)(P) + sb0), 16, 0, 0); \
;     __builtin_amdgcn_global_load_lds((const unsigned*)(_g + (size_t)lda * 128 + (size_t)offA0), (unsigned*)((char*)(P) + sb1), 16, 0, 0); } while (0)
; #define STAGE_B(P, br, kt) do { const char* _g = (const char*)(B + (long)(br) * ldb + (long)(kt) * BK); \
;     __builtin_amdgcn_global_load_lds((const unsigned*)(_g + (size_t)offB0), (unsigned*)((char*)(P) + sb0), 16, 0, 0); \
;     __builtin_amdgcn_global_load_lds((const unsigned*)(_g + (size_t)ldb * 128 + (size_t)offB0), (unsigned*)((char*)(P) + sb1), 16, 0, 0); } while (0)
; #define LDA(dst, b, h) for (int m = 0; m < 4; ++m) for (int k = 0; k < 2; ++k) \
;     dst[m][k] = *reinterpret_cast<const bf16x8*>((char*)SA(b, h) + lds_byte(wr * 64 + m * 16 + fr, k * 32 + fq * 8))
; #define LDB(dst, b, h) for (int n = 0; n < 2; ++n) for (int k = 0; k < 2; ++k) \
;     dst[n][k] = *reinterpret_cast<const bf16x8*>((char*)SB(b, h) + lds_byte(wc * 32 + n * 16 + fr, k * 32 + fq * 8))
; #define MMA(ai, bj, At_, Bt_) do { __builtin_amdgcn_s_setprio(1); \
;     for (int m = 0; m < 4; ++m) for (int n = 0; n < 2; ++n) for (int k = 0; k < 2; ++k) \
;       acc[ai][bj][m][n] = MFMA16(At_[m][k], Bt_[n][k], acc[ai][bj][m][n]); \
;     __builtin_amdgcn_s_setprio(0); } while (0)
; #define WAIT_V(n) asm volatile("s_waitcnt vmcnt(" #n ")" ::: "memory")
; #define WAIT_L(n) asm volatile("s_waitcnt lgkmcnt(" #n ")" ::: "memory")
; #define BAR __builtin_amdgcn_s_barrier()
; #define SCHED __builtin_amdgcn_sched_barrier(0)
; DI void gemm_core(WVP char* smem, const u16* __restrict__ A, int lda, int ar0, int ar1,
;                   const u16* __restrict__ B, int ldb, int bc0, int K, AccT& acc) {
;     ...
;   for (int t = 0; t < nt - 2; t += 2) {
;     LDB(B0, 0, 0); SCHED; LDA(At, 0, 0); STAGE_A(SA(1, 1), ac1, t + 1);
;     WAIT_L(8); BAR; WAIT_L(0); MMA(0, 0, At, B0); BAR; SCHED;
;     LDB(B1, 0, 1); STAGE_B(SB(0, 0), bb0, t + 2);
;     BAR; WAIT_L(0); MMA(0, 1, At, B1); BAR;
;     LDA(At, 0, 1); STAGE_A(SA(0, 0), ac0, t + 2);
;     BAR; WAIT_L(0); MMA(1, 0, At, B0); BAR; SCHED;
;     STAGE_B(SB(0, 1), bb1, t + 2);
;     WAIT_V(6); BAR; MMA(1, 1, At, B1); BAR;
.LBB0_273:
	v_add_u32_e32 v155, s0, v153
	v_add_u32_e32 v156, s1, v153
	v_add_u32_e32 v157, s19, v153
	ds_read_b128 v[160:163], v154
	ds_read_b128 v[164:167], v154 offset:1024
	ds_read_b128 v[168:171], v154 offset:2048
	ds_read_b128 v[172:175], v154 offset:3072
	ds_read_b128 v[176:179], v0
	ds_read_b128 v[180:183], v0 offset:1024
	ds_read_b128 v[184:187], v155
	ds_read_b128 v[188:191], v155 offset:1024
	ds_read_b128 v[192:195], v156
	ds_read_b128 v[196:199], v156 offset:1024
	ds_read_b128 v[200:203], v157
	ds_read_b128 v[206:209], v157 offset:1024
	ds_read_b128 v[210:213], v151
	ds_read_b128 v[214:217], v151 offset:1024
	ds_read_b128 v[218:221], v151 offset:2048
	ds_read_b128 v[222:225], v151 offset:3072
	v_add_u32_e32 v158, 0xc000, v140
	v_lshl_add_u64 v[228:229], s[10:11], 0, v[136:137]
	s_mov_b64 s[14:15], 0x1f900080
	v_lshl_add_u64 v[226:227], v[228:229], 0, s[14:15]
	v_readfirstlane_b32 s13, v158
	s_mov_b32 m0, s13
	s_nop 0
	global_load_lds_dwordx4 v[226:227], off
	v_add_u32_e32 v159, 0xe000, v140
	v_lshl_add_u64 v[228:229], s[10:11], 0, v[136:137]
	s_mov_b64 s[14:15], 0x1f910080
	v_lshl_add_u64 v[226:227], v[228:229], 0, s[14:15]
	v_readfirstlane_b32 s13, v159
	s_mov_b32 m0, s13
	s_nop 0
	global_load_lds_dwordx4 v[226:227], off
	s_waitcnt vmcnt(8)
	s_waitcnt lgkmcnt(0)
	s_barrier
	v_mfma_f32_16x16x32_bf16 v[126:129], v[176:179], v[160:163], v[126:129]
	v_mfma_f32_16x16x32_bf16 v[126:129], v[180:183], v[164:167], v[126:129]
	v_mfma_f32_16x16x32_bf16 v[122:125], v[176:179], v[168:171], v[122:125]
	v_mfma_f32_16x16x32_bf16 v[122:125], v[180:183], v[172:175], v[122:125]
	v_mfma_f32_16x16x32_bf16 v[118:121], v[184:187], v[160:163], v[118:121]
	v_mfma_f32_16x16x32_bf16 v[118:121], v[188:191], v[164:167], v[118:121]
	v_mfma_f32_16x16x32_bf16 v[114:117], v[184:187], v[168:171], v[114:117]
	v_mfma_f32_16x16x32_bf16 v[114:117], v[188:191], v[172:175], v[114:117]
	v_mfma_f32_16x16x32_bf16 v[110:113], v[192:195], v[160:163], v[110:113]
	v_mfma_f32_16x16x32_bf16 v[110:113], v[196:199], v[164:167], v[110:113]
	v_mfma_f32_16x16x32_bf16 v[106:109], v[192:195], v[168:171], v[106:109]
	v_mfma_f32_16x16x32_bf16 v[106:109], v[196:199], v[172:175], v[106:109]
	v_mfma_f32_16x16x32_bf16 v[102:105], v[200:203], v[160:163], v[102:105]
	v_mfma_f32_16x16x32_bf16 v[102:105], v[206:209], v[164:167], v[102:105]
	v_mfma_f32_16x16x32_bf16 v[98:101], v[200:203], v[168:171], v[98:101]
	v_mfma_f32_16x16x32_bf16 v[98:101], v[206:209], v[172:175], v[98:101]
	v_mfma_f32_16x16x32_bf16 v[94:97], v[176:179], v[210:213], v[94:97]
	v_mfma_f32_16x16x32_bf16 v[94:97], v[180:183], v[214:217], v[94:97]
	v_mfma_f32_16x16x32_bf16 v[90:93], v[176:179], v[218:221], v[90:93]
	v_mfma_f32_16x16x32_bf16 v[90:93], v[180:183], v[222:225], v[90:93]
	v_mfma_f32_16x16x32_bf16 v[86:89], v[184:187], v[210:213], v[86:89]
	v_mfma_f32_16x16x32_bf16 v[86:89], v[188:191], v[214:217], v[86:89]
	v_mfma_f32_16x16x32_bf16 v[82:85], v[184:187], v[218:221], v[82:85]
	v_mfma_f32_16x16x32_bf16 v[82:85], v[188:191], v[222:225], v[82:85]
	v_mfma_f32_16x16x32_bf16 v[78:81], v[192:195], v[210:213], v[78:81]
	v_mfma_f32_16x16x32_bf16 v[78:81], v[196:199], v[214:217], v[78:81]
	v_mfma_f32_16x16x32_bf16 v[74:77], v[192:195], v[218:221], v[74:77]
	v_mfma_f32_16x16x32_bf16 v[74:77], v[196:199], v[222:225], v[74:77]
	v_mfma_f32_16x16x32_bf16 v[70:73], v[200:203], v[210:213], v[70:73]
	v_mfma_f32_16x16x32_bf16 v[70:73], v[206:209], v[214:217], v[70:73]
	v_mfma_f32_16x16x32_bf16 v[66:69], v[200:203], v[218:221], v[66:69]
	v_mfma_f32_16x16x32_bf16 v[66:69], v[206:209], v[222:225], v[66:69]
	s_barrier
	ds_read_b128 v[176:179], v0 offset:16384
	ds_read_b128 v[180:183], v0 offset:17408
	ds_read_b128 v[184:187], v155 offset:16384
	ds_read_b128 v[188:191], v155 offset:17408
	ds_read_b128 v[192:195], v156 offset:16384
	ds_read_b128 v[196:199], v156 offset:17408
	ds_read_b128 v[200:203], v157 offset:16384
	ds_read_b128 v[206:209], v157 offset:17408
	v_lshl_add_u64 v[228:229], s[10:11], 0, v[132:133]
	s_mov_b64 s[14:15], 0x2300
	v_lshl_add_u64 v[226:227], v[228:229], 0, s[14:15]
	v_readfirstlane_b32 s13, v138
	s_mov_b32 m0, s13
	s_nop 0
	global_load_lds_dwordx4 v[226:227], off
	v_add_u32_e32 v205, 0x2000, v138
	v_lshl_add_u64 v[228:229], s[10:11], 0, v[132:133]
	s_mov_b64 s[14:15], 0x9a300
	v_lshl_add_u64 v[226:227], v[228:229], 0, s[14:15]
	v_readfirstlane_b32 s13, v205
	s_mov_b32 m0, s13
	s_nop 0
	global_load_lds_dwordx4 v[226:227], off
	v_lshl_add_u64 v[228:229], s[10:11], 0, v[134:135]
	v_lshl_add_u64 v[226:227], v[228:229], 0, s[20:21]
	v_readfirstlane_b32 s13, v140
	s_mov_b32 m0, s13
	s_nop 0
	global_load_lds_dwordx4 v[226:227], off
	v_lshl_add_u64 v[228:229], s[10:11], 0, v[134:135]
	v_lshl_add_u64 v[226:227], v[228:229], 0, s[22:23]
	v_readfirstlane_b32 s13, v141
	s_mov_b32 m0, s13
	s_nop 0
	global_load_lds_dwordx4 v[226:227], off
	v_lshl_add_u64 v[228:229], s[10:11], 0, v[132:133]
	s_mov_b64 s[14:15], 0x132300
	v_lshl_add_u64 v[226:227], v[228:229], 0, s[14:15]
	v_readfirstlane_b32 s13, v143
	s_mov_b32 m0, s13
	s_nop 0
	global_load_lds_dwordx4 v[226:227], off
	v_add_u32_e32 v230, 0x2000, v143
	v_lshl_add_u64 v[228:229], s[10:11], 0, v[132:133]
	s_mov_b64 s[14:15], 0x1ca300
	v_lshl_add_u64 v[226:227], v[228:229], 0, s[14:15]
	v_readfirstlane_b32 s13, v230
	s_mov_b32 m0, s13
	s_nop 0
	global_load_lds_dwordx4 v[226:227], off
	s_waitcnt vmcnt(8)
	s_waitcnt lgkmcnt(0)
	s_barrier
; #define STAGE_A(P, br, kt) do { const char* _g = (const char*)(A + (long)(br) * lda + (long)(kt) * BK); \
;     __builtin_amdgcn_global_load_lds((const unsigned*)(_g + (size_t)offA0), (unsigned*)((char*)(P) + sb0), 16, 0, 0); \
;     __builtin_amdgcn_global_load_lds((const unsigned*)(_g + (size_t)lda * 128 + (size_t)offA0), (unsigned*)((char*)(P) + sb1), 16, 0, 0); } while (0)
; #define STAGE_B(P, br, kt) do { const char* _g = (const char*)(B + (long)(br) * ldb + (long)(kt) * BK); \
;     __builtin_amdgcn_global_load_lds((const unsigned*)(_g + (size_t)offB0), (unsigned*)((char*)(P) + sb0), 16, 0, 0); \
;     __builtin_amdgcn_global_load_lds((const unsigned*)(_g + (size_t)ldb * 128 + (size_t)offB0), (unsigned*)((char*)(P) + sb1), 16, 0, 0); } while (0)
; #define LDA(dst, b, h) for (int m = 0; m < 4; ++m) for (int k = 0; k < 2; ++k) \
;     dst[m][k] = *reinterpret_cast<const bf16x8*>((char*)SA(b, h) + lds_byte(wr * 64 + m * 16 + fr, k * 32 + fq * 8))
; #define LDB(dst, b, h) for (int n = 0; n < 2; ++n) for (int k = 0; k < 2; ++k) \
;     dst[n][k] = *reinterpret_cast<const bf16x8*>((char*)SB(b, h) + lds_byte(wc * 32 + n * 16 + fr, k * 32 + fq * 8))
; #define MMA(ai, bj, At_, Bt_) do { __builtin_amdgcn_s_setprio(1); \
;     for (int m = 0; m < 4; ++m) for (int n = 0; n < 2; ++n) for (int k = 0; k < 2; ++k) \
;       acc[ai][bj][m][n] = MFMA16(At_[m][k], Bt_[n][k], acc[ai][bj][m][n]); \
;     __builtin_amdgcn_s_setprio(0); } while (0)
; #define WAIT_V(n) asm volatile("s_waitcnt vmcnt(" #n ")" ::: "memory")
; #define WAIT_L(n) asm volatile("s_waitcnt lgkmcnt(" #n ")" ::: "memory")
; #define BAR __builtin_amdgcn_s_barrier()
; #define SCHED __builtin_amdgcn_sched_barrier(0)
; DI void gemm_core(WVP char* smem, const u16* __restrict__ A, int lda, int ar0, int ar1,
;                   const u16* __restrict__ B, int ldb, int bc0, int K, AccT& acc) {
;     ...
;     BAR; WAIT_L(0); MMA(1, 0, At, B0); BAR; SCHED;
;     STAGE_B(SB(0, 1), bb1, t + 2);
;     WAIT_V(6); BAR; MMA(1, 1, At, B1); BAR;
;     LDB(B0, 1, 0); SCHED; LDA(At, 1, 0); STAGE_A(SA(0, 1), ac1, t + 2);
;     WAIT_L(8); BAR; WAIT_L(0); MMA(0, 0, At, B0); BAR; SCHED;
;     LDB(B1, 1, 1); STAGE_B(SB(1, 0), bb0, t + 3);
;     BAR; WAIT_L(0); MMA(0, 1, At, B1); BAR;
	v_mfma_f32_16x16x32_bf16 v[62:65], v[176:179], v[160:163], v[62:65]
	v_mfma_f32_16x16x32_bf16 v[62:65], v[180:183], v[164:167], v[62:65]
	v_mfma_f32_16x16x32_bf16 v[58:61], v[176:179], v[168:171], v[58:61]
	v_mfma_f32_16x16x32_bf16 v[58:61], v[180:183], v[172:175], v[58:61]
	v_mfma_f32_16x16x32_bf16 v[54:57], v[184:187], v[160:163], v[54:57]
	v_mfma_f32_16x16x32_bf16 v[54:57], v[188:191], v[164:167], v[54:57]
	v_mfma_f32_16x16x32_bf16 v[50:53], v[184:187], v[168:171], v[50:53]
	v_mfma_f32_16x16x32_bf16 v[50:53], v[188:191], v[172:175], v[50:53]
	v_mfma_f32_16x16x32_bf16 v[46:49], v[192:195], v[160:163], v[46:49]
	v_mfma_f32_16x16x32_bf16 v[46:49], v[196:199], v[164:167], v[46:49]
	v_mfma_f32_16x16x32_bf16 v[42:45], v[192:195], v[168:171], v[42:45]
	v_mfma_f32_16x16x32_bf16 v[42:45], v[196:199], v[172:175], v[42:45]
	v_mfma_f32_16x16x32_bf16 v[38:41], v[200:203], v[160:163], v[38:41]
	v_mfma_f32_16x16x32_bf16 v[38:41], v[206:209], v[164:167], v[38:41]
	v_mfma_f32_16x16x32_bf16 v[34:37], v[200:203], v[168:171], v[34:37]
	v_mfma_f32_16x16x32_bf16 v[34:37], v[206:209], v[172:175], v[34:37]
	v_mfma_f32_16x16x32_bf16 v[30:33], v[176:179], v[210:213], v[30:33]
	v_mfma_f32_16x16x32_bf16 v[30:33], v[180:183], v[214:217], v[30:33]
	v_mfma_f32_16x16x32_bf16 v[26:29], v[176:179], v[218:221], v[26:29]
	v_mfma_f32_16x16x32_bf16 v[26:29], v[180:183], v[222:225], v[26:29]
	v_mfma_f32_16x16x32_bf16 v[22:25], v[184:187], v[210:213], v[22:25]
	v_mfma_f32_16x16x32_bf16 v[22:25], v[188:191], v[214:217], v[22:25]
	v_mfma_f32_16x16x32_bf16 v[18:21], v[184:187], v[218:221], v[18:21]
	v_mfma_f32_16x16x32_bf16 v[18:21], v[188:191], v[222:225], v[18:21]
	v_mfma_f32_16x16x32_bf16 v[14:17], v[192:195], v[210:213], v[14:17]
	v_mfma_f32_16x16x32_bf16 v[14:17], v[196:199], v[214:217], v[14:17]
	v_mfma_f32_16x16x32_bf16 v[10:13], v[192:195], v[218:221], v[10:13]
	v_mfma_f32_16x16x32_bf16 v[10:13], v[196:199], v[222:225], v[10:13]
	v_mfma_f32_16x16x32_bf16 v[6:9], v[200:203], v[210:213], v[6:9]
	v_mfma_f32_16x16x32_bf16 v[6:9], v[206:209], v[214:217], v[6:9]
	v_mfma_f32_16x16x32_bf16 v[2:5], v[200:203], v[218:221], v[2:5]
	v_mfma_f32_16x16x32_bf16 v[2:5], v[206:209], v[222:225], v[2:5]
	s_barrier
	ds_read_b128 v[160:163], v142
	ds_read_b128 v[164:167], v142 offset:1024
	ds_read_b128 v[168:171], v142 offset:2048
	ds_read_b128 v[172:175], v142 offset:3072
	ds_read_b128 v[176:179], v0 offset:32768
	ds_read_b128 v[180:183], v0 offset:33792
	ds_read_b128 v[184:187], v155 offset:32768
	ds_read_b128 v[188:191], v155 offset:33792
	ds_read_b128 v[192:195], v156 offset:32768
	ds_read_b128 v[196:199], v156 offset:33792
	ds_read_b128 v[200:203], v157 offset:32768
	ds_read_b128 v[206:209], v157 offset:33792
	ds_read_b128 v[210:213], v139
	ds_read_b128 v[214:217], v139 offset:1024
	ds_read_b128 v[218:221], v139 offset:2048
	ds_read_b128 v[222:225], v139 offset:3072
	v_lshl_add_u64 v[228:229], s[10:11], 0, v[136:137]
	v_lshl_add_u64 v[226:227], v[228:229], 0, s[20:21]
	v_readfirstlane_b32 s13, v144
	s_mov_b32 m0, s13
	s_nop 0
	global_load_lds_dwordx4 v[226:227], off
	v_lshl_add_u64 v[228:229], s[10:11], 0, v[136:137]
	v_lshl_add_u64 v[226:227], v[228:229], 0, s[22:23]
	v_readfirstlane_b32 s13, v145
	s_mov_b32 m0, s13
	s_nop 0
	global_load_lds_dwordx4 v[226:227], off
	s_waitcnt vmcnt(8)
	s_waitcnt lgkmcnt(0)
	s_barrier
	v_mfma_f32_16x16x32_bf16 v[126:129], v[176:179], v[160:163], v[126:129]
	v_mfma_f32_16x16x32_bf16 v[126:129], v[180:183], v[164:167], v[126:129]
	v_mfma_f32_16x16x32_bf16 v[122:125], v[176:179], v[168:171], v[122:125]
	v_mfma_f32_16x16x32_bf16 v[122:125], v[180:183], v[172:175], v[122:125]
	v_mfma_f32_16x16x32_bf16 v[118:121], v[184:187], v[160:163], v[118:121]
	v_mfma_f32_16x16x32_bf16 v[118:121], v[188:191], v[164:167], v[118:121]
	v_mfma_f32_16x16x32_bf16 v[114:117], v[184:187], v[168:171], v[114:117]
	v_mfma_f32_16x16x32_bf16 v[114:117], v[188:191], v[172:175], v[114:117]
	v_mfma_f32_16x16x32_bf16 v[110:113], v[192:195], v[160:163], v[110:113]
	v_mfma_f32_16x16x32_bf16 v[110:113], v[196:199], v[164:167], v[110:113]
	v_mfma_f32_16x16x32_bf16 v[106:109], v[192:195], v[168:171], v[106:109]
	v_mfma_f32_16x16x32_bf16 v[106:109], v[196:199], v[172:175], v[106:109]
	v_mfma_f32_16x16x32_bf16 v[102:105], v[200:203], v[160:163], v[102:105]
	v_mfma_f32_16x16x32_bf16 v[102:105], v[206:209], v[164:167], v[102:105]
	v_mfma_f32_16x16x32_bf16 v[98:101], v[200:203], v[168:171], v[98:101]
	v_mfma_f32_16x16x32_bf16 v[98:101], v[206:209], v[172:175], v[98:101]
	v_mfma_f32_16x16x32_bf16 v[94:97], v[176:179], v[210:213], v[94:97]
	v_mfma_f32_16x16x32_bf16 v[94:97], v[180:183], v[214:217], v[94:97]
	v_mfma_f32_16x16x32_bf16 v[90:93], v[176:179], v[218:221], v[90:93]
	v_mfma_f32_16x16x32_bf16 v[90:93], v[180:183], v[222:225], v[90:93]
	v_mfma_f32_16x16x32_bf16 v[86:89], v[184:187], v[210:213], v[86:89]
	v_mfma_f32_16x16x32_bf16 v[86:89], v[188:191], v[214:217], v[86:89]
	v_mfma_f32_16x16x32_bf16 v[82:85], v[184:187], v[218:221], v[82:85]
	v_mfma_f32_16x16x32_bf16 v[82:85], v[188:191], v[222:225], v[82:85]
	v_mfma_f32_16x16x32_bf16 v[78:81], v[192:195], v[210:213], v[78:81]
	v_mfma_f32_16x16x32_bf16 v[78:81], v[196:199], v[214:217], v[78:81]
	v_mfma_f32_16x16x32_bf16 v[74:77], v[192:195], v[218:221], v[74:77]
	v_mfma_f32_16x16x32_bf16 v[74:77], v[196:199], v[222:225], v[74:77]
	v_mfma_f32_16x16x32_bf16 v[70:73], v[200:203], v[210:213], v[70:73]
	v_mfma_f32_16x16x32_bf16 v[70:73], v[206:209], v[214:217], v[70:73]
	v_mfma_f32_16x16x32_bf16 v[66:69], v[200:203], v[218:221], v[66:69]
	v_mfma_f32_16x16x32_bf16 v[66:69], v[206:209], v[222:225], v[66:69]
	s_barrier
; #define STAGE_A(P, br, kt) do { const char* _g = (const char*)(A + (long)(br) * lda + (long)(kt) * BK); \
;     __builtin_amdgcn_global_load_lds((const unsigned*)(_g + (size_t)offA0), (unsigned*)((char*)(P) + sb0), 16, 0, 0); \
;     __builtin_amdgcn_global_load_lds((const unsigned*)(_g + (size_t)lda * 128 + (size_t)offA0), (unsigned*)((char*)(P) + sb1), 16, 0, 0); } while (0)
; #define STAGE_B(P, br, kt) do { const char* _g = (const char*)(B + (long)(br) * ldb + (long)(kt) * BK); \
;     __builtin_amdgcn_global_load_lds((const unsigned*)(_g + (size_t)offB0), (unsigned*)((char*)(P) + sb0), 16, 0, 0); \
;     __builtin_amdgcn_global_load_lds((const unsigned*)(_g + (size_t)ldb * 128 + (size_t)offB0), (unsigned*)((char*)(P) + sb1), 16, 0, 0); } while (0)
; #define LDA(dst, b, h) for (int m = 0; m < 4; ++m) for (int k = 0; k < 2; ++k) \
;     dst[m][k] = *reinterpret_cast<const bf16x8*>((char*)SA(b, h) + lds_byte(wr * 64 + m * 16 + fr, k * 32 + fq * 8))
; #define LDB(dst, b, h) for (int n = 0; n < 2; ++n) for (int k = 0; k < 2; ++k) \
;     dst[n][k] = *reinterpret_cast<const bf16x8*>((char*)SB(b, h) + lds_byte(wc * 32 + n * 16 + fr, k * 32 + fq * 8))
; #define MMA(ai, bj, At_, Bt_) do { __builtin_amdgcn_s_setprio(1); \
;     for (int m = 0; m < 4; ++m) for (int n = 0; n < 2; ++n) for (int k = 0; k < 2; ++k) \
;       acc[ai][bj][m][n] = MFMA16(At_[m][k], Bt_[n][k], acc[ai][bj][m][n]); \
;     __builtin_amdgcn_s_setprio(0); } while (0)
; #define WAIT_V(n) asm volatile("s_waitcnt vmcnt(" #n ")" ::: "memory")
; #define WAIT_L(n) asm volatile("s_waitcnt lgkmcnt(" #n ")" ::: "memory")
; #define BAR __builtin_amdgcn_s_barrier()
; #define SCHED __builtin_amdgcn_sched_barrier(0)
; DI void gemm_core(WVP char* smem, const u16* __restrict__ A, int lda, int ar0, int ar1,
;                   const u16* __restrict__ B, int ldb, int bc0, int K, AccT& acc) {
;     ...
;     BAR; WAIT_L(0); MMA(0, 1, At, B1); BAR;
;     LDA(At, 1, 1); STAGE_A(SA(1, 0), ac0, t + 3);
;     BAR; WAIT_L(0); MMA(1, 0, At, B0); BAR; SCHED;
;     STAGE_B(SB(1, 1), bb1, t + 3);
;     WAIT_V(6); BAR; MMA(1, 1, At, B1); BAR;
;   }
;   { LDB(B0, 0, 0); LDA(At, 0, 0); STAGE_A(SA(1, 1), ac1, nt - 1);
;     BAR; WAIT_L(0); MMA(0, 0, At, B0); BAR;
;     LDB(B1, 0, 1); BAR; WAIT_L(0); MMA(0, 1, At, B1); BAR;
;     LDA(At, 0, 1); WAIT_V(4); BAR; WAIT_L(0); MMA(1, 0, At, B0); MMA(1, 1, At, B1); BAR; }
	ds_read_b128 v[176:179], v0 offset:49152
	ds_read_b128 v[180:183], v0 offset:50176
	ds_read_b128 v[184:187], v155 offset:49152
	ds_read_b128 v[188:191], v155 offset:50176
	ds_read_b128 v[192:195], v156 offset:49152
	ds_read_b128 v[196:199], v156 offset:50176
	ds_read_b128 v[200:203], v157 offset:49152
	ds_read_b128 v[206:209], v157 offset:50176
	v_lshl_add_u64 v[228:229], s[10:11], 0, v[132:133]
	s_mov_b64 s[14:15], 0x2380
	v_lshl_add_u64 v[226:227], v[228:229], 0, s[14:15]
	v_readfirstlane_b32 s13, v146
	s_mov_b32 m0, s13
	s_nop 0
	global_load_lds_dwordx4 v[226:227], off
	v_lshl_add_u64 v[228:229], s[10:11], 0, v[132:133]
	s_mov_b64 s[14:15], 0x9a380
	v_lshl_add_u64 v[226:227], v[228:229], 0, s[14:15]
	v_readfirstlane_b32 s13, v147
	s_mov_b32 m0, s13
	s_nop 0
	global_load_lds_dwordx4 v[226:227], off
	v_lshl_add_u64 v[228:229], s[10:11], 0, v[134:135]
	s_mov_b64 s[14:15], 0x1f900180
	v_lshl_add_u64 v[226:227], v[228:229], 0, s[14:15]
	v_readfirstlane_b32 s13, v148
	s_mov_b32 m0, s13
	s_nop 0
	global_load_lds_dwordx4 v[226:227], off
	v_lshl_add_u64 v[228:229], s[10:11], 0, v[134:135]
	s_mov_b64 s[14:15], 0x1f910180
	v_lshl_add_u64 v[226:227], v[228:229], 0, s[14:15]
	v_readfirstlane_b32 s13, v149
	s_mov_b32 m0, s13
	s_nop 0
	global_load_lds_dwordx4 v[226:227], off
	v_lshl_add_u64 v[228:229], s[10:11], 0, v[132:133]
	s_mov_b64 s[14:15], 0x132380
	v_lshl_add_u64 v[226:227], v[228:229], 0, s[14:15]
	v_readfirstlane_b32 s13, v150
	s_mov_b32 m0, s13
	s_nop 0
	global_load_lds_dwordx4 v[226:227], off
	v_lshl_add_u64 v[228:229], s[10:11], 0, v[132:133]
	s_mov_b64 s[14:15], 0x1ca380
	v_lshl_add_u64 v[226:227], v[228:229], 0, s[14:15]
	v_readfirstlane_b32 s13, v152
	s_mov_b32 m0, s13
	s_nop 0
	global_load_lds_dwordx4 v[226:227], off
	s_waitcnt vmcnt(8)
	s_waitcnt lgkmcnt(0)
	s_barrier
	v_mfma_f32_16x16x32_bf16 v[62:65], v[176:179], v[160:163], v[62:65]
	v_mfma_f32_16x16x32_bf16 v[62:65], v[180:183], v[164:167], v[62:65]
	v_mfma_f32_16x16x32_bf16 v[58:61], v[176:179], v[168:171], v[58:61]
	v_mfma_f32_16x16x32_bf16 v[58:61], v[180:183], v[172:175], v[58:61]
	v_mfma_f32_16x16x32_bf16 v[54:57], v[184:187], v[160:163], v[54:57]
	v_mfma_f32_16x16x32_bf16 v[54:57], v[188:191], v[164:167], v[54:57]
	v_mfma_f32_16x16x32_bf16 v[50:53], v[184:187], v[168:171], v[50:53]
	v_mfma_f32_16x16x32_bf16 v[50:53], v[188:191], v[172:175], v[50:53]
	v_mfma_f32_16x16x32_bf16 v[46:49], v[192:195], v[160:163], v[46:49]
	v_mfma_f32_16x16x32_bf16 v[46:49], v[196:199], v[164:167], v[46:49]
	v_mfma_f32_16x16x32_bf16 v[42:45], v[192:195], v[168:171], v[42:45]
	v_mfma_f32_16x16x32_bf16 v[42:45], v[196:199], v[172:175], v[42:45]
	v_mfma_f32_16x16x32_bf16 v[38:41], v[200:203], v[160:163], v[38:41]
	v_mfma_f32_16x16x32_bf16 v[38:41], v[206:209], v[164:167], v[38:41]
	v_mfma_f32_16x16x32_bf16 v[34:37], v[200:203], v[168:171], v[34:37]
	v_mfma_f32_16x16x32_bf16 v[34:37], v[206:209], v[172:175], v[34:37]
	v_mfma_f32_16x16x32_bf16 v[30:33], v[176:179], v[210:213], v[30:33]
	v_mfma_f32_16x16x32_bf16 v[30:33], v[180:183], v[214:217], v[30:33]
	v_mfma_f32_16x16x32_bf16 v[26:29], v[176:179], v[218:221], v[26:29]
	v_mfma_f32_16x16x32_bf16 v[26:29], v[180:183], v[222:225], v[26:29]
	v_mfma_f32_16x16x32_bf16 v[22:25], v[184:187], v[210:213], v[22:25]
	v_mfma_f32_16x16x32_bf16 v[22:25], v[188:191], v[214:217], v[22:25]
	v_mfma_f32_16x16x32_bf16 v[18:21], v[184:187], v[218:221], v[18:21]
	v_mfma_f32_16x16x32_bf16 v[18:21], v[188:191], v[222:225], v[18:21]
	v_mfma_f32_16x16x32_bf16 v[14:17], v[192:195], v[210:213], v[14:17]
	v_mfma_f32_16x16x32_bf16 v[14:17], v[196:199], v[214:217], v[14:17]
	v_mfma_f32_16x16x32_bf16 v[10:13], v[192:195], v[218:221], v[10:13]
	v_mfma_f32_16x16x32_bf16 v[10:13], v[196:199], v[222:225], v[10:13]
	v_mfma_f32_16x16x32_bf16 v[6:9], v[200:203], v[210:213], v[6:9]
	v_mfma_f32_16x16x32_bf16 v[6:9], v[206:209], v[214:217], v[6:9]
	v_mfma_f32_16x16x32_bf16 v[2:5], v[200:203], v[218:221], v[2:5]
	v_mfma_f32_16x16x32_bf16 v[2:5], v[206:209], v[222:225], v[2:5]
	s_add_i32 s12, s12, 2
	s_add_u32 s10, s10, 0x100
	s_addc_u32 s11, s11, 0
	s_cmp_lt_u32 s12, 4
	s_barrier
	s_cbranch_scc1 .LBB0_273
	s_mov_b64 s[0:1], 0x380
	v_lshl_add_u64 v[136:137], v[130:131], 0, s[0:1]
	v_readfirstlane_b32 s0, v158
	s_mov_b32 m0, s0
	s_mov_b64 s[0:1], 0x10380
	v_lshl_add_u64 v[130:131], v[130:131], 0, s[0:1]
	v_readfirstlane_b32 s0, v159
	ds_read_b128 v[132:135], v154
	ds_read_b128 v[144:147], v154 offset:1024
	ds_read_b128 v[160:163], v154 offset:2048
	ds_read_b128 v[164:167], v154 offset:3072
	ds_read_b128 v[168:171], v0
	ds_read_b128 v[172:175], v0 offset:1024
	ds_read_b128 v[176:179], v155
	ds_read_b128 v[180:183], v155 offset:1024
	ds_read_b128 v[184:187], v156
	ds_read_b128 v[188:191], v156 offset:1024
	ds_read_b128 v[192:195], v157
	ds_read_b128 v[196:199], v157 offset:1024
	global_load_lds_dwordx4 v[136:137], off
	s_mov_b32 m0, s0
	s_nop 0
	global_load_lds_dwordx4 v[130:131], off
	s_waitcnt vmcnt(8)
	s_barrier
	s_waitcnt lgkmcnt(0)
	s_setprio 1
	s_waitcnt lgkmcnt(0)
	v_mfma_f32_16x16x32_bf16 v[126:129], v[168:171], v[132:135], v[126:129]
	v_mfma_f32_16x16x32_bf16 v[122:125], v[168:171], v[160:163], v[122:125]
	v_mfma_f32_16x16x32_bf16 v[118:121], v[176:179], v[132:135], v[118:121]
	v_mfma_f32_16x16x32_bf16 v[110:113], v[184:187], v[132:135], v[110:113]
	v_mfma_f32_16x16x32_bf16 v[98:101], v[192:195], v[160:163], v[98:101]
	v_mfma_f32_16x16x32_bf16 v[126:129], v[172:175], v[144:147], v[126:129]
	v_mfma_f32_16x16x32_bf16 v[122:125], v[172:175], v[164:167], v[122:125]
	v_mfma_f32_16x16x32_bf16 v[118:121], v[180:183], v[144:147], v[118:121]
	v_mfma_f32_16x16x32_bf16 v[114:117], v[176:179], v[160:163], v[114:117]
	v_mfma_f32_16x16x32_bf16 v[110:113], v[188:191], v[144:147], v[110:113]
	v_mfma_f32_16x16x32_bf16 v[106:109], v[184:187], v[160:163], v[106:109]
	v_mfma_f32_16x16x32_bf16 v[102:105], v[192:195], v[132:135], v[102:105]
	v_mfma_f32_16x16x32_bf16 v[98:101], v[196:199], v[164:167], v[98:101]
	v_mfma_f32_16x16x32_bf16 v[200:203], v[180:183], v[164:167], v[114:117]
	v_mfma_f32_16x16x32_bf16 v[206:209], v[188:191], v[164:167], v[106:109]
	v_mfma_f32_16x16x32_bf16 v[210:213], v[196:199], v[144:147], v[102:105]
	s_setprio 0
	s_barrier
; #define STAGE_A(P, br, kt) do { const char* _g = (const char*)(A + (long)(br) * lda + (long)(kt) * BK); \
;     __builtin_amdgcn_global_load_lds((const unsigned*)(_g + (size_t)offA0), (unsigned*)((char*)(P) + sb0), 16, 0, 0); \
;     __builtin_amdgcn_global_load_lds((const unsigned*)(_g + (size_t)lda * 128 + (size_t)offA0), (unsigned*)((char*)(P) + sb1), 16, 0, 0); } while (0)
; #define LDA(dst, b, h) for (int m = 0; m < 4; ++m) for (int k = 0; k < 2; ++k) \
;     dst[m][k] = *reinterpret_cast<const bf16x8*>((char*)SA(b, h) + lds_byte(wr * 64 + m * 16 + fr, k * 32 + fq * 8))
; #define LDB(dst, b, h) for (int n = 0; n < 2; ++n) for (int k = 0; k < 2; ++k) \
;     dst[n][k] = *reinterpret_cast<const bf16x8*>((char*)SB(b, h) + lds_byte(wc * 32 + n * 16 + fr, k * 32 + fq * 8))
; #define MMA(ai, bj, At_, Bt_) do { __builtin_amdgcn_s_setprio(1); \
;     for (int m = 0; m < 4; ++m) for (int n = 0; n < 2; ++n) for (int k = 0; k < 2; ++k) \
;       acc[ai][bj][m][n] = MFMA16(At_[m][k], Bt_[n][k], acc[ai][bj][m][n]); \
;     __builtin_amdgcn_s_setprio(0); } while (0)
; #define WAIT_V(n) asm volatile("s_waitcnt vmcnt(" #n ")" ::: "memory")
; #define WAIT_L(n) asm volatile("s_waitcnt lgkmcnt(" #n ")" ::: "memory")
; #define BAR __builtin_amdgcn_s_barrier()
; DI void gemm_core(WVP char* smem, const u16* __restrict__ A, int lda, int ar0, int ar1,
;                   const u16* __restrict__ B, int ldb, int bc0, int K, AccT& acc) {
;     ...
;   { LDB(B0, 0, 0); LDA(At, 0, 0); STAGE_A(SA(1, 1), ac1, nt - 1);
;     BAR; WAIT_L(0); MMA(0, 0, At, B0); BAR;
;     LDB(B1, 0, 1); BAR; WAIT_L(0); MMA(0, 1, At, B1); BAR;
;     LDA(At, 0, 1); WAIT_V(4); BAR; WAIT_L(0); MMA(1, 0, At, B0); MMA(1, 1, At, B1); BAR; }
;   { LDB(B0, 1, 0); LDA(At, 1, 0); WAIT_V(2); BAR; WAIT_L(0); MMA(0, 0, At, B0); BAR;
	s_nop 1
	ds_read_b128 v[102:105], v151
	ds_read_b128 v[106:109], v151 offset:1024
	ds_read_b128 v[114:117], v151 offset:2048
	ds_read_b128 v[148:151], v151 offset:3072
	s_barrier
	s_waitcnt lgkmcnt(0)
	s_setprio 1
	s_waitcnt lgkmcnt(0)
	v_mfma_f32_16x16x32_bf16 v[90:93], v[168:171], v[114:117], v[90:93]
	v_mfma_f32_16x16x32_bf16 v[86:89], v[176:179], v[102:105], v[86:89]
	v_mfma_f32_16x16x32_bf16 v[78:81], v[184:187], v[102:105], v[78:81]
	v_mfma_f32_16x16x32_bf16 v[66:69], v[192:195], v[114:117], v[66:69]
	v_mfma_f32_16x16x32_bf16 v[94:97], v[168:171], v[102:105], v[94:97]
	v_mfma_f32_16x16x32_bf16 v[90:93], v[172:175], v[148:151], v[90:93]
	v_mfma_f32_16x16x32_bf16 v[86:89], v[180:183], v[106:109], v[86:89]
	v_mfma_f32_16x16x32_bf16 v[82:85], v[176:179], v[114:117], v[82:85]
	v_mfma_f32_16x16x32_bf16 v[78:81], v[188:191], v[106:109], v[78:81]
	v_mfma_f32_16x16x32_bf16 v[74:77], v[184:187], v[114:117], v[74:77]
	v_mfma_f32_16x16x32_bf16 v[70:73], v[192:195], v[102:105], v[70:73]
	v_mfma_f32_16x16x32_bf16 v[66:69], v[196:199], v[148:151], v[66:69]
	v_mfma_f32_16x16x32_bf16 v[214:217], v[172:175], v[106:109], v[94:97]
	v_mfma_f32_16x16x32_bf16 v[168:171], v[180:183], v[148:151], v[82:85]
	v_mfma_f32_16x16x32_bf16 v[172:175], v[188:191], v[148:151], v[74:77]
	v_mfma_f32_16x16x32_bf16 v[176:179], v[196:199], v[106:109], v[70:73]
	s_setprio 0
	s_barrier
	s_nop 0
	ds_read_b128 v[70:73], v0 offset:16384
	ds_read_b128 v[74:77], v0 offset:17408
	ds_read_b128 v[82:85], v155 offset:16384
	ds_read_b128 v[94:97], v155 offset:17408
	ds_read_b128 v[180:183], v156 offset:16384
	ds_read_b128 v[184:187], v156 offset:17408
	ds_read_b128 v[188:191], v157 offset:16384
	ds_read_b128 v[192:195], v157 offset:17408
	s_waitcnt vmcnt(4)
	s_barrier
	s_waitcnt lgkmcnt(0)
	s_setprio 1
	s_waitcnt lgkmcnt(0)
	v_mfma_f32_16x16x32_bf16 v[62:65], v[70:73], v[132:135], v[62:65]
	v_mfma_f32_16x16x32_bf16 v[50:53], v[82:85], v[160:163], v[50:53]
	v_mfma_f32_16x16x32_bf16 v[46:49], v[180:183], v[132:135], v[46:49]
	v_mfma_f32_16x16x32_bf16 v[34:37], v[188:191], v[160:163], v[34:37]
	v_mfma_f32_16x16x32_bf16 v[62:65], v[74:77], v[144:147], v[62:65]
	v_mfma_f32_16x16x32_bf16 v[58:61], v[70:73], v[160:163], v[58:61]
	v_mfma_f32_16x16x32_bf16 v[54:57], v[82:85], v[132:135], v[54:57]
	v_mfma_f32_16x16x32_bf16 v[50:53], v[94:97], v[164:167], v[50:53]
	v_mfma_f32_16x16x32_bf16 v[46:49], v[184:187], v[144:147], v[46:49]
	v_mfma_f32_16x16x32_bf16 v[42:45], v[180:183], v[160:163], v[42:45]
	v_mfma_f32_16x16x32_bf16 v[38:41], v[188:191], v[132:135], v[38:41]
	v_mfma_f32_16x16x32_bf16 v[34:37], v[192:195], v[164:167], v[34:37]
	v_mfma_f32_16x16x32_bf16 v[196:199], v[74:77], v[164:167], v[58:61]
	v_mfma_f32_16x16x32_bf16 v[218:221], v[94:97], v[144:147], v[54:57]
	v_mfma_f32_16x16x32_bf16 v[222:225], v[184:187], v[164:167], v[42:45]
	v_mfma_f32_16x16x32_bf16 v[130:133], v[192:195], v[144:147], v[38:41]
	s_setprio 0
	s_setprio 1
	v_mfma_f32_16x16x32_bf16 v[26:29], v[70:73], v[114:117], v[26:29]
	v_mfma_f32_16x16x32_bf16 v[18:21], v[82:85], v[114:117], v[18:21]
	v_mfma_f32_16x16x32_bf16 v[14:17], v[180:183], v[102:105], v[14:17]
	v_mfma_f32_16x16x32_bf16 v[30:33], v[70:73], v[102:105], v[30:33]
	v_mfma_f32_16x16x32_bf16 v[26:29], v[74:77], v[148:151], v[26:29]
	v_mfma_f32_16x16x32_bf16 v[22:25], v[82:85], v[102:105], v[22:25]
	v_mfma_f32_16x16x32_bf16 v[18:21], v[94:97], v[148:151], v[18:21]
	v_mfma_f32_16x16x32_bf16 v[14:17], v[184:187], v[106:109], v[14:17]
	v_mfma_f32_16x16x32_bf16 v[10:13], v[180:183], v[114:117], v[10:13]
	v_mfma_f32_16x16x32_bf16 v[6:9], v[188:191], v[102:105], v[6:9]
	v_mfma_f32_16x16x32_bf16 v[2:5], v[188:191], v[114:117], v[2:5]
	v_mfma_f32_16x16x32_bf16 v[134:137], v[74:77], v[106:109], v[30:33]
	v_mfma_f32_16x16x32_bf16 v[144:147], v[94:97], v[106:109], v[22:25]
	v_mfma_f32_16x16x32_bf16 v[158:161], v[184:187], v[148:151], v[10:13]
	v_mfma_f32_16x16x32_bf16 v[162:165], v[192:195], v[106:109], v[6:9]
	v_mfma_f32_16x16x32_bf16 v[148:151], v[192:195], v[148:151], v[2:5]
	s_setprio 0
	s_barrier
	ds_read_b128 v[180:183], v142
	ds_read_b128 v[184:187], v142 offset:1024
	ds_read_b128 v[188:191], v142 offset:2048
	ds_read_b128 v[140:143], v142 offset:3072
	ds_read_b128 v[2:5], v0 offset:32768
	ds_read_b128 v[6:9], v0 offset:33792
	ds_read_b128 v[10:13], v155 offset:32768
	ds_read_b128 v[22:25], v155 offset:33792
	ds_read_b128 v[192:195], v156 offset:32768
	ds_read_b128 v[226:229], v156 offset:33792
	ds_read_b128 v[230:233], v157 offset:32768
	ds_read_b128 v[234:237], v157 offset:33792
	s_waitcnt vmcnt(2)
	s_barrier
; #define LDA(dst, b, h) for (int m = 0; m < 4; ++m) for (int k = 0; k < 2; ++k) \
;     dst[m][k] = *reinterpret_cast<const bf16x8*>((char*)SA(b, h) + lds_byte(wr * 64 + m * 16 + fr, k * 32 + fq * 8))
; #define LDB(dst, b, h) for (int n = 0; n < 2; ++n) for (int k = 0; k < 2; ++k) \
;     dst[n][k] = *reinterpret_cast<const bf16x8*>((char*)SB(b, h) + lds_byte(wc * 32 + n * 16 + fr, k * 32 + fq * 8))
; #define MMA(ai, bj, At_, Bt_) do { __builtin_amdgcn_s_setprio(1); \
;     for (int m = 0; m < 4; ++m) for (int n = 0; n < 2; ++n) for (int k = 0; k < 2; ++k) \
;       acc[ai][bj][m][n] = MFMA16(At_[m][k], Bt_[n][k], acc[ai][bj][m][n]); \
;     __builtin_amdgcn_s_setprio(0); } while (0)
; #define WAIT_V(n) asm volatile("s_waitcnt vmcnt(" #n ")" ::: "memory")
; #define WAIT_L(n) asm volatile("s_waitcnt lgkmcnt(" #n ")" ::: "memory")
; #define BAR __builtin_amdgcn_s_barrier()
; DI void gemm_core(WVP char* smem, const u16* __restrict__ A, int lda, int ar0, int ar1,
;                   const u16* __restrict__ B, int ldb, int bc0, int K, AccT& acc) {
;     ...
;     LDA(At, 0, 1); WAIT_V(4); BAR; WAIT_L(0); MMA(1, 0, At, B0); MMA(1, 1, At, B1); BAR; }
;   { LDB(B0, 1, 0); LDA(At, 1, 0); WAIT_V(2); BAR; WAIT_L(0); MMA(0, 0, At, B0); BAR;
;     LDB(B1, 1, 1); WAIT_V(0); BAR; WAIT_L(0); MMA(0, 1, At, B1); BAR;
;     LDA(At, 1, 1); BAR; WAIT_L(0); MMA(1, 0, At, B0); MMA(1, 1, At, B1); BAR; }
;   if (wr == 0) BAR;
	s_waitcnt lgkmcnt(0)
	s_setprio 1
	s_waitcnt lgkmcnt(0)
	v_mfma_f32_16x16x32_bf16 v[30:33], v[2:5], v[180:183], v[126:129]
	v_mfma_f32_16x16x32_bf16 v[114:117], v[6:9], v[184:187], v[30:33]
	v_mfma_f32_16x16x32_bf16 v[30:33], v[2:5], v[188:191], v[122:125]
	v_mfma_f32_16x16x32_bf16 v[106:109], v[6:9], v[140:143], v[30:33]
	v_mfma_f32_16x16x32_bf16 v[30:33], v[10:13], v[180:183], v[118:121]
	v_mfma_f32_16x16x32_bf16 v[102:105], v[22:25], v[184:187], v[30:33]
	v_mfma_f32_16x16x32_bf16 v[30:33], v[10:13], v[188:191], v[200:203]
	v_mfma_f32_16x16x32_bf16 v[94:97], v[22:25], v[140:143], v[30:33]
	v_mfma_f32_16x16x32_bf16 v[30:33], v[192:195], v[180:183], v[110:113]
	v_mfma_f32_16x16x32_bf16 v[82:85], v[226:229], v[184:187], v[30:33]
	v_mfma_f32_16x16x32_bf16 v[30:33], v[192:195], v[188:191], v[206:209]
	v_mfma_f32_16x16x32_bf16 v[74:77], v[226:229], v[140:143], v[30:33]
	v_mfma_f32_16x16x32_bf16 v[30:33], v[230:233], v[180:183], v[210:213]
	v_mfma_f32_16x16x32_bf16 v[70:73], v[234:237], v[184:187], v[30:33]
	v_mfma_f32_16x16x32_bf16 v[30:33], v[230:233], v[188:191], v[98:101]
	v_mfma_f32_16x16x32_bf16 v[58:61], v[234:237], v[140:143], v[30:33]
	s_setprio 0
	s_barrier
	ds_read_b128 v[200:203], v139
	ds_read_b128 v[206:209], v139 offset:1024
	ds_read_b128 v[210:213], v139 offset:2048
	ds_read_b128 v[238:241], v139 offset:3072
	s_waitcnt vmcnt(0)
	s_barrier
	s_waitcnt lgkmcnt(0)
	s_setprio 1
	s_waitcnt lgkmcnt(0)
	v_mfma_f32_16x16x32_bf16 v[30:33], v[2:5], v[200:203], v[214:217]
	v_mfma_f32_16x16x32_bf16 v[2:5], v[2:5], v[210:213], v[90:93]
	v_mfma_f32_16x16x32_bf16 v[42:45], v[6:9], v[238:241], v[2:5]
	v_mfma_f32_16x16x32_bf16 v[2:5], v[10:13], v[200:203], v[86:89]
	v_mfma_f32_16x16x32_bf16 v[38:41], v[22:25], v[206:209], v[2:5]
	v_mfma_f32_16x16x32_bf16 v[2:5], v[10:13], v[210:213], v[168:171]
	v_mfma_f32_16x16x32_bf16 v[54:57], v[6:9], v[206:209], v[30:33]
	v_mfma_f32_16x16x32_bf16 v[30:33], v[22:25], v[238:241], v[2:5]
	v_mfma_f32_16x16x32_bf16 v[2:5], v[192:195], v[200:203], v[78:81]
	v_mfma_f32_16x16x32_bf16 v[22:25], v[226:229], v[206:209], v[2:5]
	v_mfma_f32_16x16x32_bf16 v[2:5], v[192:195], v[210:213], v[172:175]
	v_mfma_f32_16x16x32_bf16 v[10:13], v[226:229], v[238:241], v[2:5]
	v_mfma_f32_16x16x32_bf16 v[2:5], v[230:233], v[200:203], v[176:179]
	v_mfma_f32_16x16x32_bf16 v[6:9], v[234:237], v[206:209], v[2:5]
	v_mfma_f32_16x16x32_bf16 v[2:5], v[230:233], v[210:213], v[66:69]
	v_mfma_f32_16x16x32_bf16 v[2:5], v[234:237], v[238:241], v[2:5]
	s_setprio 0
	s_barrier
	ds_read_b128 v[166:169], v0 offset:49152
	ds_read_b128 v[170:173], v0 offset:50176
	ds_read_b128 v[174:177], v155 offset:49152
	ds_read_b128 v[152:155], v155 offset:50176
	ds_read_b128 v[192:195], v156 offset:49152
	ds_read_b128 v[214:217], v156 offset:50176
	ds_read_b128 v[226:229], v157 offset:49152
	ds_read_b128 v[230:233], v157 offset:50176
	s_barrier
	s_waitcnt lgkmcnt(0)
	s_setprio 1
	s_waitcnt lgkmcnt(0)
	v_mfma_f32_16x16x32_bf16 v[62:65], v[166:169], v[180:183], v[62:65]
	v_mfma_f32_16x16x32_bf16 v[46:49], v[192:195], v[180:183], v[46:49]
	v_mfma_f32_16x16x32_bf16 v[126:129], v[170:173], v[184:187], v[62:65]
	v_mfma_f32_16x16x32_bf16 v[62:65], v[166:169], v[188:191], v[196:199]
	v_mfma_f32_16x16x32_bf16 v[98:101], v[214:217], v[184:187], v[46:49]
	v_mfma_f32_16x16x32_bf16 v[46:49], v[192:195], v[188:191], v[222:225]
	v_mfma_f32_16x16x32_bf16 v[122:125], v[170:173], v[140:143], v[62:65]
	v_mfma_f32_16x16x32_bf16 v[62:65], v[174:177], v[180:183], v[218:221]
	v_mfma_f32_16x16x32_bf16 v[50:53], v[174:177], v[188:191], v[50:53]
	v_mfma_f32_16x16x32_bf16 v[90:93], v[214:217], v[140:143], v[46:49]
	v_mfma_f32_16x16x32_bf16 v[46:49], v[226:229], v[180:183], v[130:133]
	v_mfma_f32_16x16x32_bf16 v[34:37], v[226:229], v[188:191], v[34:37]
	v_mfma_f32_16x16x32_bf16 v[118:121], v[152:155], v[184:187], v[62:65]
	v_mfma_f32_16x16x32_bf16 v[110:113], v[152:155], v[140:143], v[50:53]
	v_mfma_f32_16x16x32_bf16 v[86:89], v[230:233], v[184:187], v[46:49]
	v_mfma_f32_16x16x32_bf16 v[78:81], v[230:233], v[140:143], v[34:37]
	s_setprio 0
	s_setprio 1
	v_mfma_f32_16x16x32_bf16 v[34:37], v[166:169], v[200:203], v[134:137]
	v_mfma_f32_16x16x32_bf16 v[26:29], v[166:169], v[210:213], v[26:29]
	v_mfma_f32_16x16x32_bf16 v[14:17], v[192:195], v[200:203], v[14:17]
	v_mfma_f32_16x16x32_bf16 v[66:69], v[170:173], v[206:209], v[34:37]
	v_mfma_f32_16x16x32_bf16 v[62:65], v[170:173], v[238:241], v[26:29]
	v_mfma_f32_16x16x32_bf16 v[26:29], v[174:177], v[200:203], v[144:147]
	v_mfma_f32_16x16x32_bf16 v[34:37], v[214:217], v[206:209], v[14:17]
	v_mfma_f32_16x16x32_bf16 v[14:17], v[192:195], v[210:213], v[158:161]
	v_mfma_f32_16x16x32_bf16 v[50:53], v[152:155], v[206:209], v[26:29]
	v_mfma_f32_16x16x32_bf16 v[18:21], v[174:177], v[210:213], v[18:21]
	v_mfma_f32_16x16x32_bf16 v[26:29], v[214:217], v[238:241], v[14:17]
	v_mfma_f32_16x16x32_bf16 v[14:17], v[226:229], v[200:203], v[162:165]
	v_mfma_f32_16x16x32_bf16 v[46:49], v[152:155], v[238:241], v[18:21]
	v_mfma_f32_16x16x32_bf16 v[18:21], v[230:233], v[206:209], v[14:17]
	v_mfma_f32_16x16x32_bf16 v[14:17], v[226:229], v[210:213], v[148:151]
	v_mfma_f32_16x16x32_bf16 v[14:17], v[230:233], v[238:241], v[14:17]
	s_setprio 0
	s_cmp_gt_u32 s18, 3
	s_barrier
	s_cbranch_scc1 .LBB0_265
	s_barrier
	s_branch .LBB0_265

; #define STAGE_A(P, br, kt) do { const char* _g = (const char*)(A + (long)(br) * lda + (long)(kt) * BK); \
;     __builtin_amdgcn_global_load_lds((const unsigned*)(_g + (size_t)offA0), (unsigned*)((char*)(P) + sb0), 16, 0, 0); \
;     __builtin_amdgcn_global_load_lds((const unsigned*)(_g + (size_t)lda * 128 + (size_t)offA0), (unsigned*)((char*)(P) + sb1), 16, 0, 0); } while (0)
; #define STAGE_B(P, br, kt) do { const char* _g = (const char*)(B + (long)(br) * ldb + (long)(kt) * BK); \
;     __builtin_amdgcn_global_load_lds((const unsigned*)(_g + (size_t)offB0), (unsigned*)((char*)(P) + sb0), 16, 0, 0); \
;     __builtin_amdgcn_global_load_lds((const unsigned*)(_g + (size_t)ldb * 128 + (size_t)offB0), (unsigned*)((char*)(P) + sb1), 16, 0, 0); } while (0)
; #define LDA(dst, b, h) for (int m = 0; m < 4; ++m) for (int k = 0; k < 2; ++k) \
;     dst[m][k] = *reinterpret_cast<const bf16x8*>((char*)SA(b, h) + lds_byte(wr * 64 + m * 16 + fr, k * 32 + fq * 8))
; #define LDB(dst, b, h) for (int n = 0; n < 2; ++n) for (int k = 0; k < 2; ++k) \
;     dst[n][k] = *reinterpret_cast<const bf16x8*>((char*)SB(b, h) + lds_byte(wc * 32 + n * 16 + fr, k * 32 + fq * 8))
; #define MMA(ai, bj, At_, Bt_) do { __builtin_amdgcn_s_setprio(1); \
;     for (int m = 0; m < 4; ++m) for (int n = 0; n < 2; ++n) for (int k = 0; k < 2; ++k) \
;       acc[ai][bj][m][n] = MFMA16(At_[m][k], Bt_[n][k], acc[ai][bj][m][n]); \
;     __builtin_amdgcn_s_setprio(0); } while (0)
; #define WAIT_V(n) asm volatile("s_waitcnt vmcnt(" #n ")" ::: "memory")
; #define WAIT_L(n) asm volatile("s_waitcnt lgkmcnt(" #n ")" ::: "memory")
; #define BAR __builtin_amdgcn_s_barrier()
; #define SCHED __builtin_amdgcn_sched_barrier(0)
; DI void gemm_core(WVP char* smem, const u16* __restrict__ A, int lda, int ar0, int ar1,
;                   const u16* __restrict__ B, int ldb, int bc0, int K, AccT& acc) {
;     ...
;   for (int t = 0; t < nt - 2; t += 2) {
;     LDB(B0, 0, 0); SCHED; LDA(At, 0, 0); STAGE_A(SA(1, 1), ac1, t + 1);
;     WAIT_L(8); BAR; WAIT_L(0); MMA(0, 0, At, B0); BAR; SCHED;
;     LDB(B1, 0, 1); STAGE_B(SB(0, 0), bb0, t + 2);
;     BAR; WAIT_L(0); MMA(0, 1, At, B1); BAR;
;     LDA(At, 0, 1); STAGE_A(SA(0, 0), ac0, t + 2);
;     BAR; WAIT_L(0); MMA(1, 0, At, B0); BAR; SCHED;
;     STAGE_B(SB(0, 1), bb1, t + 2);
;     WAIT_V(6); BAR; MMA(1, 1, At, B1); BAR;
.LBB0_427:
	v_add_u32_e32 v150, s0, v148
	v_add_u32_e32 v151, s1, v148
	v_add_u32_e32 v152, s5, v148
	ds_read_b128 v[156:159], v149
	ds_read_b128 v[160:163], v149 offset:1024
	ds_read_b128 v[164:167], v149 offset:2048
	ds_read_b128 v[168:171], v149 offset:3072
	ds_read_b128 v[172:175], v132
	ds_read_b128 v[176:179], v132 offset:1024
	ds_read_b128 v[180:183], v150
	ds_read_b128 v[184:187], v150 offset:1024
	ds_read_b128 v[188:191], v151
	ds_read_b128 v[206:209], v151 offset:1024
	ds_read_b128 v[210:213], v152
	ds_read_b128 v[214:217], v152 offset:1024
	ds_read_b128 v[218:221], v147
	ds_read_b128 v[222:225], v147 offset:1024
	ds_read_b128 v[226:229], v147 offset:2048
	ds_read_b128 v[230:233], v147 offset:3072
	v_add_u32_e32 v153, 0xc000, v135
	v_lshl_add_u64 v[194:195], s[14:15], 0, v[0:1]
	s_mov_b64 s[16:17], 0x1d1c0080
	v_lshl_add_u64 v[192:193], v[194:195], 0, s[16:17]
	v_readfirstlane_b32 s11, v153
	s_mov_b32 m0, s11
	s_nop 0
	global_load_lds_dwordx4 v[192:193], off
	v_add_u32_e32 v154, 0xe000, v135
	v_lshl_add_u64 v[194:195], s[14:15], 0, v[0:1]
	s_mov_b64 s[16:17], 0x1d1e0080
	v_lshl_add_u64 v[192:193], v[194:195], 0, s[16:17]
	v_readfirstlane_b32 s11, v154
	s_mov_b32 m0, s11
	s_nop 0
	global_load_lds_dwordx4 v[192:193], off
	s_waitcnt vmcnt(8)
	s_waitcnt lgkmcnt(0)
	s_barrier
	v_mfma_f32_16x16x32_bf16 v[126:129], v[172:175], v[156:159], v[126:129]
	v_mfma_f32_16x16x32_bf16 v[126:129], v[176:179], v[160:163], v[126:129]
	v_mfma_f32_16x16x32_bf16 v[122:125], v[172:175], v[164:167], v[122:125]
	v_mfma_f32_16x16x32_bf16 v[122:125], v[176:179], v[168:171], v[122:125]
	v_mfma_f32_16x16x32_bf16 v[118:121], v[180:183], v[156:159], v[118:121]
	v_mfma_f32_16x16x32_bf16 v[118:121], v[184:187], v[160:163], v[118:121]
	v_mfma_f32_16x16x32_bf16 v[114:117], v[180:183], v[164:167], v[114:117]
	v_mfma_f32_16x16x32_bf16 v[114:117], v[184:187], v[168:171], v[114:117]
	v_mfma_f32_16x16x32_bf16 v[110:113], v[188:191], v[156:159], v[110:113]
	v_mfma_f32_16x16x32_bf16 v[110:113], v[206:209], v[160:163], v[110:113]
	v_mfma_f32_16x16x32_bf16 v[106:109], v[188:191], v[164:167], v[106:109]
	v_mfma_f32_16x16x32_bf16 v[106:109], v[206:209], v[168:171], v[106:109]
	v_mfma_f32_16x16x32_bf16 v[102:105], v[210:213], v[156:159], v[102:105]
	v_mfma_f32_16x16x32_bf16 v[102:105], v[214:217], v[160:163], v[102:105]
	v_mfma_f32_16x16x32_bf16 v[98:101], v[210:213], v[164:167], v[98:101]
	v_mfma_f32_16x16x32_bf16 v[98:101], v[214:217], v[168:171], v[98:101]
	v_mfma_f32_16x16x32_bf16 v[94:97], v[172:175], v[218:221], v[94:97]
	v_mfma_f32_16x16x32_bf16 v[94:97], v[176:179], v[222:225], v[94:97]
	v_mfma_f32_16x16x32_bf16 v[90:93], v[172:175], v[226:229], v[90:93]
	v_mfma_f32_16x16x32_bf16 v[90:93], v[176:179], v[230:233], v[90:93]
	v_mfma_f32_16x16x32_bf16 v[86:89], v[180:183], v[218:221], v[86:89]
	v_mfma_f32_16x16x32_bf16 v[86:89], v[184:187], v[222:225], v[86:89]
	v_mfma_f32_16x16x32_bf16 v[82:85], v[180:183], v[226:229], v[82:85]
	v_mfma_f32_16x16x32_bf16 v[82:85], v[184:187], v[230:233], v[82:85]
	v_mfma_f32_16x16x32_bf16 v[78:81], v[188:191], v[218:221], v[78:81]
	v_mfma_f32_16x16x32_bf16 v[78:81], v[206:209], v[222:225], v[78:81]
	v_mfma_f32_16x16x32_bf16 v[74:77], v[188:191], v[226:229], v[74:77]
	v_mfma_f32_16x16x32_bf16 v[74:77], v[206:209], v[230:233], v[74:77]
	v_mfma_f32_16x16x32_bf16 v[70:73], v[210:213], v[218:221], v[70:73]
	v_mfma_f32_16x16x32_bf16 v[70:73], v[214:217], v[222:225], v[70:73]
	v_mfma_f32_16x16x32_bf16 v[66:69], v[210:213], v[226:229], v[66:69]
	v_mfma_f32_16x16x32_bf16 v[66:69], v[214:217], v[230:233], v[66:69]
	s_barrier
	ds_read_b128 v[172:175], v132 offset:16384
	ds_read_b128 v[176:179], v132 offset:17408
	ds_read_b128 v[180:183], v150 offset:16384
	ds_read_b128 v[184:187], v150 offset:17408
	ds_read_b128 v[188:191], v151 offset:16384
	ds_read_b128 v[206:209], v151 offset:17408
	ds_read_b128 v[210:213], v152 offset:16384
	ds_read_b128 v[214:217], v152 offset:17408
	v_lshl_add_u64 v[194:195], s[12:13], 0, v[0:1]
	v_lshl_add_u64 v[192:193], v[194:195], 0, s[80:81]
	v_readfirstlane_b32 s11, v133
	s_mov_b32 m0, s11
	s_nop 0
	global_load_lds_dwordx4 v[192:193], off
	v_add_u32_e32 v155, 0x2000, v133
	v_lshl_add_u64 v[194:195], s[12:13], 0, v[0:1]
	v_lshl_add_u64 v[192:193], v[194:195], 0, s[82:83]
	v_readfirstlane_b32 s11, v155
	s_mov_b32 m0, s11
	s_nop 0
	global_load_lds_dwordx4 v[192:193], off
	v_lshl_add_u64 v[194:195], s[14:15], 0, v[0:1]
	s_mov_b64 s[16:17], 0x1d180100
	v_lshl_add_u64 v[192:193], v[194:195], 0, s[16:17]
	v_readfirstlane_b32 s11, v135
	s_mov_b32 m0, s11
	s_nop 0
	global_load_lds_dwordx4 v[192:193], off
	v_lshl_add_u64 v[194:195], s[14:15], 0, v[0:1]
	s_mov_b64 s[16:17], 0x1d1a0100
	v_lshl_add_u64 v[192:193], v[194:195], 0, s[16:17]
	v_readfirstlane_b32 s11, v136
	s_mov_b32 m0, s11
	s_nop 0
	global_load_lds_dwordx4 v[192:193], off
	v_lshl_add_u64 v[194:195], s[12:13], 0, v[0:1]
	v_lshl_add_u64 v[192:193], v[194:195], 0, s[88:89]
	v_readfirstlane_b32 s11, v137
	s_mov_b32 m0, s11
	s_nop 0
	global_load_lds_dwordx4 v[192:193], off
	v_add_u32_e32 v155, 0x2000, v137
	v_lshl_add_u64 v[194:195], s[12:13], 0, v[0:1]
	v_lshl_add_u64 v[192:193], v[194:195], 0, s[90:91]
	v_readfirstlane_b32 s11, v155
	s_mov_b32 m0, s11
	s_nop 0
	global_load_lds_dwordx4 v[192:193], off
	s_waitcnt vmcnt(8)
	s_waitcnt lgkmcnt(0)
	s_barrier
; #define STAGE_A(P, br, kt) do { const char* _g = (const char*)(A + (long)(br) * lda + (long)(kt) * BK); \
;     __builtin_amdgcn_global_load_lds((const unsigned*)(_g + (size_t)offA0), (unsigned*)((char*)(P) + sb0), 16, 0, 0); \
;     __builtin_amdgcn_global_load_lds((const unsigned*)(_g + (size_t)lda * 128 + (size_t)offA0), (unsigned*)((char*)(P) + sb1), 16, 0, 0); } while (0)
; #define STAGE_B(P, br, kt) do { const char* _g = (const char*)(B + (long)(br) * ldb + (long)(kt) * BK); \
;     __builtin_amdgcn_global_load_lds((const unsigned*)(_g + (size_t)offB0), (unsigned*)((char*)(P) + sb0), 16, 0, 0); \
;     __builtin_amdgcn_global_load_lds((const unsigned*)(_g + (size_t)ldb * 128 + (size_t)offB0), (unsigned*)((char*)(P) + sb1), 16, 0, 0); } while (0)
; #define LDA(dst, b, h) for (int m = 0; m < 4; ++m) for (int k = 0; k < 2; ++k) \
;     dst[m][k] = *reinterpret_cast<const bf16x8*>((char*)SA(b, h) + lds_byte(wr * 64 + m * 16 + fr, k * 32 + fq * 8))
; #define LDB(dst, b, h) for (int n = 0; n < 2; ++n) for (int k = 0; k < 2; ++k) \
;     dst[n][k] = *reinterpret_cast<const bf16x8*>((char*)SB(b, h) + lds_byte(wc * 32 + n * 16 + fr, k * 32 + fq * 8))
; #define MMA(ai, bj, At_, Bt_) do { __builtin_amdgcn_s_setprio(1); \
;     for (int m = 0; m < 4; ++m) for (int n = 0; n < 2; ++n) for (int k = 0; k < 2; ++k) \
;       acc[ai][bj][m][n] = MFMA16(At_[m][k], Bt_[n][k], acc[ai][bj][m][n]); \
;     __builtin_amdgcn_s_setprio(0); } while (0)
; #define WAIT_V(n) asm volatile("s_waitcnt vmcnt(" #n ")" ::: "memory")
; #define WAIT_L(n) asm volatile("s_waitcnt lgkmcnt(" #n ")" ::: "memory")
; #define BAR __builtin_amdgcn_s_barrier()
; #define SCHED __builtin_amdgcn_sched_barrier(0)
; DI void gemm_core(WVP char* smem, const u16* __restrict__ A, int lda, int ar0, int ar1,
;                   const u16* __restrict__ B, int ldb, int bc0, int K, AccT& acc) {
;     ...
;     BAR; WAIT_L(0); MMA(1, 0, At, B0); BAR; SCHED;
;     STAGE_B(SB(0, 1), bb1, t + 2);
;     WAIT_V(6); BAR; MMA(1, 1, At, B1); BAR;
;     LDB(B0, 1, 0); SCHED; LDA(At, 1, 0); STAGE_A(SA(0, 1), ac1, t + 2);
;     WAIT_L(8); BAR; WAIT_L(0); MMA(0, 0, At, B0); BAR; SCHED;
;     LDB(B1, 1, 1); STAGE_B(SB(1, 0), bb0, t + 3);
;     BAR; WAIT_L(0); MMA(0, 1, At, B1); BAR;
	v_mfma_f32_16x16x32_bf16 v[62:65], v[172:175], v[156:159], v[62:65]
	v_mfma_f32_16x16x32_bf16 v[62:65], v[176:179], v[160:163], v[62:65]
	v_mfma_f32_16x16x32_bf16 v[58:61], v[172:175], v[164:167], v[58:61]
	v_mfma_f32_16x16x32_bf16 v[58:61], v[176:179], v[168:171], v[58:61]
	v_mfma_f32_16x16x32_bf16 v[54:57], v[180:183], v[156:159], v[54:57]
	v_mfma_f32_16x16x32_bf16 v[54:57], v[184:187], v[160:163], v[54:57]
	v_mfma_f32_16x16x32_bf16 v[50:53], v[180:183], v[164:167], v[50:53]
	v_mfma_f32_16x16x32_bf16 v[50:53], v[184:187], v[168:171], v[50:53]
	v_mfma_f32_16x16x32_bf16 v[46:49], v[188:191], v[156:159], v[46:49]
	v_mfma_f32_16x16x32_bf16 v[46:49], v[206:209], v[160:163], v[46:49]
	v_mfma_f32_16x16x32_bf16 v[42:45], v[188:191], v[164:167], v[42:45]
	v_mfma_f32_16x16x32_bf16 v[42:45], v[206:209], v[168:171], v[42:45]
	v_mfma_f32_16x16x32_bf16 v[38:41], v[210:213], v[156:159], v[38:41]
	v_mfma_f32_16x16x32_bf16 v[38:41], v[214:217], v[160:163], v[38:41]
	v_mfma_f32_16x16x32_bf16 v[34:37], v[210:213], v[164:167], v[34:37]
	v_mfma_f32_16x16x32_bf16 v[34:37], v[214:217], v[168:171], v[34:37]
	v_mfma_f32_16x16x32_bf16 v[30:33], v[172:175], v[218:221], v[30:33]
	v_mfma_f32_16x16x32_bf16 v[30:33], v[176:179], v[222:225], v[30:33]
	v_mfma_f32_16x16x32_bf16 v[26:29], v[172:175], v[226:229], v[26:29]
	v_mfma_f32_16x16x32_bf16 v[26:29], v[176:179], v[230:233], v[26:29]
	v_mfma_f32_16x16x32_bf16 v[22:25], v[180:183], v[218:221], v[22:25]
	v_mfma_f32_16x16x32_bf16 v[22:25], v[184:187], v[222:225], v[22:25]
	v_mfma_f32_16x16x32_bf16 v[18:21], v[180:183], v[226:229], v[18:21]
	v_mfma_f32_16x16x32_bf16 v[18:21], v[184:187], v[230:233], v[18:21]
	v_mfma_f32_16x16x32_bf16 v[14:17], v[188:191], v[218:221], v[14:17]
	v_mfma_f32_16x16x32_bf16 v[14:17], v[206:209], v[222:225], v[14:17]
	v_mfma_f32_16x16x32_bf16 v[10:13], v[188:191], v[226:229], v[10:13]
	v_mfma_f32_16x16x32_bf16 v[10:13], v[206:209], v[230:233], v[10:13]
	v_mfma_f32_16x16x32_bf16 v[6:9], v[210:213], v[218:221], v[6:9]
	v_mfma_f32_16x16x32_bf16 v[6:9], v[214:217], v[222:225], v[6:9]
	v_mfma_f32_16x16x32_bf16 v[2:5], v[210:213], v[226:229], v[2:5]
	v_mfma_f32_16x16x32_bf16 v[2:5], v[214:217], v[230:233], v[2:5]
	s_barrier
	ds_read_b128 v[156:159], v138
	ds_read_b128 v[160:163], v138 offset:1024
	ds_read_b128 v[164:167], v138 offset:2048
	ds_read_b128 v[168:171], v138 offset:3072
	ds_read_b128 v[172:175], v132 offset:32768
	ds_read_b128 v[176:179], v132 offset:33792
	ds_read_b128 v[180:183], v150 offset:32768
	ds_read_b128 v[184:187], v150 offset:33792
	ds_read_b128 v[188:191], v151 offset:32768
	ds_read_b128 v[206:209], v151 offset:33792
	ds_read_b128 v[210:213], v152 offset:32768
	ds_read_b128 v[214:217], v152 offset:33792
	ds_read_b128 v[218:221], v134
	ds_read_b128 v[222:225], v134 offset:1024
	ds_read_b128 v[226:229], v134 offset:2048
	ds_read_b128 v[230:233], v134 offset:3072
	v_lshl_add_u64 v[194:195], s[14:15], 0, v[0:1]
	s_mov_b64 s[16:17], 0x1d1c0100
	v_lshl_add_u64 v[192:193], v[194:195], 0, s[16:17]
	v_readfirstlane_b32 s11, v139
	s_mov_b32 m0, s11
	s_nop 0
	global_load_lds_dwordx4 v[192:193], off
	v_lshl_add_u64 v[194:195], s[14:15], 0, v[0:1]
	s_mov_b64 s[16:17], 0x1d1e0100
	v_lshl_add_u64 v[192:193], v[194:195], 0, s[16:17]
	v_readfirstlane_b32 s11, v140
	s_mov_b32 m0, s11
	s_nop 0
	global_load_lds_dwordx4 v[192:193], off
	s_waitcnt vmcnt(8)
	s_waitcnt lgkmcnt(0)
	s_barrier
	v_mfma_f32_16x16x32_bf16 v[126:129], v[172:175], v[156:159], v[126:129]
	v_mfma_f32_16x16x32_bf16 v[126:129], v[176:179], v[160:163], v[126:129]
	v_mfma_f32_16x16x32_bf16 v[122:125], v[172:175], v[164:167], v[122:125]
	v_mfma_f32_16x16x32_bf16 v[122:125], v[176:179], v[168:171], v[122:125]
	v_mfma_f32_16x16x32_bf16 v[118:121], v[180:183], v[156:159], v[118:121]
	v_mfma_f32_16x16x32_bf16 v[118:121], v[184:187], v[160:163], v[118:121]
	v_mfma_f32_16x16x32_bf16 v[114:117], v[180:183], v[164:167], v[114:117]
	v_mfma_f32_16x16x32_bf16 v[114:117], v[184:187], v[168:171], v[114:117]
	v_mfma_f32_16x16x32_bf16 v[110:113], v[188:191], v[156:159], v[110:113]
	v_mfma_f32_16x16x32_bf16 v[110:113], v[206:209], v[160:163], v[110:113]
	v_mfma_f32_16x16x32_bf16 v[106:109], v[188:191], v[164:167], v[106:109]
	v_mfma_f32_16x16x32_bf16 v[106:109], v[206:209], v[168:171], v[106:109]
	v_mfma_f32_16x16x32_bf16 v[102:105], v[210:213], v[156:159], v[102:105]
	v_mfma_f32_16x16x32_bf16 v[102:105], v[214:217], v[160:163], v[102:105]
	v_mfma_f32_16x16x32_bf16 v[98:101], v[210:213], v[164:167], v[98:101]
	v_mfma_f32_16x16x32_bf16 v[98:101], v[214:217], v[168:171], v[98:101]
	v_mfma_f32_16x16x32_bf16 v[94:97], v[172:175], v[218:221], v[94:97]
	v_mfma_f32_16x16x32_bf16 v[94:97], v[176:179], v[222:225], v[94:97]
	v_mfma_f32_16x16x32_bf16 v[90:93], v[172:175], v[226:229], v[90:93]
	v_mfma_f32_16x16x32_bf16 v[90:93], v[176:179], v[230:233], v[90:93]
	v_mfma_f32_16x16x32_bf16 v[86:89], v[180:183], v[218:221], v[86:89]
	v_mfma_f32_16x16x32_bf16 v[86:89], v[184:187], v[222:225], v[86:89]
	v_mfma_f32_16x16x32_bf16 v[82:85], v[180:183], v[226:229], v[82:85]
	v_mfma_f32_16x16x32_bf16 v[82:85], v[184:187], v[230:233], v[82:85]
	v_mfma_f32_16x16x32_bf16 v[78:81], v[188:191], v[218:221], v[78:81]
	v_mfma_f32_16x16x32_bf16 v[78:81], v[206:209], v[222:225], v[78:81]
	v_mfma_f32_16x16x32_bf16 v[74:77], v[188:191], v[226:229], v[74:77]
	v_mfma_f32_16x16x32_bf16 v[74:77], v[206:209], v[230:233], v[74:77]
	v_mfma_f32_16x16x32_bf16 v[70:73], v[210:213], v[218:221], v[70:73]
	v_mfma_f32_16x16x32_bf16 v[70:73], v[214:217], v[222:225], v[70:73]
	v_mfma_f32_16x16x32_bf16 v[66:69], v[210:213], v[226:229], v[66:69]
	v_mfma_f32_16x16x32_bf16 v[66:69], v[214:217], v[230:233], v[66:69]
	s_barrier
; #define STAGE_A(P, br, kt) do { const char* _g = (const char*)(A + (long)(br) * lda + (long)(kt) * BK); \
;     __builtin_amdgcn_global_load_lds((const unsigned*)(_g + (size_t)offA0), (unsigned*)((char*)(P) + sb0), 16, 0, 0); \
;     __builtin_amdgcn_global_load_lds((const unsigned*)(_g + (size_t)lda * 128 + (size_t)offA0), (unsigned*)((char*)(P) + sb1), 16, 0, 0); } while (0)
; #define STAGE_B(P, br, kt) do { const char* _g = (const char*)(B + (long)(br) * ldb + (long)(kt) * BK); \
;     __builtin_amdgcn_global_load_lds((const unsigned*)(_g + (size_t)offB0), (unsigned*)((char*)(P) + sb0), 16, 0, 0); \
;     __builtin_amdgcn_global_load_lds((const unsigned*)(_g + (size_t)ldb * 128 + (size_t)offB0), (unsigned*)((char*)(P) + sb1), 16, 0, 0); } while (0)
; #define LDA(dst, b, h) for (int m = 0; m < 4; ++m) for (int k = 0; k < 2; ++k) \
;     dst[m][k] = *reinterpret_cast<const bf16x8*>((char*)SA(b, h) + lds_byte(wr * 64 + m * 16 + fr, k * 32 + fq * 8))
; #define LDB(dst, b, h) for (int n = 0; n < 2; ++n) for (int k = 0; k < 2; ++k) \
;     dst[n][k] = *reinterpret_cast<const bf16x8*>((char*)SB(b, h) + lds_byte(wc * 32 + n * 16 + fr, k * 32 + fq * 8))
; #define MMA(ai, bj, At_, Bt_) do { __builtin_amdgcn_s_setprio(1); \
;     for (int m = 0; m < 4; ++m) for (int n = 0; n < 2; ++n) for (int k = 0; k < 2; ++k) \
;       acc[ai][bj][m][n] = MFMA16(At_[m][k], Bt_[n][k], acc[ai][bj][m][n]); \
;     __builtin_amdgcn_s_setprio(0); } while (0)
; #define WAIT_V(n) asm volatile("s_waitcnt vmcnt(" #n ")" ::: "memory")
; #define WAIT_L(n) asm volatile("s_waitcnt lgkmcnt(" #n ")" ::: "memory")
; #define BAR __builtin_amdgcn_s_barrier()
; #define SCHED __builtin_amdgcn_sched_barrier(0)
; DI void gemm_core(WVP char* smem, const u16* __restrict__ A, int lda, int ar0, int ar1,
;                   const u16* __restrict__ B, int ldb, int bc0, int K, AccT& acc) {
;     ...
;     BAR; WAIT_L(0); MMA(0, 1, At, B1); BAR;
;     LDA(At, 1, 1); STAGE_A(SA(1, 0), ac0, t + 3);
;     BAR; WAIT_L(0); MMA(1, 0, At, B0); BAR; SCHED;
;     STAGE_B(SB(1, 1), bb1, t + 3);
;     WAIT_V(6); BAR; MMA(1, 1, At, B1); BAR;
;   }
;   { LDB(B0, 0, 0); LDA(At, 0, 0); STAGE_A(SA(1, 1), ac1, nt - 1);
;     BAR; WAIT_L(0); MMA(0, 0, At, B0); BAR;
;     LDB(B1, 0, 1); BAR; WAIT_L(0); MMA(0, 1, At, B1); BAR;
;     LDA(At, 0, 1); WAIT_V(4); BAR; WAIT_L(0); MMA(1, 0, At, B0); MMA(1, 1, At, B1); BAR; }
	ds_read_b128 v[172:175], v132 offset:49152
	ds_read_b128 v[176:179], v132 offset:50176
	ds_read_b128 v[180:183], v150 offset:49152
	ds_read_b128 v[184:187], v150 offset:50176
	ds_read_b128 v[188:191], v151 offset:49152
	ds_read_b128 v[206:209], v151 offset:50176
	ds_read_b128 v[210:213], v152 offset:49152
	ds_read_b128 v[214:217], v152 offset:50176
	v_lshl_add_u64 v[194:195], s[12:13], 0, v[0:1]
	v_lshl_add_u64 v[192:193], v[194:195], 0, s[92:93]
	v_readfirstlane_b32 s11, v141
	s_mov_b32 m0, s11
	s_nop 0
	global_load_lds_dwordx4 v[192:193], off
	v_lshl_add_u64 v[194:195], s[12:13], 0, v[0:1]
	v_lshl_add_u64 v[192:193], v[194:195], 0, s[94:95]
	v_readfirstlane_b32 s11, v142
	s_mov_b32 m0, s11
	s_nop 0
	global_load_lds_dwordx4 v[192:193], off
	v_lshl_add_u64 v[194:195], s[14:15], 0, v[0:1]
	s_mov_b64 s[16:17], 0x1d180180
	v_lshl_add_u64 v[192:193], v[194:195], 0, s[16:17]
	v_readfirstlane_b32 s11, v143
	s_mov_b32 m0, s11
	s_nop 0
	global_load_lds_dwordx4 v[192:193], off
	v_lshl_add_u64 v[194:195], s[14:15], 0, v[0:1]
	s_mov_b64 s[16:17], 0x1d1a0180
	v_lshl_add_u64 v[192:193], v[194:195], 0, s[16:17]
	v_readfirstlane_b32 s11, v144
	s_mov_b32 m0, s11
	s_nop 0
	global_load_lds_dwordx4 v[192:193], off
	v_lshl_add_u64 v[194:195], s[12:13], 0, v[0:1]
	v_lshl_add_u64 v[192:193], v[194:195], 0, s[96:97]
	v_readfirstlane_b32 s11, v145
	s_mov_b32 m0, s11
	s_nop 0
	global_load_lds_dwordx4 v[192:193], off
	v_lshl_add_u64 v[194:195], s[12:13], 0, v[0:1]
	v_lshl_add_u64 v[192:193], v[194:195], 0, s[72:73]
	v_readfirstlane_b32 s11, v146
	s_mov_b32 m0, s11
	s_nop 0
	global_load_lds_dwordx4 v[192:193], off
	s_waitcnt vmcnt(8)
	s_waitcnt lgkmcnt(0)
	s_barrier
	v_mfma_f32_16x16x32_bf16 v[62:65], v[172:175], v[156:159], v[62:65]
	v_mfma_f32_16x16x32_bf16 v[62:65], v[176:179], v[160:163], v[62:65]
	v_mfma_f32_16x16x32_bf16 v[58:61], v[172:175], v[164:167], v[58:61]
	v_mfma_f32_16x16x32_bf16 v[58:61], v[176:179], v[168:171], v[58:61]
	v_mfma_f32_16x16x32_bf16 v[54:57], v[180:183], v[156:159], v[54:57]
	v_mfma_f32_16x16x32_bf16 v[54:57], v[184:187], v[160:163], v[54:57]
	v_mfma_f32_16x16x32_bf16 v[50:53], v[180:183], v[164:167], v[50:53]
	v_mfma_f32_16x16x32_bf16 v[50:53], v[184:187], v[168:171], v[50:53]
	v_mfma_f32_16x16x32_bf16 v[46:49], v[188:191], v[156:159], v[46:49]
	v_mfma_f32_16x16x32_bf16 v[46:49], v[206:209], v[160:163], v[46:49]
	v_mfma_f32_16x16x32_bf16 v[42:45], v[188:191], v[164:167], v[42:45]
	v_mfma_f32_16x16x32_bf16 v[42:45], v[206:209], v[168:171], v[42:45]
	v_mfma_f32_16x16x32_bf16 v[38:41], v[210:213], v[156:159], v[38:41]
	v_mfma_f32_16x16x32_bf16 v[38:41], v[214:217], v[160:163], v[38:41]
	v_mfma_f32_16x16x32_bf16 v[34:37], v[210:213], v[164:167], v[34:37]
	v_mfma_f32_16x16x32_bf16 v[34:37], v[214:217], v[168:171], v[34:37]
	v_mfma_f32_16x16x32_bf16 v[30:33], v[172:175], v[218:221], v[30:33]
	v_mfma_f32_16x16x32_bf16 v[30:33], v[176:179], v[222:225], v[30:33]
	v_mfma_f32_16x16x32_bf16 v[26:29], v[172:175], v[226:229], v[26:29]
	v_mfma_f32_16x16x32_bf16 v[26:29], v[176:179], v[230:233], v[26:29]
	v_mfma_f32_16x16x32_bf16 v[22:25], v[180:183], v[218:221], v[22:25]
	v_mfma_f32_16x16x32_bf16 v[22:25], v[184:187], v[222:225], v[22:25]
	v_mfma_f32_16x16x32_bf16 v[18:21], v[180:183], v[226:229], v[18:21]
	v_mfma_f32_16x16x32_bf16 v[18:21], v[184:187], v[230:233], v[18:21]
	v_mfma_f32_16x16x32_bf16 v[14:17], v[188:191], v[218:221], v[14:17]
	v_mfma_f32_16x16x32_bf16 v[14:17], v[206:209], v[222:225], v[14:17]
	v_mfma_f32_16x16x32_bf16 v[10:13], v[188:191], v[226:229], v[10:13]
	v_mfma_f32_16x16x32_bf16 v[10:13], v[206:209], v[230:233], v[10:13]
	v_mfma_f32_16x16x32_bf16 v[6:9], v[210:213], v[218:221], v[6:9]
	v_mfma_f32_16x16x32_bf16 v[6:9], v[214:217], v[222:225], v[6:9]
	v_mfma_f32_16x16x32_bf16 v[2:5], v[210:213], v[226:229], v[2:5]
	v_mfma_f32_16x16x32_bf16 v[2:5], v[214:217], v[230:233], v[2:5]
	s_add_i32 s9, s9, 2
	s_add_u32 s12, s12, 0x100
	s_addc_u32 s13, s13, 0
	s_add_u32 s14, s14, 0x100
	s_addc_u32 s15, s15, 0
	s_cmp_lt_u32 s9, 12
	s_barrier
	s_cbranch_scc1 .LBB0_427
	s_mov_b64 s[0:1], 0x780
	v_lshl_add_u64 v[136:137], v[130:131], 0, s[0:1]
	v_readfirstlane_b32 s0, v153
	s_mov_b32 m0, s0
	s_mov_b64 s[0:1], 0x20780
	v_lshl_add_u64 v[130:131], v[130:131], 0, s[0:1]
	v_readfirstlane_b32 s0, v154
	ds_read_b128 v[140:143], v149
	ds_read_b128 v[156:159], v149 offset:1024
	ds_read_b128 v[160:163], v149 offset:2048
	ds_read_b128 v[164:167], v149 offset:3072
	ds_read_b128 v[168:171], v132
	ds_read_b128 v[172:175], v132 offset:1024
	ds_read_b128 v[176:179], v150
	ds_read_b128 v[180:183], v150 offset:1024
	ds_read_b128 v[184:187], v151
	ds_read_b128 v[188:191], v151 offset:1024
	ds_read_b128 v[206:209], v152
	ds_read_b128 v[210:213], v152 offset:1024
	global_load_lds_dwordx4 v[136:137], off
	s_mov_b32 m0, s0
	s_nop 0
	global_load_lds_dwordx4 v[130:131], off
	s_waitcnt vmcnt(8)
	s_barrier
	s_waitcnt lgkmcnt(0)
	s_setprio 1
	s_waitcnt lgkmcnt(0)
	v_mfma_f32_16x16x32_bf16 v[126:129], v[168:171], v[140:143], v[126:129]
	v_mfma_f32_16x16x32_bf16 v[122:125], v[168:171], v[160:163], v[122:125]
	v_mfma_f32_16x16x32_bf16 v[118:121], v[176:179], v[140:143], v[118:121]
	v_mfma_f32_16x16x32_bf16 v[114:117], v[176:179], v[160:163], v[114:117]
	v_mfma_f32_16x16x32_bf16 v[110:113], v[184:187], v[140:143], v[110:113]
	v_mfma_f32_16x16x32_bf16 v[106:109], v[184:187], v[160:163], v[106:109]
	v_mfma_f32_16x16x32_bf16 v[102:105], v[206:209], v[140:143], v[102:105]
	v_mfma_f32_16x16x32_bf16 v[126:129], v[172:175], v[156:159], v[126:129]
	v_mfma_f32_16x16x32_bf16 v[122:125], v[172:175], v[164:167], v[122:125]
	v_mfma_f32_16x16x32_bf16 v[118:121], v[180:183], v[156:159], v[118:121]
	v_mfma_f32_16x16x32_bf16 v[114:117], v[180:183], v[164:167], v[114:117]
	v_mfma_f32_16x16x32_bf16 v[110:113], v[188:191], v[156:159], v[110:113]
	v_mfma_f32_16x16x32_bf16 v[106:109], v[188:191], v[164:167], v[106:109]
	v_mfma_f32_16x16x32_bf16 v[102:105], v[210:213], v[156:159], v[102:105]
	v_mfma_f32_16x16x32_bf16 v[98:101], v[206:209], v[160:163], v[98:101]
	v_mfma_f32_16x16x32_bf16 v[214:217], v[210:213], v[164:167], v[98:101]
	s_setprio 0
	s_barrier
; #define STAGE_A(P, br, kt) do { const char* _g = (const char*)(A + (long)(br) * lda + (long)(kt) * BK); \
;     __builtin_amdgcn_global_load_lds((const unsigned*)(_g + (size_t)offA0), (unsigned*)((char*)(P) + sb0), 16, 0, 0); \
;     __builtin_amdgcn_global_load_lds((const unsigned*)(_g + (size_t)lda * 128 + (size_t)offA0), (unsigned*)((char*)(P) + sb1), 16, 0, 0); } while (0)
; #define LDA(dst, b, h) for (int m = 0; m < 4; ++m) for (int k = 0; k < 2; ++k) \
;     dst[m][k] = *reinterpret_cast<const bf16x8*>((char*)SA(b, h) + lds_byte(wr * 64 + m * 16 + fr, k * 32 + fq * 8))
; #define LDB(dst, b, h) for (int n = 0; n < 2; ++n) for (int k = 0; k < 2; ++k) \
;     dst[n][k] = *reinterpret_cast<const bf16x8*>((char*)SB(b, h) + lds_byte(wc * 32 + n * 16 + fr, k * 32 + fq * 8))
; #define MMA(ai, bj, At_, Bt_) do { __builtin_amdgcn_s_setprio(1); \
;     for (int m = 0; m < 4; ++m) for (int n = 0; n < 2; ++n) for (int k = 0; k < 2; ++k) \
;       acc[ai][bj][m][n] = MFMA16(At_[m][k], Bt_[n][k], acc[ai][bj][m][n]); \
;     __builtin_amdgcn_s_setprio(0); } while (0)
; #define WAIT_V(n) asm volatile("s_waitcnt vmcnt(" #n ")" ::: "memory")
; #define WAIT_L(n) asm volatile("s_waitcnt lgkmcnt(" #n ")" ::: "memory")
; #define BAR __builtin_amdgcn_s_barrier()
; DI void gemm_core(WVP char* smem, const u16* __restrict__ A, int lda, int ar0, int ar1,
;                   const u16* __restrict__ B, int ldb, int bc0, int K, AccT& acc) {
;     ...
;   { LDB(B0, 0, 0); LDA(At, 0, 0); STAGE_A(SA(1, 1), ac1, nt - 1);
;     BAR; WAIT_L(0); MMA(0, 0, At, B0); BAR;
;     LDB(B1, 0, 1); BAR; WAIT_L(0); MMA(0, 1, At, B1); BAR;
;     LDA(At, 0, 1); WAIT_V(4); BAR; WAIT_L(0); MMA(1, 0, At, B0); MMA(1, 1, At, B1); BAR; }
;   { LDB(B0, 1, 0); LDA(At, 1, 0); WAIT_V(2); BAR; WAIT_L(0); MMA(0, 0, At, B0); BAR;
	s_nop 4
	ds_read_b128 v[98:101], v147
	ds_read_b128 v[218:221], v147 offset:1024
	ds_read_b128 v[222:225], v147 offset:2048
	ds_read_b128 v[144:147], v147 offset:3072
	s_barrier
	s_waitcnt lgkmcnt(0)
	s_setprio 1
	s_waitcnt lgkmcnt(0)
	v_mfma_f32_16x16x32_bf16 v[94:97], v[168:171], v[98:101], v[94:97]
	v_mfma_f32_16x16x32_bf16 v[86:89], v[176:179], v[98:101], v[86:89]
	v_mfma_f32_16x16x32_bf16 v[78:81], v[184:187], v[98:101], v[78:81]
	v_mfma_f32_16x16x32_bf16 v[70:73], v[206:209], v[98:101], v[70:73]
	v_mfma_f32_16x16x32_bf16 v[94:97], v[172:175], v[218:221], v[94:97]
	v_mfma_f32_16x16x32_bf16 v[90:93], v[168:171], v[222:225], v[90:93]
	v_mfma_f32_16x16x32_bf16 v[86:89], v[180:183], v[218:221], v[86:89]
	v_mfma_f32_16x16x32_bf16 v[82:85], v[176:179], v[222:225], v[82:85]
	v_mfma_f32_16x16x32_bf16 v[78:81], v[188:191], v[218:221], v[78:81]
	v_mfma_f32_16x16x32_bf16 v[74:77], v[184:187], v[222:225], v[74:77]
	v_mfma_f32_16x16x32_bf16 v[70:73], v[210:213], v[218:221], v[70:73]
	v_mfma_f32_16x16x32_bf16 v[66:69], v[206:209], v[222:225], v[66:69]
	v_mfma_f32_16x16x32_bf16 v[168:171], v[172:175], v[144:147], v[90:93]
	v_mfma_f32_16x16x32_bf16 v[172:175], v[180:183], v[144:147], v[82:85]
	v_mfma_f32_16x16x32_bf16 v[176:179], v[188:191], v[144:147], v[74:77]
	v_mfma_f32_16x16x32_bf16 v[180:183], v[210:213], v[144:147], v[66:69]
	s_setprio 0
	s_barrier
	s_nop 1
	ds_read_b128 v[66:69], v132 offset:16384
	ds_read_b128 v[74:77], v132 offset:17408
	ds_read_b128 v[82:85], v150 offset:16384
	ds_read_b128 v[90:93], v150 offset:17408
	ds_read_b128 v[184:187], v151 offset:16384
	ds_read_b128 v[188:191], v151 offset:17408
	ds_read_b128 v[206:209], v152 offset:16384
	ds_read_b128 v[210:213], v152 offset:17408
	s_waitcnt vmcnt(4)
	s_barrier
	s_waitcnt lgkmcnt(0)
	s_setprio 1
	s_waitcnt lgkmcnt(0)
	v_mfma_f32_16x16x32_bf16 v[62:65], v[66:69], v[140:143], v[62:65]
	v_mfma_f32_16x16x32_bf16 v[54:57], v[82:85], v[140:143], v[54:57]
	v_mfma_f32_16x16x32_bf16 v[42:45], v[184:187], v[160:163], v[42:45]
	v_mfma_f32_16x16x32_bf16 v[34:37], v[206:209], v[160:163], v[34:37]
	v_mfma_f32_16x16x32_bf16 v[62:65], v[74:77], v[156:159], v[62:65]
	v_mfma_f32_16x16x32_bf16 v[58:61], v[66:69], v[160:163], v[58:61]
	v_mfma_f32_16x16x32_bf16 v[54:57], v[90:93], v[156:159], v[54:57]
	v_mfma_f32_16x16x32_bf16 v[50:53], v[82:85], v[160:163], v[50:53]
	v_mfma_f32_16x16x32_bf16 v[46:49], v[184:187], v[140:143], v[46:49]
	v_mfma_f32_16x16x32_bf16 v[42:45], v[188:191], v[164:167], v[42:45]
	v_mfma_f32_16x16x32_bf16 v[38:41], v[206:209], v[140:143], v[38:41]
	v_mfma_f32_16x16x32_bf16 v[34:37], v[210:213], v[164:167], v[34:37]
	v_mfma_f32_16x16x32_bf16 v[226:229], v[74:77], v[164:167], v[58:61]
	v_mfma_f32_16x16x32_bf16 v[230:233], v[90:93], v[164:167], v[50:53]
	v_mfma_f32_16x16x32_bf16 v[234:237], v[188:191], v[156:159], v[46:49]
	v_mfma_f32_16x16x32_bf16 v[140:143], v[210:213], v[156:159], v[38:41]
	s_setprio 0
	s_setprio 1
	v_mfma_f32_16x16x32_bf16 v[26:29], v[66:69], v[222:225], v[26:29]
	v_mfma_f32_16x16x32_bf16 v[30:33], v[66:69], v[98:101], v[30:33]
	v_mfma_f32_16x16x32_bf16 v[26:29], v[74:77], v[144:147], v[26:29]
	v_mfma_f32_16x16x32_bf16 v[22:25], v[82:85], v[98:101], v[22:25]
	v_mfma_f32_16x16x32_bf16 v[18:21], v[82:85], v[222:225], v[18:21]
	v_mfma_f32_16x16x32_bf16 v[14:17], v[184:187], v[98:101], v[14:17]
	v_mfma_f32_16x16x32_bf16 v[10:13], v[184:187], v[222:225], v[10:13]
	v_mfma_f32_16x16x32_bf16 v[6:9], v[206:209], v[98:101], v[6:9]
	v_mfma_f32_16x16x32_bf16 v[2:5], v[206:209], v[222:225], v[2:5]
	v_mfma_f32_16x16x32_bf16 v[154:157], v[74:77], v[218:221], v[30:33]
	v_mfma_f32_16x16x32_bf16 v[158:161], v[90:93], v[218:221], v[22:25]
	v_mfma_f32_16x16x32_bf16 v[162:165], v[90:93], v[144:147], v[18:21]
	v_mfma_f32_16x16x32_bf16 v[238:241], v[188:191], v[218:221], v[14:17]
	v_mfma_f32_16x16x32_bf16 v[184:187], v[188:191], v[144:147], v[10:13]
	v_mfma_f32_16x16x32_bf16 v[188:191], v[210:213], v[218:221], v[6:9]
	v_mfma_f32_16x16x32_bf16 v[144:147], v[210:213], v[144:147], v[2:5]
	s_setprio 0
	s_barrier
	ds_read_b128 v[206:209], v138
	ds_read_b128 v[210:213], v138 offset:1024
	ds_read_b128 v[218:221], v138 offset:2048
	ds_read_b128 v[136:139], v138 offset:3072
	ds_read_b128 v[2:5], v132 offset:32768
	ds_read_b128 v[6:9], v132 offset:33792
	ds_read_b128 v[10:13], v150 offset:32768
	ds_read_b128 v[14:17], v150 offset:33792
	ds_read_b128 v[222:225], v151 offset:32768
	ds_read_b128 v[242:245], v151 offset:33792
	ds_read_b128 v[246:249], v152 offset:32768
	ds_read_b128 v[250:253], v152 offset:33792
	s_waitcnt vmcnt(2)
	s_barrier
; #define LDA(dst, b, h) for (int m = 0; m < 4; ++m) for (int k = 0; k < 2; ++k) \
;     dst[m][k] = *reinterpret_cast<const bf16x8*>((char*)SA(b, h) + lds_byte(wr * 64 + m * 16 + fr, k * 32 + fq * 8))
; #define LDB(dst, b, h) for (int n = 0; n < 2; ++n) for (int k = 0; k < 2; ++k) \
;     dst[n][k] = *reinterpret_cast<const bf16x8*>((char*)SB(b, h) + lds_byte(wc * 32 + n * 16 + fr, k * 32 + fq * 8))
; #define MMA(ai, bj, At_, Bt_) do { __builtin_amdgcn_s_setprio(1); \
;     for (int m = 0; m < 4; ++m) for (int n = 0; n < 2; ++n) for (int k = 0; k < 2; ++k) \
;       acc[ai][bj][m][n] = MFMA16(At_[m][k], Bt_[n][k], acc[ai][bj][m][n]); \
;     __builtin_amdgcn_s_setprio(0); } while (0)
; #define WAIT_V(n) asm volatile("s_waitcnt vmcnt(" #n ")" ::: "memory")
; #define WAIT_L(n) asm volatile("s_waitcnt lgkmcnt(" #n ")" ::: "memory")
; #define BAR __builtin_amdgcn_s_barrier()
; DI void gemm_core(WVP char* smem, const u16* __restrict__ A, int lda, int ar0, int ar1,
;                   const u16* __restrict__ B, int ldb, int bc0, int K, AccT& acc) {
;     ...
;     LDA(At, 0, 1); WAIT_V(4); BAR; WAIT_L(0); MMA(1, 0, At, B0); MMA(1, 1, At, B1); BAR; }
;   { LDB(B0, 1, 0); LDA(At, 1, 0); WAIT_V(2); BAR; WAIT_L(0); MMA(0, 0, At, B0); BAR;
;     LDB(B1, 1, 1); WAIT_V(0); BAR; WAIT_L(0); MMA(0, 1, At, B1); BAR;
;     LDA(At, 1, 1); BAR; WAIT_L(0); MMA(1, 0, At, B0); MMA(1, 1, At, B1); BAR; }
;   if (wr == 0) BAR;
	s_waitcnt lgkmcnt(0)
	s_setprio 1
	s_waitcnt lgkmcnt(0)
	v_mfma_f32_16x16x32_bf16 v[18:21], v[2:5], v[206:209], v[126:129]
	v_mfma_f32_16x16x32_bf16 v[98:101], v[6:9], v[210:213], v[18:21]
	v_mfma_f32_16x16x32_bf16 v[18:21], v[2:5], v[218:221], v[122:125]
	v_mfma_f32_16x16x32_bf16 v[90:93], v[6:9], v[136:139], v[18:21]
	v_mfma_f32_16x16x32_bf16 v[18:21], v[10:13], v[206:209], v[118:121]
	v_mfma_f32_16x16x32_bf16 v[82:85], v[14:17], v[210:213], v[18:21]
	v_mfma_f32_16x16x32_bf16 v[18:21], v[10:13], v[218:221], v[114:117]
	v_mfma_f32_16x16x32_bf16 v[74:77], v[14:17], v[136:139], v[18:21]
	v_mfma_f32_16x16x32_bf16 v[18:21], v[222:225], v[206:209], v[110:113]
	v_mfma_f32_16x16x32_bf16 v[66:69], v[242:245], v[210:213], v[18:21]
	v_mfma_f32_16x16x32_bf16 v[18:21], v[222:225], v[218:221], v[106:109]
	v_mfma_f32_16x16x32_bf16 v[58:61], v[242:245], v[136:139], v[18:21]
	v_mfma_f32_16x16x32_bf16 v[18:21], v[246:249], v[206:209], v[102:105]
	v_mfma_f32_16x16x32_bf16 v[50:53], v[250:253], v[210:213], v[18:21]
	v_mfma_f32_16x16x32_bf16 v[18:21], v[246:249], v[218:221], v[214:217]
	v_mfma_f32_16x16x32_bf16 v[38:41], v[250:253], v[136:139], v[18:21]
	s_setprio 0
	s_barrier
	ds_read_b128 v[214:217], v134
	ds_read_b128 v[196:199], v134 offset:1024
	ds_read_b128 v[192:195], v134 offset:2048
	ds_read_b128 v[200:203], v134 offset:3072
	s_waitcnt vmcnt(0)
	s_barrier
	s_waitcnt lgkmcnt(0)
	s_setprio 1
	s_waitcnt lgkmcnt(0)
	v_mfma_f32_16x16x32_bf16 v[18:21], v[2:5], v[214:217], v[94:97]
	v_mfma_f32_16x16x32_bf16 v[2:5], v[2:5], v[192:195], v[168:171]
	v_mfma_f32_16x16x32_bf16 v[30:33], v[6:9], v[200:203], v[2:5]
	v_mfma_f32_16x16x32_bf16 v[2:5], v[10:13], v[214:217], v[86:89]
	v_mfma_f32_16x16x32_bf16 v[22:25], v[14:17], v[196:199], v[2:5]
	v_mfma_f32_16x16x32_bf16 v[2:5], v[10:13], v[192:195], v[172:175]
	v_mfma_f32_16x16x32_bf16 v[46:49], v[6:9], v[196:199], v[18:21]
	v_mfma_f32_16x16x32_bf16 v[18:21], v[14:17], v[200:203], v[2:5]
	v_mfma_f32_16x16x32_bf16 v[2:5], v[222:225], v[214:217], v[78:81]
	v_mfma_f32_16x16x32_bf16 v[14:17], v[242:245], v[196:199], v[2:5]
	v_mfma_f32_16x16x32_bf16 v[2:5], v[222:225], v[192:195], v[176:179]
	v_mfma_f32_16x16x32_bf16 v[10:13], v[242:245], v[200:203], v[2:5]
	v_mfma_f32_16x16x32_bf16 v[2:5], v[246:249], v[214:217], v[70:73]
	v_mfma_f32_16x16x32_bf16 v[6:9], v[250:253], v[196:199], v[2:5]
	v_mfma_f32_16x16x32_bf16 v[2:5], v[246:249], v[192:195], v[180:183]
	v_mfma_f32_16x16x32_bf16 v[2:5], v[250:253], v[200:203], v[2:5]
	s_setprio 0
	s_barrier
	ds_read_b128 v[70:73], v132 offset:49152
	ds_read_b128 v[78:81], v132 offset:50176
	ds_read_b128 v[130:133], v150 offset:49152
	ds_read_b128 v[166:169], v150 offset:50176
	ds_read_b128 v[170:173], v151 offset:49152
	ds_read_b128 v[148:151], v151 offset:50176
	ds_read_b128 v[174:177], v152 offset:49152
	ds_read_b128 v[178:181], v152 offset:50176
	s_barrier
	s_waitcnt lgkmcnt(0)
	s_setprio 1
	s_waitcnt lgkmcnt(0)
	v_mfma_f32_16x16x32_bf16 v[54:57], v[130:133], v[206:209], v[54:57]
	v_mfma_f32_16x16x32_bf16 v[62:65], v[70:73], v[206:209], v[62:65]
	v_mfma_f32_16x16x32_bf16 v[118:121], v[166:169], v[210:213], v[54:57]
	v_mfma_f32_16x16x32_bf16 v[54:57], v[130:133], v[218:221], v[230:233]
	v_mfma_f32_16x16x32_bf16 v[42:45], v[170:173], v[218:221], v[42:45]
	v_mfma_f32_16x16x32_bf16 v[126:129], v[78:81], v[210:213], v[62:65]
	v_mfma_f32_16x16x32_bf16 v[62:65], v[70:73], v[218:221], v[226:229]
	v_mfma_f32_16x16x32_bf16 v[114:117], v[166:169], v[136:139], v[54:57]
	v_mfma_f32_16x16x32_bf16 v[54:57], v[170:173], v[206:209], v[234:237]
	v_mfma_f32_16x16x32_bf16 v[106:109], v[148:151], v[136:139], v[42:45]
	v_mfma_f32_16x16x32_bf16 v[42:45], v[174:177], v[206:209], v[140:143]
	v_mfma_f32_16x16x32_bf16 v[34:37], v[174:177], v[218:221], v[34:37]
	v_mfma_f32_16x16x32_bf16 v[122:125], v[78:81], v[136:139], v[62:65]
	v_mfma_f32_16x16x32_bf16 v[110:113], v[148:151], v[210:213], v[54:57]
	v_mfma_f32_16x16x32_bf16 v[102:105], v[178:181], v[210:213], v[42:45]
	v_mfma_f32_16x16x32_bf16 v[94:97], v[178:181], v[136:139], v[34:37]
	s_setprio 0
	s_setprio 1
	v_mfma_f32_16x16x32_bf16 v[34:37], v[70:73], v[214:217], v[154:157]
	v_mfma_f32_16x16x32_bf16 v[26:29], v[70:73], v[192:195], v[26:29]
	v_mfma_f32_16x16x32_bf16 v[86:89], v[78:81], v[196:199], v[34:37]
	v_mfma_f32_16x16x32_bf16 v[78:81], v[78:81], v[200:203], v[26:29]
	v_mfma_f32_16x16x32_bf16 v[26:29], v[130:133], v[214:217], v[158:161]
	v_mfma_f32_16x16x32_bf16 v[70:73], v[166:169], v[196:199], v[26:29]
	v_mfma_f32_16x16x32_bf16 v[26:29], v[130:133], v[192:195], v[162:165]
	v_mfma_f32_16x16x32_bf16 v[62:65], v[166:169], v[200:203], v[26:29]
	v_mfma_f32_16x16x32_bf16 v[26:29], v[170:173], v[214:217], v[238:241]
	v_mfma_f32_16x16x32_bf16 v[54:57], v[148:151], v[196:199], v[26:29]
	v_mfma_f32_16x16x32_bf16 v[26:29], v[170:173], v[192:195], v[184:187]
	v_mfma_f32_16x16x32_bf16 v[42:45], v[148:151], v[200:203], v[26:29]
	v_mfma_f32_16x16x32_bf16 v[26:29], v[174:177], v[214:217], v[188:191]
	v_mfma_f32_16x16x32_bf16 v[34:37], v[178:181], v[196:199], v[26:29]
	v_mfma_f32_16x16x32_bf16 v[26:29], v[174:177], v[192:195], v[144:147]
	v_mfma_f32_16x16x32_bf16 v[26:29], v[178:181], v[200:203], v[26:29]
	s_setprio 0
	s_cmp_gt_u32 s4, 3
	s_barrier
	s_cbranch_scc1 .LBB0_423
	s_barrier
	s_branch .LBB0_423
